# K-loop back-edge rotation: head scalar select block + counter/pointer increments moved into the last MFMA block (one per MFMA gap); only the branch follows the loop-back barrier
# baseline (speedup 1.0000x reference)
; #define PG8_STAGE(bufoff, gbase, voff) do { _Pragma("unroll") for (int _i = 0; _i < 2; ++_i) \
;         __builtin_amdgcn_global_load_lds((const unsigned*)((const char*)(gbase) + (voff)[_i]), (LAS unsigned*)(lds + (bufoff) + ldsw + _i * 8192), 16, 0, 0); } while (0)
; #define PG8_LDA(dst, b, h) do { _Pragma("unroll") for (int m = 0; m < 4; ++m) _Pragma("unroll") for (int k = 0; k < 2; ++k) dst[m][k] = *(const LAS bf16x8*)(lds + PG8_SA(b, h) + aoff + m * 2048 + k * 1024); } while (0)
; #define PG8_LDB(dst, b, h) do { _Pragma("unroll") for (int n = 0; n < 2; ++n) _Pragma("unroll") for (int k = 0; k < 2; ++k) dst[n][k] = *(const LAS bf16x8*)(lds + PG8_SB(b, h) + boff + n * 2048 + k * 1024); } while (0)
; #define PG8_BAR __builtin_amdgcn_s_barrier()
; template <class Epi>
; __device__ __forceinline__ void gemm_phase(LAS unsigned char* lds, const Gemm g, const StaticOrder& S, const Epi& E, const int tid) {
;     ...
;         const bool has_next = S.next(ui + 1, nxt);
;         const char* nA = has_next ? (const char*)g.A + (size_t)nxt.pm * tstep : cA; const char* nB = has_next ? (const char*)g.Bt + (size_t)nxt.pn * tstep : cB;
;         for (int t = 0; t < ntt; t += 2) {
;             const bool last = (t == ntt - 2);
;             const bool s1 = Epi::TWO && (t >= nt), s2 = Epi::TWO && (t + 2 >= nt);
;             const char* a1 = (s1 ? cA2 + (size_t)(t - nt + 1) * kstep : cA + (size_t)(t + 1) * kstep);
;             const char* a2 = last ? nA : (s2 ? cA2 + (size_t)(t + 2 - nt) * kstep : cA + (size_t)(t + 2) * kstep);
;             const char* b2 = last ? nB : (s2 ? cB2 + (size_t)(t + 2 - nt) * kstep : cB + (size_t)(t + 2) * kstep);
;             const char* a3 = a2 + kstep; const char* b3 = b2 + kstep;
;             if constexpr (Epi::TWO) { if (t == nt) E.mid(acc, cur, wr, wc, fr, fq); }
;             if constexpr (SP2) {
;             PG8_LDB(B0, 0, 0); PG8_LDB(B1, 0, 1); PG8_SCHED; PG8_LDA(At, 0, 0); PG8_STAGE(PG8_SA(1, 1), a1 + hstep, voffA);
;             PG8_WAIT_V(8); PG8_WAIT_L(0); PG8_BAR; PG8_MMA(0, 0, At, B0); PG8_MMA(0, 1, At, B1); PG8_BAR; PG8_SCHED;
;     ...
; #pragma unroll
;         for (int a = 0; a < 2; ++a)
; #pragma unroll
;             for (int b = 0; b < 2; ++b)
; #pragma unroll
;                 for (int m = 0; m < 4; ++m)
; #pragma unroll
;                     for (int n = 0; n < 2; ++n) acc[a][b][m][n] = (f32x4){0.f, 0.f, 0.f, 0.f};
.LBB0_125:
	s_ashr_i32 s17, s16, 31
	s_lshl_b64 s[18:19], s[16:17], 22
	v_readlane_b32 s20, v251, 43
	v_readlane_b32 s21, v251, 44
	s_add_u32 s18, s20, s18
	s_addc_u32 s19, s21, s19
	s_and_b64 s[20:21], s[22:23], exec
	s_cselect_b32 s17, s19, s31
	s_cselect_b32 s27, s18, s30
	s_ashr_i32 s15, s14, 31
	s_lshl_b64 s[20:21], s[14:15], 22
	v_readlane_b32 s34, v251, 41
	v_readlane_b32 s35, v251, 42
	s_add_u32 s20, s34, s20
	s_addc_u32 s21, s35, s21
	s_and_b64 s[34:35], s[22:23], exec
	s_cselect_b32 s15, s21, s29
	s_cselect_b32 s33, s20, s28
	s_add_u32 s49, s28, 0x100
	s_addc_u32 s50, s29, 0
	s_add_u32 s28, s30, 0x200080
	v_mov_b32_e32 v2, 0
	s_addc_u32 s29, s31, 0
	s_mov_b32 s51, -2
	v_mov_b32_e32 v3, v2
	s_waitcnt lgkmcnt(0)
	v_mov_b32_e32 v4, v2
	v_mov_b32_e32 v5, v2
	v_mov_b32_e32 v6, v2
	v_mov_b32_e32 v7, v2
	v_mov_b32_e32 v8, v2
	v_mov_b32_e32 v9, v2
	v_mov_b32_e32 v34, v2
	v_mov_b32_e32 v35, v2
	v_mov_b32_e32 v36, v2
	v_mov_b32_e32 v37, v2
	v_mov_b32_e32 v38, v2
	v_mov_b32_e32 v39, v2
	v_mov_b32_e32 v40, v2
	v_mov_b32_e32 v41, v2
	v_mov_b32_e32 v66, v2
	v_mov_b32_e32 v67, v2
	v_mov_b32_e32 v68, v2
	v_mov_b32_e32 v69, v2
	v_mov_b32_e32 v70, v2
	v_mov_b32_e32 v71, v2
	v_mov_b32_e32 v72, v2
	v_mov_b32_e32 v73, v2
	v_mov_b32_e32 v82, v2
	v_mov_b32_e32 v83, v2
	v_mov_b32_e32 v84, v2
	v_mov_b32_e32 v85, v2
	v_mov_b32_e32 v86, v2
	v_mov_b32_e32 v87, v2
	v_mov_b32_e32 v88, v2
	v_mov_b32_e32 v89, v2
	v_mov_b32_e32 v10, v2
	v_mov_b32_e32 v11, v2
	v_mov_b32_e32 v12, v2
	v_mov_b32_e32 v13, v2
	v_mov_b32_e32 v14, v2
	v_mov_b32_e32 v15, v2
	v_mov_b32_e32 v16, v2
	v_mov_b32_e32 v17, v2
	v_mov_b32_e32 v58, v2
	v_mov_b32_e32 v59, v2
	v_mov_b32_e32 v60, v2
	v_mov_b32_e32 v61, v2
	v_mov_b32_e32 v62, v2
	v_mov_b32_e32 v63, v2
	v_mov_b32_e32 v64, v2
	v_mov_b32_e32 v65, v2
	v_mov_b32_e32 v74, v2
	v_mov_b32_e32 v75, v2
	v_mov_b32_e32 v76, v2
	v_mov_b32_e32 v77, v2
	v_mov_b32_e32 v78, v2
	v_mov_b32_e32 v79, v2
	v_mov_b32_e32 v80, v2
	v_mov_b32_e32 v81, v2
	v_mov_b32_e32 v90, v2
	v_mov_b32_e32 v91, v2
	v_mov_b32_e32 v92, v2
	v_mov_b32_e32 v93, v2
	v_mov_b32_e32 v94, v2
	v_mov_b32_e32 v95, v2
	v_mov_b32_e32 v96, v2
	v_mov_b32_e32 v97, v2
	v_mov_b32_e32 v98, v2
	v_mov_b32_e32 v99, v2
	v_mov_b32_e32 v100, v2
	v_mov_b32_e32 v101, v2
	v_mov_b32_e32 v102, v2
	v_mov_b32_e32 v103, v2
	v_mov_b32_e32 v104, v2
	v_mov_b32_e32 v105, v2
	v_mov_b32_e32 v114, v2
	v_mov_b32_e32 v115, v2
	v_mov_b32_e32 v116, v2
	v_mov_b32_e32 v117, v2
	v_mov_b32_e32 v118, v2
	v_mov_b32_e32 v119, v2
	v_mov_b32_e32 v120, v2
	v_mov_b32_e32 v121, v2
	v_mov_b32_e32 v130, v2
	v_mov_b32_e32 v131, v2
	v_mov_b32_e32 v132, v2
	v_mov_b32_e32 v133, v2
	v_mov_b32_e32 v134, v2
	v_mov_b32_e32 v135, v2
	v_mov_b32_e32 v136, v2
	v_mov_b32_e32 v137, v2
	v_mov_b32_e32 v146, v2
	v_mov_b32_e32 v147, v2
	v_mov_b32_e32 v148, v2
	v_mov_b32_e32 v149, v2
	v_mov_b32_e32 v150, v2
	v_mov_b32_e32 v151, v2
	v_mov_b32_e32 v152, v2
	v_mov_b32_e32 v153, v2
	v_mov_b32_e32 v106, v2
	v_mov_b32_e32 v107, v2
	v_mov_b32_e32 v108, v2
	v_mov_b32_e32 v109, v2
	v_mov_b32_e32 v110, v2
	v_mov_b32_e32 v111, v2
	v_mov_b32_e32 v112, v2
	v_mov_b32_e32 v113, v2
	v_mov_b32_e32 v122, v2
	v_mov_b32_e32 v123, v2
	v_mov_b32_e32 v124, v2
	v_mov_b32_e32 v125, v2
	v_mov_b32_e32 v126, v2
	v_mov_b32_e32 v127, v2
	v_mov_b32_e32 v128, v2
	v_mov_b32_e32 v129, v2
	v_mov_b32_e32 v138, v2
	v_mov_b32_e32 v139, v2
	v_mov_b32_e32 v140, v2
	v_mov_b32_e32 v141, v2
	v_mov_b32_e32 v142, v2
	v_mov_b32_e32 v143, v2
	v_mov_b32_e32 v144, v2
	v_mov_b32_e32 v145, v2
	v_mov_b32_e32 v154, v2
	v_mov_b32_e32 v155, v2
	v_mov_b32_e32 v156, v2
	v_mov_b32_e32 v157, v2
	v_mov_b32_e32 v158, v2
	v_mov_b32_e32 v159, v2
	v_mov_b32_e32 v160, v2
	v_mov_b32_e32 v161, v2
	s_add_u32 s30, s28, 0xffe00080
	s_addc_u32 s31, s29, -1
	s_add_i32 s52, 0, 0x10000
	s_cmpk_eq_i32 s51, 0x7c
	s_cselect_b32 s35, s17, s31
	s_cselect_b32 s34, s27, s30
	s_cselect_b32 s31, s15, s50
	s_cselect_b32 s30, s33, s49
	s_add_i32 s54, 0, 0x14000
.LBB0_126:
	v_add_u32_e32 v30, s52, v193
	v_add_u32_e32 v54, s54, v193
	ds_read_b128 v[18:21], v30
	ds_read_b128 v[22:25], v30 offset:1024
	ds_read_b128 v[26:29], v30 offset:2048
	ds_read_b128 v[30:33], v30 offset:3072
	ds_read_b128 v[42:45], v54
	ds_read_b128 v[46:49], v54 offset:1024
	ds_read_b128 v[50:53], v54 offset:2048
	ds_read_b128 v[54:57], v54 offset:3072
	v_lshl_add_u64 v[172:173], s[28:29], 0, v[180:181]
	s_add_i32 m0, s37, 0xc000
	ds_read_b128 v[182:185], v199
	global_load_lds_dwordx4 v[172:173], off
	ds_read_b128 v[186:189], v199 offset:1024
	ds_read_b128 v[212:215], v199 offset:2048
	v_lshl_add_u64 v[172:173], s[28:29], 0, v[178:179]
	s_add_i32 m0, s37, 0xe000
	s_nop 0
	global_load_lds_dwordx4 v[172:173], off
	ds_read_b128 v[216:219], v199 offset:3072
	ds_read_b128 v[220:223], v199 offset:4096
	ds_read_b128 v[224:227], v199 offset:5120
	ds_read_b128 v[228:231], v199 offset:6144
	ds_read_b128 v[232:235], v199 offset:7168
	s_waitcnt vmcnt(8)
	s_waitcnt lgkmcnt(0)
	s_barrier
; #define PG8_STAGE(bufoff, gbase, voff) do { _Pragma("unroll") for (int _i = 0; _i < 2; ++_i) \
;         __builtin_amdgcn_global_load_lds((const unsigned*)((const char*)(gbase) + (voff)[_i]), (LAS unsigned*)(lds + (bufoff) + ldsw + _i * 8192), 16, 0, 0); } while (0)
; #define PG8_LDA(dst, b, h) do { _Pragma("unroll") for (int m = 0; m < 4; ++m) _Pragma("unroll") for (int k = 0; k < 2; ++k) dst[m][k] = *(const LAS bf16x8*)(lds + PG8_SA(b, h) + aoff + m * 2048 + k * 1024); } while (0)
; #define PG8_LDB(dst, b, h) do { _Pragma("unroll") for (int n = 0; n < 2; ++n) _Pragma("unroll") for (int k = 0; k < 2; ++k) dst[n][k] = *(const LAS bf16x8*)(lds + PG8_SB(b, h) + boff + n * 2048 + k * 1024); } while (0)
; #define PG8_MMA(ai, bj, At, Bt) do { __builtin_amdgcn_s_setprio(1); _Pragma("unroll") for (int m = 0; m < 4; ++m) _Pragma("unroll") for (int n = 0; n < 2; ++n) _Pragma("unroll") for (int k = 0; k < 2; ++k) \
;         acc[ai][bj][m][n] = __builtin_amdgcn_mfma_f32_16x16x32_bf16(Bt[n][k], At[m][k], acc[ai][bj][m][n], 0, 0, 0); __builtin_amdgcn_s_setprio(0); } while (0)
; #define PG8_WAIT_V(n) asm volatile("s_waitcnt vmcnt(" #n ")" ::: "memory")
; #define PG8_WAIT_L(n) asm volatile("s_waitcnt lgkmcnt(" #n ")" ::: "memory")
; #define PG8_BAR __builtin_amdgcn_s_barrier()
; #define PG8_SCHED __builtin_amdgcn_sched_barrier(0)
; template <class Epi>
; __device__ __forceinline__ void gemm_phase(LAS unsigned char* lds, const Gemm g, const StaticOrder& S, const Epi& E, const int tid) {
;     ...
;             PG8_WAIT_V(8); PG8_WAIT_L(0); PG8_BAR; PG8_MMA(0, 0, At, B0); PG8_MMA(0, 1, At, B1); PG8_BAR; PG8_SCHED;
;             PG8_LDA(At, 0, 1); PG8_STAGE(PG8_SB(0, 0), b2, voffB); PG8_STAGE(PG8_SB(0, 1), b2 + bhs, voffB); PG8_STAGE(PG8_SA(0, 0), a2, voffA);
;             PG8_WAIT_V(8); PG8_WAIT_L(0); PG8_BAR; PG8_MMA(1, 0, At, B0); PG8_MMA(1, 1, At, B1); PG8_BAR; PG8_SCHED;
;             PG8_LDB(B0, 1, 0); PG8_LDB(B1, 1, 1); PG8_SCHED; PG8_LDA(At, 1, 0); PG8_STAGE(PG8_SA(0, 1), a2 + hstep, voffA);
	s_setprio 1
	s_waitcnt lgkmcnt(0)
	v_mfma_f32_16x16x32_bf16 v[158:161], v[18:21], v[182:185], v[158:161]
	v_mfma_f32_16x16x32_bf16 v[154:157], v[26:29], v[182:185], v[154:157]
	v_mfma_f32_16x16x32_bf16 v[142:145], v[18:21], v[212:215], v[142:145]
	v_mfma_f32_16x16x32_bf16 v[138:141], v[26:29], v[212:215], v[138:141]
	v_mfma_f32_16x16x32_bf16 v[126:129], v[18:21], v[220:223], v[126:129]
	v_mfma_f32_16x16x32_bf16 v[122:125], v[26:29], v[220:223], v[122:125]
	v_mfma_f32_16x16x32_bf16 v[110:113], v[18:21], v[228:231], v[110:113]
	v_mfma_f32_16x16x32_bf16 v[106:109], v[26:29], v[228:231], v[106:109]
	v_mfma_f32_16x16x32_bf16 v[158:161], v[22:25], v[186:189], v[158:161]
	v_mfma_f32_16x16x32_bf16 v[154:157], v[30:33], v[186:189], v[154:157]
	v_mfma_f32_16x16x32_bf16 v[142:145], v[22:25], v[216:219], v[142:145]
	v_mfma_f32_16x16x32_bf16 v[138:141], v[30:33], v[216:219], v[138:141]
	v_mfma_f32_16x16x32_bf16 v[126:129], v[22:25], v[224:227], v[126:129]
	v_mfma_f32_16x16x32_bf16 v[122:125], v[30:33], v[224:227], v[122:125]
	v_mfma_f32_16x16x32_bf16 v[110:113], v[22:25], v[232:235], v[110:113]
	v_mfma_f32_16x16x32_bf16 v[106:109], v[30:33], v[232:235], v[106:109]
	s_setprio 0
	s_setprio 1
	v_mfma_f32_16x16x32_bf16 v[150:153], v[42:45], v[182:185], v[150:153]
	v_mfma_f32_16x16x32_bf16 v[146:149], v[50:53], v[182:185], v[146:149]
	v_mfma_f32_16x16x32_bf16 v[134:137], v[42:45], v[212:215], v[134:137]
	v_mfma_f32_16x16x32_bf16 v[130:133], v[50:53], v[212:215], v[130:133]
	v_mfma_f32_16x16x32_bf16 v[118:121], v[42:45], v[220:223], v[118:121]
	v_mfma_f32_16x16x32_bf16 v[114:117], v[50:53], v[220:223], v[114:117]
	v_mfma_f32_16x16x32_bf16 v[102:105], v[42:45], v[228:231], v[102:105]
	v_mfma_f32_16x16x32_bf16 v[98:101], v[50:53], v[228:231], v[98:101]
	v_mfma_f32_16x16x32_bf16 v[150:153], v[46:49], v[186:189], v[150:153]
	v_mfma_f32_16x16x32_bf16 v[146:149], v[54:57], v[186:189], v[146:149]
	v_mfma_f32_16x16x32_bf16 v[134:137], v[46:49], v[216:219], v[134:137]
	v_mfma_f32_16x16x32_bf16 v[130:133], v[54:57], v[216:219], v[130:133]
	v_mfma_f32_16x16x32_bf16 v[118:121], v[46:49], v[224:227], v[118:121]
	v_mfma_f32_16x16x32_bf16 v[114:117], v[54:57], v[224:227], v[114:117]
	v_mfma_f32_16x16x32_bf16 v[102:105], v[46:49], v[232:235], v[102:105]
	v_mfma_f32_16x16x32_bf16 v[98:101], v[54:57], v[232:235], v[98:101]
	s_setprio 0
	s_barrier
	s_add_i32 s52, s52, s36
	v_lshl_add_u64 v[172:173], s[30:31], 0, v[0:1]
	s_mov_b32 m0, s52
	ds_read_b128 v[182:185], v199 offset:16384
	global_load_lds_dwordx4 v[172:173], off
	ds_read_b128 v[186:189], v199 offset:17408
	ds_read_b128 v[212:215], v199 offset:18432
	s_add_i32 m0, s52, 0x2000
	s_add_u32 s52, s30, 0x20000
	v_lshl_add_u64 v[174:175], s[30:31], 0, v[166:167]
	s_addc_u32 s53, s31, 0
	s_add_i32 s54, s54, s36
	global_load_lds_dwordx4 v[174:175], off
	ds_read_b128 v[216:219], v199 offset:19456
	ds_read_b128 v[220:223], v199 offset:20480
	v_lshl_add_u64 v[176:177], s[52:53], 0, v[0:1]
	s_mov_b32 m0, s54
	v_lshl_add_u64 v[200:201], s[34:35], 0, v[164:165]
	global_load_lds_dwordx4 v[176:177], off
	ds_read_b128 v[224:227], v199 offset:21504
	ds_read_b128 v[228:231], v199 offset:22528
	v_lshl_add_u64 v[176:177], s[52:53], 0, v[166:167]
	s_add_i32 m0, s54, 0x2000
	s_nop 0
	global_load_lds_dwordx4 v[176:177], off
	ds_read_b128 v[232:235], v199 offset:23552
	v_lshl_add_u64 v[176:177], s[34:35], 0, v[162:163]
	s_mov_b32 m0, s37
	s_nop 0
	global_load_lds_dwordx4 v[176:177], off
	s_mov_b32 m0, s38
	s_nop 0
	global_load_lds_dwordx4 v[200:201], off
	s_waitcnt vmcnt(8)
	s_waitcnt lgkmcnt(0)
	s_barrier
	s_setprio 1
	s_waitcnt lgkmcnt(0)
	v_mfma_f32_16x16x32_bf16 v[94:97], v[18:21], v[182:185], v[94:97]
	v_mfma_f32_16x16x32_bf16 v[90:93], v[26:29], v[182:185], v[90:93]
	v_mfma_f32_16x16x32_bf16 v[78:81], v[18:21], v[212:215], v[78:81]
	v_mfma_f32_16x16x32_bf16 v[74:77], v[26:29], v[212:215], v[74:77]
	v_mfma_f32_16x16x32_bf16 v[62:65], v[18:21], v[220:223], v[62:65]
	v_mfma_f32_16x16x32_bf16 v[58:61], v[26:29], v[220:223], v[58:61]
	v_mfma_f32_16x16x32_bf16 v[14:17], v[18:21], v[228:231], v[14:17]
	v_mfma_f32_16x16x32_bf16 v[10:13], v[26:29], v[228:231], v[10:13]
	v_mfma_f32_16x16x32_bf16 v[94:97], v[22:25], v[186:189], v[94:97]
	v_mfma_f32_16x16x32_bf16 v[90:93], v[30:33], v[186:189], v[90:93]
	v_mfma_f32_16x16x32_bf16 v[78:81], v[22:25], v[216:219], v[78:81]
	v_mfma_f32_16x16x32_bf16 v[74:77], v[30:33], v[216:219], v[74:77]
	v_mfma_f32_16x16x32_bf16 v[62:65], v[22:25], v[224:227], v[62:65]
	v_mfma_f32_16x16x32_bf16 v[58:61], v[30:33], v[224:227], v[58:61]
	v_mfma_f32_16x16x32_bf16 v[14:17], v[22:25], v[232:235], v[14:17]
	v_mfma_f32_16x16x32_bf16 v[10:13], v[30:33], v[232:235], v[10:13]
	s_setprio 0
	s_setprio 1
	v_mfma_f32_16x16x32_bf16 v[38:41], v[42:45], v[220:223], v[38:41]
	v_mfma_f32_16x16x32_bf16 v[34:37], v[50:53], v[220:223], v[34:37]
	v_mfma_f32_16x16x32_bf16 v[6:9], v[42:45], v[228:231], v[6:9]
	v_mfma_f32_16x16x32_bf16 v[2:5], v[50:53], v[228:231], v[2:5]
	v_mfma_f32_16x16x32_bf16 v[18:21], v[42:45], v[182:185], v[86:89]
	v_mfma_f32_16x16x32_bf16 v[22:25], v[50:53], v[182:185], v[82:85]
	v_mfma_f32_16x16x32_bf16 v[26:29], v[42:45], v[212:215], v[70:73]
	v_mfma_f32_16x16x32_bf16 v[30:33], v[50:53], v[212:215], v[66:69]
	v_mfma_f32_16x16x32_bf16 v[38:41], v[46:49], v[224:227], v[38:41]
	v_mfma_f32_16x16x32_bf16 v[34:37], v[54:57], v[224:227], v[34:37]
	v_mfma_f32_16x16x32_bf16 v[6:9], v[46:49], v[232:235], v[6:9]
	v_mfma_f32_16x16x32_bf16 v[2:5], v[54:57], v[232:235], v[2:5]
	v_mfma_f32_16x16x32_bf16 v[18:21], v[46:49], v[186:189], v[18:21]
	v_mfma_f32_16x16x32_bf16 v[22:25], v[54:57], v[186:189], v[22:25]
	v_mfma_f32_16x16x32_bf16 v[26:29], v[46:49], v[216:219], v[26:29]
	v_mfma_f32_16x16x32_bf16 v[30:33], v[54:57], v[216:219], v[30:33]
	s_setprio 0
	s_barrier
; #define PG8_STAGE(bufoff, gbase, voff) do { _Pragma("unroll") for (int _i = 0; _i < 2; ++_i) \
;         __builtin_amdgcn_global_load_lds((const unsigned*)((const char*)(gbase) + (voff)[_i]), (LAS unsigned*)(lds + (bufoff) + ldsw + _i * 8192), 16, 0, 0); } while (0)
; #define PG8_LDA(dst, b, h) do { _Pragma("unroll") for (int m = 0; m < 4; ++m) _Pragma("unroll") for (int k = 0; k < 2; ++k) dst[m][k] = *(const LAS bf16x8*)(lds + PG8_SA(b, h) + aoff + m * 2048 + k * 1024); } while (0)
; #define PG8_LDB(dst, b, h) do { _Pragma("unroll") for (int n = 0; n < 2; ++n) _Pragma("unroll") for (int k = 0; k < 2; ++k) dst[n][k] = *(const LAS bf16x8*)(lds + PG8_SB(b, h) + boff + n * 2048 + k * 1024); } while (0)
; #define PG8_MMA(ai, bj, At, Bt) do { __builtin_amdgcn_s_setprio(1); _Pragma("unroll") for (int m = 0; m < 4; ++m) _Pragma("unroll") for (int n = 0; n < 2; ++n) _Pragma("unroll") for (int k = 0; k < 2; ++k) \
;         acc[ai][bj][m][n] = __builtin_amdgcn_mfma_f32_16x16x32_bf16(Bt[n][k], At[m][k], acc[ai][bj][m][n], 0, 0, 0); __builtin_amdgcn_s_setprio(0); } while (0)
; #define PG8_WAIT_V(n) asm volatile("s_waitcnt vmcnt(" #n ")" ::: "memory")
; #define PG8_WAIT_L(n) asm volatile("s_waitcnt lgkmcnt(" #n ")" ::: "memory")
; #define PG8_BAR __builtin_amdgcn_s_barrier()
; #define PG8_SCHED __builtin_amdgcn_sched_barrier(0)
; template <class Epi>
; __device__ __forceinline__ void gemm_phase(LAS unsigned char* lds, const Gemm g, const StaticOrder& S, const Epi& E, const int tid) {
;     ...
;             PG8_LDB(B0, 1, 0); PG8_LDB(B1, 1, 1); PG8_SCHED; PG8_LDA(At, 1, 0); PG8_STAGE(PG8_SA(0, 1), a2 + hstep, voffA);
;             PG8_WAIT_V(8); PG8_WAIT_L(0); PG8_BAR; PG8_MMA(0, 0, At, B0); PG8_MMA(0, 1, At, B1); PG8_BAR; PG8_SCHED;
	s_add_i32 s52, 0, 0x18000
	s_add_i32 s53, 0, 0x1c000
	v_add_u32_e32 v54, s52, v193
	v_add_u32_e32 v66, s53, v193
	ds_read_b128 v[42:45], v54
	ds_read_b128 v[46:49], v54 offset:1024
	ds_read_b128 v[50:53], v54 offset:2048
	ds_read_b128 v[54:57], v54 offset:3072
	ds_read_b128 v[182:185], v66
	ds_read_b128 v[186:189], v66 offset:1024
	ds_read_b128 v[212:215], v66 offset:2048
	ds_read_b128 v[216:219], v66 offset:3072
	s_add_u32 s34, s34, 0x200000
	s_addc_u32 s35, s35, 0
	s_mov_b32 m0, s39
	v_lshl_add_u64 v[236:237], s[34:35], 0, v[162:163]
	ds_read_b128 v[66:69], v199 offset:32768
	global_load_lds_dwordx4 v[236:237], off
	ds_read_b128 v[70:73], v199 offset:33792
	ds_read_b128 v[82:85], v199 offset:34816
	v_lshl_add_u64 v[236:237], s[34:35], 0, v[164:165]
	s_mov_b32 m0, s44
	s_nop 0
	global_load_lds_dwordx4 v[236:237], off
	ds_read_b128 v[86:89], v199 offset:35840
	ds_read_b128 v[220:223], v199 offset:36864
	ds_read_b128 v[224:227], v199 offset:37888
	ds_read_b128 v[228:231], v199 offset:38912
	ds_read_b128 v[232:235], v199 offset:39936
	s_waitcnt vmcnt(8)
	s_waitcnt lgkmcnt(0)
	s_barrier
	s_setprio 1
	s_waitcnt lgkmcnt(0)
	v_mfma_f32_16x16x32_bf16 v[158:161], v[42:45], v[66:69], v[158:161]
	v_mfma_f32_16x16x32_bf16 v[154:157], v[50:53], v[66:69], v[154:157]
	v_mfma_f32_16x16x32_bf16 v[142:145], v[42:45], v[82:85], v[142:145]
	v_mfma_f32_16x16x32_bf16 v[138:141], v[50:53], v[82:85], v[138:141]
	v_mfma_f32_16x16x32_bf16 v[126:129], v[42:45], v[220:223], v[126:129]
	v_mfma_f32_16x16x32_bf16 v[122:125], v[50:53], v[220:223], v[122:125]
	v_mfma_f32_16x16x32_bf16 v[110:113], v[42:45], v[228:231], v[110:113]
	v_mfma_f32_16x16x32_bf16 v[106:109], v[50:53], v[228:231], v[106:109]
	v_mfma_f32_16x16x32_bf16 v[158:161], v[46:49], v[70:73], v[158:161]
	v_mfma_f32_16x16x32_bf16 v[154:157], v[54:57], v[70:73], v[154:157]
	v_mfma_f32_16x16x32_bf16 v[142:145], v[46:49], v[86:89], v[142:145]
	v_mfma_f32_16x16x32_bf16 v[138:141], v[54:57], v[86:89], v[138:141]
	v_mfma_f32_16x16x32_bf16 v[126:129], v[46:49], v[224:227], v[126:129]
	v_mfma_f32_16x16x32_bf16 v[122:125], v[54:57], v[224:227], v[122:125]
	v_mfma_f32_16x16x32_bf16 v[110:113], v[46:49], v[232:235], v[110:113]
	v_mfma_f32_16x16x32_bf16 v[106:109], v[54:57], v[232:235], v[106:109]
	s_setprio 0
	s_setprio 1
	v_mfma_f32_16x16x32_bf16 v[150:153], v[182:185], v[66:69], v[150:153]
	v_mfma_f32_16x16x32_bf16 v[66:69], v[212:215], v[66:69], v[146:149]
	v_mfma_f32_16x16x32_bf16 v[146:149], v[216:219], v[70:73], v[66:69]
	v_mfma_f32_16x16x32_bf16 v[66:69], v[182:185], v[82:85], v[134:137]
	v_mfma_f32_16x16x32_bf16 v[134:137], v[186:189], v[86:89], v[66:69]
	v_mfma_f32_16x16x32_bf16 v[66:69], v[212:215], v[82:85], v[130:133]
	v_mfma_f32_16x16x32_bf16 v[130:133], v[216:219], v[86:89], v[66:69]
	v_mfma_f32_16x16x32_bf16 v[66:69], v[182:185], v[220:223], v[118:121]
	v_mfma_f32_16x16x32_bf16 v[118:121], v[186:189], v[224:227], v[66:69]
	v_mfma_f32_16x16x32_bf16 v[66:69], v[212:215], v[220:223], v[114:117]
	v_mfma_f32_16x16x32_bf16 v[114:117], v[216:219], v[224:227], v[66:69]
	v_mfma_f32_16x16x32_bf16 v[66:69], v[182:185], v[228:231], v[102:105]
	v_mfma_f32_16x16x32_bf16 v[102:105], v[186:189], v[232:235], v[66:69]
	v_mfma_f32_16x16x32_bf16 v[66:69], v[212:215], v[228:231], v[98:101]
	v_mfma_f32_16x16x32_bf16 v[150:153], v[186:189], v[70:73], v[150:153]
	v_mfma_f32_16x16x32_bf16 v[98:101], v[216:219], v[232:235], v[66:69]
	s_setprio 0
	s_barrier
; #define PG8_STAGE(bufoff, gbase, voff) do { _Pragma("unroll") for (int _i = 0; _i < 2; ++_i) \
;         __builtin_amdgcn_global_load_lds((const unsigned*)((const char*)(gbase) + (voff)[_i]), (LAS unsigned*)(lds + (bufoff) + ldsw + _i * 8192), 16, 0, 0); } while (0)
; #define PG8_LDA(dst, b, h) do { _Pragma("unroll") for (int m = 0; m < 4; ++m) _Pragma("unroll") for (int k = 0; k < 2; ++k) dst[m][k] = *(const LAS bf16x8*)(lds + PG8_SA(b, h) + aoff + m * 2048 + k * 1024); } while (0)
; #define PG8_MMA(ai, bj, At, Bt) do { __builtin_amdgcn_s_setprio(1); _Pragma("unroll") for (int m = 0; m < 4; ++m) _Pragma("unroll") for (int n = 0; n < 2; ++n) _Pragma("unroll") for (int k = 0; k < 2; ++k) \
;         acc[ai][bj][m][n] = __builtin_amdgcn_mfma_f32_16x16x32_bf16(Bt[n][k], At[m][k], acc[ai][bj][m][n], 0, 0, 0); __builtin_amdgcn_s_setprio(0); } while (0)
; #define PG8_WAIT_V(n) asm volatile("s_waitcnt vmcnt(" #n ")" ::: "memory")
; #define PG8_WAIT_L(n) asm volatile("s_waitcnt lgkmcnt(" #n ")" ::: "memory")
; #define PG8_BAR __builtin_amdgcn_s_barrier()
; #define PG8_SCHED __builtin_amdgcn_sched_barrier(0)
; template <class Epi>
; __device__ __forceinline__ void gemm_phase(LAS unsigned char* lds, const Gemm g, const StaticOrder& S, const Epi& E, const int tid) {
;     ...
;         for (int t = 0; t < ntt; t += 2) {
;             const bool last = (t == ntt - 2);
;             const bool s1 = Epi::TWO && (t >= nt), s2 = Epi::TWO && (t + 2 >= nt);
;             const char* a1 = (s1 ? cA2 + (size_t)(t - nt + 1) * kstep : cA + (size_t)(t + 1) * kstep);
;             const char* a2 = last ? nA : (s2 ? cA2 + (size_t)(t + 2 - nt) * kstep : cA + (size_t)(t + 2) * kstep);
;             const char* b2 = last ? nB : (s2 ? cB2 + (size_t)(t + 2 - nt) * kstep : cB + (size_t)(t + 2) * kstep);
;             const char* a3 = a2 + kstep; const char* b3 = b2 + kstep;
;     ...
;             PG8_LDA(At, 1, 1); PG8_STAGE(PG8_SB(1, 0), b3, voffB); PG8_STAGE(PG8_SB(1, 1), b3 + bhs, voffB); PG8_STAGE(PG8_SA(1, 0), a3, voffA);
;             PG8_WAIT_V(8); PG8_WAIT_L(0); PG8_BAR; PG8_MMA(1, 0, At, B0); PG8_MMA(1, 1, At, B1); PG8_BAR; PG8_SCHED;
	s_add_i32 s34, s52, s36
	v_lshl_add_u64 v[82:83], v[172:173], 0, s[70:71]
	s_mov_b32 m0, s34
	s_nop 0
	ds_read_b128 v[66:69], v199 offset:49152
	global_load_lds_dwordx4 v[82:83], off
	ds_read_b128 v[70:73], v199 offset:50176
	ds_read_b128 v[220:223], v199 offset:51200
	s_add_i32 m0, s34, 0x2000
	s_add_u32 s30, s30, 0x20080
	v_lshl_add_u64 v[82:83], v[174:175], 0, s[70:71]
	s_addc_u32 s31, s31, 0
	s_add_i32 s34, s53, s36
	global_load_lds_dwordx4 v[82:83], off
	ds_read_b128 v[224:227], v199 offset:52224
	ds_read_b128 v[228:231], v199 offset:53248
	v_lshl_add_u64 v[82:83], s[30:31], 0, v[0:1]
	s_mov_b32 m0, s34
	s_nop 0
	global_load_lds_dwordx4 v[82:83], off
	ds_read_b128 v[232:235], v199 offset:54272
	ds_read_b128 v[236:239], v199 offset:55296
	v_lshl_add_u64 v[82:83], s[30:31], 0, v[166:167]
	s_add_i32 m0, s34, 0x2000
	s_nop 0
	global_load_lds_dwordx4 v[82:83], off
	ds_read_b128 v[240:243], v199 offset:56320
	v_lshl_add_u64 v[82:83], v[176:177], 0, s[70:71]
	s_mov_b32 m0, s45
	s_nop 0
	global_load_lds_dwordx4 v[82:83], off
	v_lshl_add_u64 v[82:83], v[200:201], 0, s[70:71]
	s_mov_b32 m0, s46
	s_nop 0
	global_load_lds_dwordx4 v[82:83], off
	s_waitcnt vmcnt(8)
	s_waitcnt lgkmcnt(0)
	s_barrier
	s_setprio 1
	s_waitcnt lgkmcnt(0)
	v_mfma_f32_16x16x32_bf16 v[82:85], v[42:45], v[66:69], v[94:97]
	v_mfma_f32_16x16x32_bf16 v[94:97], v[46:49], v[70:73], v[82:85]
	v_mfma_f32_16x16x32_bf16 v[82:85], v[50:53], v[66:69], v[90:93]
	v_mfma_f32_16x16x32_bf16 v[78:81], v[42:45], v[220:223], v[78:81]
	v_mfma_f32_16x16x32_bf16 v[74:77], v[50:53], v[220:223], v[74:77]
	v_mfma_f32_16x16x32_bf16 v[62:65], v[42:45], v[228:231], v[62:65]
	v_mfma_f32_16x16x32_bf16 v[58:61], v[50:53], v[228:231], v[58:61]
	v_mfma_f32_16x16x32_bf16 v[14:17], v[42:45], v[236:239], v[14:17]
	v_mfma_f32_16x16x32_bf16 v[10:13], v[50:53], v[236:239], v[10:13]
	v_mfma_f32_16x16x32_bf16 v[90:93], v[54:57], v[70:73], v[82:85]
	v_mfma_f32_16x16x32_bf16 v[78:81], v[46:49], v[224:227], v[78:81]
	v_mfma_f32_16x16x32_bf16 v[74:77], v[54:57], v[224:227], v[74:77]
	v_mfma_f32_16x16x32_bf16 v[62:65], v[46:49], v[232:235], v[62:65]
	v_mfma_f32_16x16x32_bf16 v[58:61], v[54:57], v[232:235], v[58:61]
	v_mfma_f32_16x16x32_bf16 v[14:17], v[46:49], v[240:243], v[14:17]
	v_mfma_f32_16x16x32_bf16 v[10:13], v[54:57], v[240:243], v[10:13]
	s_setprio 0
	s_setprio 1
	v_mfma_f32_16x16x32_bf16 v[18:21], v[182:185], v[66:69], v[18:21]
	s_add_i32 s51, s51, 2
	v_mfma_f32_16x16x32_bf16 v[86:89], v[186:189], v[70:73], v[18:21]
	s_add_u32 s49, s49, 0x100
	v_mfma_f32_16x16x32_bf16 v[18:21], v[212:215], v[66:69], v[22:25]
	s_addc_u32 s50, s50, 0
	v_mfma_f32_16x16x32_bf16 v[82:85], v[216:219], v[70:73], v[18:21]
	s_add_u32 s28, s28, 0x100
	v_mfma_f32_16x16x32_bf16 v[18:21], v[182:185], v[220:223], v[26:29]
	s_addc_u32 s29, s29, 0
	v_mfma_f32_16x16x32_bf16 v[70:73], v[186:189], v[224:227], v[18:21]
	s_add_u32 s30, s28, 0xffe00080
	v_mfma_f32_16x16x32_bf16 v[18:21], v[212:215], v[220:223], v[30:33]
	s_addc_u32 s31, s29, -1
	v_mfma_f32_16x16x32_bf16 v[66:69], v[216:219], v[224:227], v[18:21]
	s_add_i32 s52, 0, 0x10000
	v_mfma_f32_16x16x32_bf16 v[18:21], v[182:185], v[228:231], v[38:41]
	s_cmpk_eq_i32 s51, 0x7c
	v_mfma_f32_16x16x32_bf16 v[38:41], v[186:189], v[232:235], v[18:21]
	s_cselect_b32 s35, s17, s31
	v_mfma_f32_16x16x32_bf16 v[18:21], v[212:215], v[228:231], v[34:37]
	s_cselect_b32 s34, s27, s30
	v_mfma_f32_16x16x32_bf16 v[6:9], v[182:185], v[236:239], v[6:9]
	s_cselect_b32 s31, s15, s50
	v_mfma_f32_16x16x32_bf16 v[2:5], v[212:215], v[236:239], v[2:5]
	s_cselect_b32 s30, s33, s49
	v_mfma_f32_16x16x32_bf16 v[34:37], v[216:219], v[232:235], v[18:21]
	s_add_i32 s54, 0, 0x14000
	v_mfma_f32_16x16x32_bf16 v[6:9], v[186:189], v[240:243], v[6:9]
	s_cmpk_gt_u32 s51, 0x7d
	v_mfma_f32_16x16x32_bf16 v[2:5], v[216:219], v[240:243], v[2:5]
	s_setprio 0
	s_barrier
	s_cbranch_scc0 .LBB0_126
	s_and_b64 vcc, exec, s[12:13]
	s_cbranch_vccz .LBB0_129
	s_barrier

; #define PG8_STAGE(bufoff, gbase, voff) do { _Pragma("unroll") for (int _i = 0; _i < 2; ++_i) \
;         __builtin_amdgcn_global_load_lds((const unsigned*)((const char*)(gbase) + (voff)[_i]), (LAS unsigned*)(lds + (bufoff) + ldsw + _i * 8192), 16, 0, 0); } while (0)
; #define PG8_LDA(dst, b, h) do { _Pragma("unroll") for (int m = 0; m < 4; ++m) _Pragma("unroll") for (int k = 0; k < 2; ++k) dst[m][k] = *(const LAS bf16x8*)(lds + PG8_SA(b, h) + aoff + m * 2048 + k * 1024); } while (0)
; #define PG8_LDB(dst, b, h) do { _Pragma("unroll") for (int n = 0; n < 2; ++n) _Pragma("unroll") for (int k = 0; k < 2; ++k) dst[n][k] = *(const LAS bf16x8*)(lds + PG8_SB(b, h) + boff + n * 2048 + k * 1024); } while (0)
; #define PG8_BAR __builtin_amdgcn_s_barrier()
; template <class Epi>
; __device__ __forceinline__ void gemm_phase(LAS unsigned char* lds, const Gemm g, const StaticOrder& S, const Epi& E, const int tid) {
;     ...
;         const bool has_next = S.next(ui + 1, nxt);
;         const char* nA = has_next ? (const char*)g.A + (size_t)nxt.pm * tstep : cA; const char* nB = has_next ? (const char*)g.Bt + (size_t)nxt.pn * tstep : cB;
;         for (int t = 0; t < ntt; t += 2) {
;             const bool last = (t == ntt - 2);
;             const bool s1 = Epi::TWO && (t >= nt), s2 = Epi::TWO && (t + 2 >= nt);
;             const char* a1 = (s1 ? cA2 + (size_t)(t - nt + 1) * kstep : cA + (size_t)(t + 1) * kstep);
;             const char* a2 = last ? nA : (s2 ? cA2 + (size_t)(t + 2 - nt) * kstep : cA + (size_t)(t + 2) * kstep);
;             const char* b2 = last ? nB : (s2 ? cB2 + (size_t)(t + 2 - nt) * kstep : cB + (size_t)(t + 2) * kstep);
;             const char* a3 = a2 + kstep; const char* b3 = b2 + kstep;
;             if constexpr (Epi::TWO) { if (t == nt) E.mid(acc, cur, wr, wc, fr, fq); }
;             if constexpr (SP2) {
;             PG8_LDB(B0, 0, 0); PG8_LDB(B1, 0, 1); PG8_SCHED; PG8_LDA(At, 0, 0); PG8_STAGE(PG8_SA(1, 1), a1 + hstep, voffA);
;             PG8_WAIT_V(8); PG8_WAIT_L(0); PG8_BAR; PG8_MMA(0, 0, At, B0); PG8_MMA(0, 1, At, B1); PG8_BAR; PG8_SCHED;
;     ...
; #pragma unroll
;         for (int a = 0; a < 2; ++a)
; #pragma unroll
;             for (int b = 0; b < 2; ++b)
; #pragma unroll
;                 for (int m = 0; m < 4; ++m)
; #pragma unroll
;                     for (int n = 0; n < 2; ++n) acc[a][b][m][n] = (f32x4){0.f, 0.f, 0.f, 0.f};
.LBB0_172:
	s_ashr_i32 s17, s16, 31
	s_lshl_b64 s[18:19], s[16:17], 20
	v_readlane_b32 s20, v251, 31
	v_readlane_b32 s21, v251, 32
	s_add_u32 s18, s20, s18
	s_addc_u32 s19, s21, s19
	s_and_b64 s[20:21], s[22:23], exec
	s_cselect_b32 s17, s19, s29
	s_cselect_b32 s42, s18, s28
	s_ashr_i32 s15, s14, 31
	s_lshl_b64 s[20:21], s[14:15], 20
	s_add_u32 s20, s8, s20
	s_addc_u32 s21, s9, s21
	s_and_b64 s[30:31], s[22:23], exec
	s_cselect_b32 s15, s21, s27
	s_cselect_b32 s43, s20, s26
	s_add_u32 s44, s26, 0x100
	s_addc_u32 s45, s27, 0
	s_add_u32 s26, s28, 0x80080
	v_mov_b32_e32 v2, 0
	s_addc_u32 s27, s29, 0
	s_mov_b32 s46, -2
	v_mov_b32_e32 v3, v2
	v_mov_b32_e32 v4, v2
	v_mov_b32_e32 v5, v2
	v_mov_b32_e32 v6, v2
	v_mov_b32_e32 v7, v2
	v_mov_b32_e32 v8, v2
	v_mov_b32_e32 v9, v2
	v_mov_b32_e32 v18, v2
	v_mov_b32_e32 v19, v2
	v_mov_b32_e32 v20, v2
	v_mov_b32_e32 v21, v2
	v_mov_b32_e32 v22, v2
	v_mov_b32_e32 v23, v2
	v_mov_b32_e32 v24, v2
	v_mov_b32_e32 v25, v2
	v_mov_b32_e32 v34, v2
	v_mov_b32_e32 v35, v2
	v_mov_b32_e32 v36, v2
	v_mov_b32_e32 v37, v2
	v_mov_b32_e32 v38, v2
	v_mov_b32_e32 v39, v2
	v_mov_b32_e32 v40, v2
	v_mov_b32_e32 v41, v2
	v_mov_b32_e32 v50, v2
	v_mov_b32_e32 v51, v2
	v_mov_b32_e32 v52, v2
	v_mov_b32_e32 v53, v2
	v_mov_b32_e32 v54, v2
	v_mov_b32_e32 v55, v2
	v_mov_b32_e32 v56, v2
	v_mov_b32_e32 v57, v2
	v_mov_b32_e32 v10, v2
	v_mov_b32_e32 v11, v2
	v_mov_b32_e32 v12, v2
	v_mov_b32_e32 v13, v2
	v_mov_b32_e32 v14, v2
	v_mov_b32_e32 v15, v2
	v_mov_b32_e32 v16, v2
	v_mov_b32_e32 v17, v2
	v_mov_b32_e32 v26, v2
	v_mov_b32_e32 v27, v2
	v_mov_b32_e32 v28, v2
	v_mov_b32_e32 v29, v2
	v_mov_b32_e32 v30, v2
	v_mov_b32_e32 v31, v2
	v_mov_b32_e32 v32, v2
	v_mov_b32_e32 v33, v2
	v_mov_b32_e32 v42, v2
	v_mov_b32_e32 v43, v2
	v_mov_b32_e32 v44, v2
	v_mov_b32_e32 v45, v2
	v_mov_b32_e32 v46, v2
	v_mov_b32_e32 v47, v2
	v_mov_b32_e32 v48, v2
	v_mov_b32_e32 v49, v2
	v_mov_b32_e32 v58, v2
	v_mov_b32_e32 v59, v2
	v_mov_b32_e32 v60, v2
	v_mov_b32_e32 v61, v2
	v_mov_b32_e32 v62, v2
	v_mov_b32_e32 v63, v2
	v_mov_b32_e32 v64, v2
	v_mov_b32_e32 v65, v2
	v_mov_b32_e32 v66, v2
	v_mov_b32_e32 v67, v2
	v_mov_b32_e32 v68, v2
	v_mov_b32_e32 v69, v2
	v_mov_b32_e32 v70, v2
	v_mov_b32_e32 v71, v2
	v_mov_b32_e32 v72, v2
	v_mov_b32_e32 v73, v2
	v_mov_b32_e32 v82, v2
	v_mov_b32_e32 v83, v2
	v_mov_b32_e32 v84, v2
	v_mov_b32_e32 v85, v2
	v_mov_b32_e32 v86, v2
	v_mov_b32_e32 v87, v2
	v_mov_b32_e32 v88, v2
	v_mov_b32_e32 v89, v2
	v_mov_b32_e32 v98, v2
	v_mov_b32_e32 v99, v2
	v_mov_b32_e32 v100, v2
	v_mov_b32_e32 v101, v2
	v_mov_b32_e32 v102, v2
	v_mov_b32_e32 v103, v2
	v_mov_b32_e32 v104, v2
	v_mov_b32_e32 v105, v2
	v_mov_b32_e32 v114, v2
	v_mov_b32_e32 v115, v2
	v_mov_b32_e32 v116, v2
	v_mov_b32_e32 v117, v2
	v_mov_b32_e32 v118, v2
	v_mov_b32_e32 v119, v2
	v_mov_b32_e32 v120, v2
	v_mov_b32_e32 v121, v2
	v_mov_b32_e32 v74, v2
	v_mov_b32_e32 v75, v2
	v_mov_b32_e32 v76, v2
	v_mov_b32_e32 v77, v2
	v_mov_b32_e32 v78, v2
	v_mov_b32_e32 v79, v2
	v_mov_b32_e32 v80, v2
	v_mov_b32_e32 v81, v2
	v_mov_b32_e32 v90, v2
	v_mov_b32_e32 v91, v2
	v_mov_b32_e32 v92, v2
	v_mov_b32_e32 v93, v2
	v_mov_b32_e32 v94, v2
	v_mov_b32_e32 v95, v2
	v_mov_b32_e32 v96, v2
	v_mov_b32_e32 v97, v2
	v_mov_b32_e32 v106, v2
	v_mov_b32_e32 v107, v2
	v_mov_b32_e32 v108, v2
	v_mov_b32_e32 v109, v2
	v_mov_b32_e32 v110, v2
	v_mov_b32_e32 v111, v2
	v_mov_b32_e32 v112, v2
	v_mov_b32_e32 v113, v2
	v_mov_b32_e32 v122, v2
	v_mov_b32_e32 v123, v2
	v_mov_b32_e32 v124, v2
	v_mov_b32_e32 v125, v2
	v_mov_b32_e32 v126, v2
	v_mov_b32_e32 v127, v2
	v_mov_b32_e32 v128, v2
	v_mov_b32_e32 v129, v2
	s_add_u32 s28, s26, 0xfff80080
	s_addc_u32 s29, s27, -1
	s_add_i32 s47, 0, 0x10000
	s_cmp_eq_u32 s46, 28
	s_cselect_b32 s31, s17, s29
	s_cselect_b32 s30, s42, s28
	s_cselect_b32 s29, s15, s45
	s_cselect_b32 s28, s43, s44
	s_add_i32 s50, 0, 0x14000
.LBB0_173:
	v_add_u32_e32 v142, s47, v149
	ds_read_b128 v[156:159], v142
	ds_read_b128 v[160:163], v142 offset:1024
	ds_read_b128 v[164:167], v142 offset:2048
	ds_read_b128 v[178:181], v142 offset:3072
	v_add_u32_e32 v142, s50, v149
	ds_read_b128 v[182:185], v142
	ds_read_b128 v[186:189], v142 offset:1024
	ds_read_b128 v[190:193], v142 offset:2048
	ds_read_b128 v[194:197], v142 offset:3072
	v_lshl_add_u64 v[142:143], s[26:27], 0, v[140:141]
	s_add_i32 m0, s2, 0xc000
	ds_read_b128 v[198:201], v154
	global_load_lds_dwordx4 v[142:143], off
	ds_read_b128 v[212:215], v154 offset:1024
	ds_read_b128 v[216:219], v154 offset:2048
	v_lshl_add_u64 v[142:143], s[26:27], 0, v[138:139]
	s_add_i32 m0, s2, 0xe000
	s_nop 0
	global_load_lds_dwordx4 v[142:143], off
	ds_read_b128 v[220:223], v154 offset:3072
	ds_read_b128 v[224:227], v154 offset:4096
	ds_read_b128 v[228:231], v154 offset:5120
	ds_read_b128 v[232:235], v154 offset:6144
	ds_read_b128 v[236:239], v154 offset:7168
	s_waitcnt vmcnt(8)
	s_waitcnt lgkmcnt(0)
	s_barrier
; #define PG8_STAGE(bufoff, gbase, voff) do { _Pragma("unroll") for (int _i = 0; _i < 2; ++_i) \
;         __builtin_amdgcn_global_load_lds((const unsigned*)((const char*)(gbase) + (voff)[_i]), (LAS unsigned*)(lds + (bufoff) + ldsw + _i * 8192), 16, 0, 0); } while (0)
; #define PG8_LDA(dst, b, h) do { _Pragma("unroll") for (int m = 0; m < 4; ++m) _Pragma("unroll") for (int k = 0; k < 2; ++k) dst[m][k] = *(const LAS bf16x8*)(lds + PG8_SA(b, h) + aoff + m * 2048 + k * 1024); } while (0)
; #define PG8_LDB(dst, b, h) do { _Pragma("unroll") for (int n = 0; n < 2; ++n) _Pragma("unroll") for (int k = 0; k < 2; ++k) dst[n][k] = *(const LAS bf16x8*)(lds + PG8_SB(b, h) + boff + n * 2048 + k * 1024); } while (0)
; #define PG8_MMA(ai, bj, At, Bt) do { __builtin_amdgcn_s_setprio(1); _Pragma("unroll") for (int m = 0; m < 4; ++m) _Pragma("unroll") for (int n = 0; n < 2; ++n) _Pragma("unroll") for (int k = 0; k < 2; ++k) \
;         acc[ai][bj][m][n] = __builtin_amdgcn_mfma_f32_16x16x32_bf16(Bt[n][k], At[m][k], acc[ai][bj][m][n], 0, 0, 0); __builtin_amdgcn_s_setprio(0); } while (0)
; #define PG8_WAIT_V(n) asm volatile("s_waitcnt vmcnt(" #n ")" ::: "memory")
; #define PG8_WAIT_L(n) asm volatile("s_waitcnt lgkmcnt(" #n ")" ::: "memory")
; #define PG8_BAR __builtin_amdgcn_s_barrier()
; #define PG8_SCHED __builtin_amdgcn_sched_barrier(0)
; template <class Epi>
; __device__ __forceinline__ void gemm_phase(LAS unsigned char* lds, const Gemm g, const StaticOrder& S, const Epi& E, const int tid) {
;     ...
;             PG8_WAIT_V(8); PG8_WAIT_L(0); PG8_BAR; PG8_MMA(0, 0, At, B0); PG8_MMA(0, 1, At, B1); PG8_BAR; PG8_SCHED;
;             PG8_LDA(At, 0, 1); PG8_STAGE(PG8_SB(0, 0), b2, voffB); PG8_STAGE(PG8_SB(0, 1), b2 + bhs, voffB); PG8_STAGE(PG8_SA(0, 0), a2, voffA);
;             PG8_WAIT_V(8); PG8_WAIT_L(0); PG8_BAR; PG8_MMA(1, 0, At, B0); PG8_MMA(1, 1, At, B1); PG8_BAR; PG8_SCHED;
;             PG8_LDB(B0, 1, 0); PG8_LDB(B1, 1, 1); PG8_SCHED; PG8_LDA(At, 1, 0); PG8_STAGE(PG8_SA(0, 1), a2 + hstep, voffA);
	s_setprio 1
	s_waitcnt lgkmcnt(0)
	v_mfma_f32_16x16x32_bf16 v[126:129], v[156:159], v[198:201], v[126:129]
	v_mfma_f32_16x16x32_bf16 v[122:125], v[164:167], v[198:201], v[122:125]
	v_mfma_f32_16x16x32_bf16 v[110:113], v[156:159], v[216:219], v[110:113]
	v_mfma_f32_16x16x32_bf16 v[106:109], v[164:167], v[216:219], v[106:109]
	v_mfma_f32_16x16x32_bf16 v[94:97], v[156:159], v[224:227], v[94:97]
	v_mfma_f32_16x16x32_bf16 v[90:93], v[164:167], v[224:227], v[90:93]
	v_mfma_f32_16x16x32_bf16 v[78:81], v[156:159], v[232:235], v[78:81]
	v_mfma_f32_16x16x32_bf16 v[74:77], v[164:167], v[232:235], v[74:77]
	v_mfma_f32_16x16x32_bf16 v[126:129], v[160:163], v[212:215], v[126:129]
	v_mfma_f32_16x16x32_bf16 v[122:125], v[178:181], v[212:215], v[122:125]
	v_mfma_f32_16x16x32_bf16 v[110:113], v[160:163], v[220:223], v[110:113]
	v_mfma_f32_16x16x32_bf16 v[106:109], v[178:181], v[220:223], v[106:109]
	v_mfma_f32_16x16x32_bf16 v[94:97], v[160:163], v[228:231], v[94:97]
	v_mfma_f32_16x16x32_bf16 v[90:93], v[178:181], v[228:231], v[90:93]
	v_mfma_f32_16x16x32_bf16 v[78:81], v[160:163], v[236:239], v[78:81]
	v_mfma_f32_16x16x32_bf16 v[74:77], v[178:181], v[236:239], v[74:77]
	s_setprio 0
	s_setprio 1
	v_mfma_f32_16x16x32_bf16 v[118:121], v[182:185], v[198:201], v[118:121]
	v_mfma_f32_16x16x32_bf16 v[114:117], v[190:193], v[198:201], v[114:117]
	v_mfma_f32_16x16x32_bf16 v[102:105], v[182:185], v[216:219], v[102:105]
	v_mfma_f32_16x16x32_bf16 v[98:101], v[190:193], v[216:219], v[98:101]
	v_mfma_f32_16x16x32_bf16 v[86:89], v[182:185], v[224:227], v[86:89]
	v_mfma_f32_16x16x32_bf16 v[82:85], v[190:193], v[224:227], v[82:85]
	v_mfma_f32_16x16x32_bf16 v[70:73], v[182:185], v[232:235], v[70:73]
	v_mfma_f32_16x16x32_bf16 v[66:69], v[190:193], v[232:235], v[66:69]
	v_mfma_f32_16x16x32_bf16 v[118:121], v[186:189], v[212:215], v[118:121]
	v_mfma_f32_16x16x32_bf16 v[114:117], v[194:197], v[212:215], v[114:117]
	v_mfma_f32_16x16x32_bf16 v[102:105], v[186:189], v[220:223], v[102:105]
	v_mfma_f32_16x16x32_bf16 v[98:101], v[194:197], v[220:223], v[98:101]
	v_mfma_f32_16x16x32_bf16 v[86:89], v[186:189], v[228:231], v[86:89]
	v_mfma_f32_16x16x32_bf16 v[82:85], v[194:197], v[228:231], v[82:85]
	v_mfma_f32_16x16x32_bf16 v[70:73], v[186:189], v[236:239], v[70:73]
	v_mfma_f32_16x16x32_bf16 v[66:69], v[194:197], v[236:239], v[66:69]
	s_setprio 0
	s_barrier
	s_add_i32 s47, s47, s34
	v_lshl_add_u64 v[142:143], s[28:29], 0, v[0:1]
	s_mov_b32 m0, s47
	ds_read_b128 v[198:201], v154 offset:16384
	global_load_lds_dwordx4 v[142:143], off
	ds_read_b128 v[212:215], v154 offset:17408
	ds_read_b128 v[216:219], v154 offset:18432
	s_add_i32 m0, s47, 0x2000
	s_add_u32 s48, s28, 0x8000
	v_lshl_add_u64 v[168:169], s[28:29], 0, v[134:135]
	s_addc_u32 s49, s29, 0
	s_add_i32 s47, s50, s34
	global_load_lds_dwordx4 v[168:169], off
	ds_read_b128 v[220:223], v154 offset:19456
	ds_read_b128 v[224:227], v154 offset:20480
	v_lshl_add_u64 v[172:173], s[48:49], 0, v[0:1]
	s_mov_b32 m0, s47
	v_lshl_add_u64 v[174:175], s[30:31], 0, v[132:133]
	global_load_lds_dwordx4 v[172:173], off
	ds_read_b128 v[228:231], v154 offset:21504
	ds_read_b128 v[232:235], v154 offset:22528
	v_lshl_add_u64 v[172:173], s[48:49], 0, v[134:135]
	s_add_i32 m0, s47, 0x2000
	s_nop 0
	global_load_lds_dwordx4 v[172:173], off
	ds_read_b128 v[236:239], v154 offset:23552
	v_lshl_add_u64 v[172:173], s[30:31], 0, v[130:131]
	s_mov_b32 m0, s2
	s_nop 0
	global_load_lds_dwordx4 v[172:173], off
	s_mov_b32 m0, s25
	s_nop 0
	global_load_lds_dwordx4 v[174:175], off
	s_waitcnt vmcnt(8)
	s_waitcnt lgkmcnt(0)
	s_barrier
	s_setprio 1
	s_waitcnt lgkmcnt(0)
	v_mfma_f32_16x16x32_bf16 v[62:65], v[156:159], v[198:201], v[62:65]
	v_mfma_f32_16x16x32_bf16 v[58:61], v[164:167], v[198:201], v[58:61]
	v_mfma_f32_16x16x32_bf16 v[46:49], v[156:159], v[216:219], v[46:49]
	v_mfma_f32_16x16x32_bf16 v[42:45], v[164:167], v[216:219], v[42:45]
	v_mfma_f32_16x16x32_bf16 v[30:33], v[156:159], v[224:227], v[30:33]
	v_mfma_f32_16x16x32_bf16 v[26:29], v[164:167], v[224:227], v[26:29]
	v_mfma_f32_16x16x32_bf16 v[14:17], v[156:159], v[232:235], v[14:17]
	v_mfma_f32_16x16x32_bf16 v[10:13], v[164:167], v[232:235], v[10:13]
	v_mfma_f32_16x16x32_bf16 v[62:65], v[160:163], v[212:215], v[62:65]
	v_mfma_f32_16x16x32_bf16 v[58:61], v[178:181], v[212:215], v[58:61]
	v_mfma_f32_16x16x32_bf16 v[46:49], v[160:163], v[220:223], v[46:49]
	v_mfma_f32_16x16x32_bf16 v[42:45], v[178:181], v[220:223], v[42:45]
	v_mfma_f32_16x16x32_bf16 v[30:33], v[160:163], v[228:231], v[30:33]
	v_mfma_f32_16x16x32_bf16 v[26:29], v[178:181], v[228:231], v[26:29]
	v_mfma_f32_16x16x32_bf16 v[14:17], v[160:163], v[236:239], v[14:17]
	v_mfma_f32_16x16x32_bf16 v[10:13], v[178:181], v[236:239], v[10:13]
	s_setprio 0
	s_setprio 1
	v_mfma_f32_16x16x32_bf16 v[54:57], v[182:185], v[198:201], v[54:57]
	v_mfma_f32_16x16x32_bf16 v[50:53], v[190:193], v[198:201], v[50:53]
	v_mfma_f32_16x16x32_bf16 v[38:41], v[182:185], v[216:219], v[38:41]
	v_mfma_f32_16x16x32_bf16 v[34:37], v[190:193], v[216:219], v[34:37]
	v_mfma_f32_16x16x32_bf16 v[22:25], v[182:185], v[224:227], v[22:25]
	v_mfma_f32_16x16x32_bf16 v[18:21], v[190:193], v[224:227], v[18:21]
	v_mfma_f32_16x16x32_bf16 v[6:9], v[182:185], v[232:235], v[6:9]
	v_mfma_f32_16x16x32_bf16 v[2:5], v[190:193], v[232:235], v[2:5]
	v_mfma_f32_16x16x32_bf16 v[54:57], v[186:189], v[212:215], v[54:57]
	v_mfma_f32_16x16x32_bf16 v[50:53], v[194:197], v[212:215], v[50:53]
	v_mfma_f32_16x16x32_bf16 v[38:41], v[186:189], v[220:223], v[38:41]
	v_mfma_f32_16x16x32_bf16 v[34:37], v[194:197], v[220:223], v[34:37]
	v_mfma_f32_16x16x32_bf16 v[22:25], v[186:189], v[228:231], v[22:25]
	v_mfma_f32_16x16x32_bf16 v[18:21], v[194:197], v[228:231], v[18:21]
	v_mfma_f32_16x16x32_bf16 v[6:9], v[186:189], v[236:239], v[6:9]
	v_mfma_f32_16x16x32_bf16 v[2:5], v[194:197], v[236:239], v[2:5]
	s_setprio 0
	s_barrier
; #define PG8_STAGE(bufoff, gbase, voff) do { _Pragma("unroll") for (int _i = 0; _i < 2; ++_i) \
;         __builtin_amdgcn_global_load_lds((const unsigned*)((const char*)(gbase) + (voff)[_i]), (LAS unsigned*)(lds + (bufoff) + ldsw + _i * 8192), 16, 0, 0); } while (0)
; #define PG8_LDA(dst, b, h) do { _Pragma("unroll") for (int m = 0; m < 4; ++m) _Pragma("unroll") for (int k = 0; k < 2; ++k) dst[m][k] = *(const LAS bf16x8*)(lds + PG8_SA(b, h) + aoff + m * 2048 + k * 1024); } while (0)
; #define PG8_LDB(dst, b, h) do { _Pragma("unroll") for (int n = 0; n < 2; ++n) _Pragma("unroll") for (int k = 0; k < 2; ++k) dst[n][k] = *(const LAS bf16x8*)(lds + PG8_SB(b, h) + boff + n * 2048 + k * 1024); } while (0)
; #define PG8_MMA(ai, bj, At, Bt) do { __builtin_amdgcn_s_setprio(1); _Pragma("unroll") for (int m = 0; m < 4; ++m) _Pragma("unroll") for (int n = 0; n < 2; ++n) _Pragma("unroll") for (int k = 0; k < 2; ++k) \
;         acc[ai][bj][m][n] = __builtin_amdgcn_mfma_f32_16x16x32_bf16(Bt[n][k], At[m][k], acc[ai][bj][m][n], 0, 0, 0); __builtin_amdgcn_s_setprio(0); } while (0)
; #define PG8_WAIT_V(n) asm volatile("s_waitcnt vmcnt(" #n ")" ::: "memory")
; #define PG8_WAIT_L(n) asm volatile("s_waitcnt lgkmcnt(" #n ")" ::: "memory")
; #define PG8_BAR __builtin_amdgcn_s_barrier()
; #define PG8_SCHED __builtin_amdgcn_sched_barrier(0)
; template <class Epi>
; __device__ __forceinline__ void gemm_phase(LAS unsigned char* lds, const Gemm g, const StaticOrder& S, const Epi& E, const int tid) {
;     ...
;             PG8_LDB(B0, 1, 0); PG8_LDB(B1, 1, 1); PG8_SCHED; PG8_LDA(At, 1, 0); PG8_STAGE(PG8_SA(0, 1), a2 + hstep, voffA);
;             PG8_WAIT_V(8); PG8_WAIT_L(0); PG8_BAR; PG8_MMA(0, 0, At, B0); PG8_MMA(0, 1, At, B1); PG8_BAR; PG8_SCHED;
	s_add_i32 s47, 0, 0x18000
	v_add_u32_e32 v155, s47, v149
	s_add_i32 s48, 0, 0x1c000
	ds_read_b128 v[156:159], v155
	ds_read_b128 v[160:163], v155 offset:1024
	ds_read_b128 v[164:167], v155 offset:2048
	ds_read_b128 v[178:181], v155 offset:3072
	v_add_u32_e32 v155, s48, v149
	ds_read_b128 v[182:185], v155
	ds_read_b128 v[186:189], v155 offset:1024
	ds_read_b128 v[190:193], v155 offset:2048
	ds_read_b128 v[194:197], v155 offset:3072
	s_add_u32 s30, s30, 0x80000
	s_addc_u32 s31, s31, 0
	s_mov_b32 m0, s35
	v_lshl_add_u64 v[176:177], s[30:31], 0, v[130:131]
	ds_read_b128 v[198:201], v154 offset:32768
	global_load_lds_dwordx4 v[176:177], off
	ds_read_b128 v[212:215], v154 offset:33792
	ds_read_b128 v[216:219], v154 offset:34816
	v_lshl_add_u64 v[176:177], s[30:31], 0, v[132:133]
	s_mov_b32 m0, s36
	s_nop 0
	global_load_lds_dwordx4 v[176:177], off
	ds_read_b128 v[220:223], v154 offset:35840
	ds_read_b128 v[224:227], v154 offset:36864
	ds_read_b128 v[228:231], v154 offset:37888
	ds_read_b128 v[232:235], v154 offset:38912
	ds_read_b128 v[236:239], v154 offset:39936
	s_waitcnt vmcnt(8)
	s_waitcnt lgkmcnt(0)
	s_barrier
	s_setprio 1
	s_waitcnt lgkmcnt(0)
	v_mfma_f32_16x16x32_bf16 v[126:129], v[156:159], v[198:201], v[126:129]
	v_mfma_f32_16x16x32_bf16 v[122:125], v[164:167], v[198:201], v[122:125]
	v_mfma_f32_16x16x32_bf16 v[110:113], v[156:159], v[216:219], v[110:113]
	v_mfma_f32_16x16x32_bf16 v[106:109], v[164:167], v[216:219], v[106:109]
	v_mfma_f32_16x16x32_bf16 v[94:97], v[156:159], v[224:227], v[94:97]
	v_mfma_f32_16x16x32_bf16 v[90:93], v[164:167], v[224:227], v[90:93]
	v_mfma_f32_16x16x32_bf16 v[78:81], v[156:159], v[232:235], v[78:81]
	v_mfma_f32_16x16x32_bf16 v[74:77], v[164:167], v[232:235], v[74:77]
	v_mfma_f32_16x16x32_bf16 v[126:129], v[160:163], v[212:215], v[126:129]
	v_mfma_f32_16x16x32_bf16 v[122:125], v[178:181], v[212:215], v[122:125]
	v_mfma_f32_16x16x32_bf16 v[110:113], v[160:163], v[220:223], v[110:113]
	v_mfma_f32_16x16x32_bf16 v[106:109], v[178:181], v[220:223], v[106:109]
	v_mfma_f32_16x16x32_bf16 v[94:97], v[160:163], v[228:231], v[94:97]
	v_mfma_f32_16x16x32_bf16 v[90:93], v[178:181], v[228:231], v[90:93]
	v_mfma_f32_16x16x32_bf16 v[78:81], v[160:163], v[236:239], v[78:81]
	v_mfma_f32_16x16x32_bf16 v[74:77], v[178:181], v[236:239], v[74:77]
	s_setprio 0
	s_setprio 1
	v_mfma_f32_16x16x32_bf16 v[118:121], v[182:185], v[198:201], v[118:121]
	v_mfma_f32_16x16x32_bf16 v[114:117], v[190:193], v[198:201], v[114:117]
	v_mfma_f32_16x16x32_bf16 v[102:105], v[182:185], v[216:219], v[102:105]
	v_mfma_f32_16x16x32_bf16 v[98:101], v[190:193], v[216:219], v[98:101]
	v_mfma_f32_16x16x32_bf16 v[86:89], v[182:185], v[224:227], v[86:89]
	v_mfma_f32_16x16x32_bf16 v[82:85], v[190:193], v[224:227], v[82:85]
	v_mfma_f32_16x16x32_bf16 v[70:73], v[182:185], v[232:235], v[70:73]
	v_mfma_f32_16x16x32_bf16 v[66:69], v[190:193], v[232:235], v[66:69]
	v_mfma_f32_16x16x32_bf16 v[118:121], v[186:189], v[212:215], v[118:121]
	v_mfma_f32_16x16x32_bf16 v[114:117], v[194:197], v[212:215], v[114:117]
	v_mfma_f32_16x16x32_bf16 v[102:105], v[186:189], v[220:223], v[102:105]
	v_mfma_f32_16x16x32_bf16 v[98:101], v[194:197], v[220:223], v[98:101]
	v_mfma_f32_16x16x32_bf16 v[86:89], v[186:189], v[228:231], v[86:89]
	v_mfma_f32_16x16x32_bf16 v[82:85], v[194:197], v[228:231], v[82:85]
	v_mfma_f32_16x16x32_bf16 v[70:73], v[186:189], v[236:239], v[70:73]
	v_mfma_f32_16x16x32_bf16 v[66:69], v[194:197], v[236:239], v[66:69]
	s_setprio 0
	s_barrier
; #define PG8_STAGE(bufoff, gbase, voff) do { _Pragma("unroll") for (int _i = 0; _i < 2; ++_i) \
;         __builtin_amdgcn_global_load_lds((const unsigned*)((const char*)(gbase) + (voff)[_i]), (LAS unsigned*)(lds + (bufoff) + ldsw + _i * 8192), 16, 0, 0); } while (0)
; #define PG8_LDA(dst, b, h) do { _Pragma("unroll") for (int m = 0; m < 4; ++m) _Pragma("unroll") for (int k = 0; k < 2; ++k) dst[m][k] = *(const LAS bf16x8*)(lds + PG8_SA(b, h) + aoff + m * 2048 + k * 1024); } while (0)
; #define PG8_MMA(ai, bj, At, Bt) do { __builtin_amdgcn_s_setprio(1); _Pragma("unroll") for (int m = 0; m < 4; ++m) _Pragma("unroll") for (int n = 0; n < 2; ++n) _Pragma("unroll") for (int k = 0; k < 2; ++k) \
;         acc[ai][bj][m][n] = __builtin_amdgcn_mfma_f32_16x16x32_bf16(Bt[n][k], At[m][k], acc[ai][bj][m][n], 0, 0, 0); __builtin_amdgcn_s_setprio(0); } while (0)
; #define PG8_WAIT_V(n) asm volatile("s_waitcnt vmcnt(" #n ")" ::: "memory")
; #define PG8_WAIT_L(n) asm volatile("s_waitcnt lgkmcnt(" #n ")" ::: "memory")
; #define PG8_BAR __builtin_amdgcn_s_barrier()
; #define PG8_SCHED __builtin_amdgcn_sched_barrier(0)
; template <class Epi>
; __device__ __forceinline__ void gemm_phase(LAS unsigned char* lds, const Gemm g, const StaticOrder& S, const Epi& E, const int tid) {
;     ...
;         for (int t = 0; t < ntt; t += 2) {
;             const bool last = (t == ntt - 2);
;             const bool s1 = Epi::TWO && (t >= nt), s2 = Epi::TWO && (t + 2 >= nt);
;             const char* a1 = (s1 ? cA2 + (size_t)(t - nt + 1) * kstep : cA + (size_t)(t + 1) * kstep);
;             const char* a2 = last ? nA : (s2 ? cA2 + (size_t)(t + 2 - nt) * kstep : cA + (size_t)(t + 2) * kstep);
;             const char* b2 = last ? nB : (s2 ? cB2 + (size_t)(t + 2 - nt) * kstep : cB + (size_t)(t + 2) * kstep);
;             const char* a3 = a2 + kstep; const char* b3 = b2 + kstep;
;     ...
;             PG8_LDA(At, 1, 1); PG8_STAGE(PG8_SB(1, 0), b3, voffB); PG8_STAGE(PG8_SB(1, 1), b3 + bhs, voffB); PG8_STAGE(PG8_SA(1, 0), a3, voffA);
;             PG8_WAIT_V(8); PG8_WAIT_L(0); PG8_BAR; PG8_MMA(1, 0, At, B0); PG8_MMA(1, 1, At, B1); PG8_BAR; PG8_SCHED;
	s_add_i32 s30, s47, s34
	v_lshl_add_u64 v[142:143], v[142:143], 0, s[70:71]
	s_mov_b32 m0, s30
	ds_read_b128 v[198:201], v154 offset:49152
	global_load_lds_dwordx4 v[142:143], off
	ds_read_b128 v[212:215], v154 offset:50176
	ds_read_b128 v[216:219], v154 offset:51200
	s_add_i32 m0, s30, 0x2000
	s_add_u32 s28, s28, 0x8080
	v_lshl_add_u64 v[142:143], v[168:169], 0, s[70:71]
	s_addc_u32 s29, s29, 0
	s_add_i32 s30, s48, s34
	global_load_lds_dwordx4 v[142:143], off
	ds_read_b128 v[220:223], v154 offset:52224
	ds_read_b128 v[224:227], v154 offset:53248
	v_lshl_add_u64 v[142:143], s[28:29], 0, v[0:1]
	s_mov_b32 m0, s30
	s_nop 0
	global_load_lds_dwordx4 v[142:143], off
	ds_read_b128 v[228:231], v154 offset:54272
	ds_read_b128 v[232:235], v154 offset:55296
	v_lshl_add_u64 v[142:143], s[28:29], 0, v[134:135]
	s_add_i32 m0, s30, 0x2000
	s_nop 0
	global_load_lds_dwordx4 v[142:143], off
	ds_read_b128 v[236:239], v154 offset:56320
	v_lshl_add_u64 v[142:143], v[172:173], 0, s[70:71]
	s_mov_b32 m0, s37
	s_nop 0
	global_load_lds_dwordx4 v[142:143], off
	v_lshl_add_u64 v[142:143], v[174:175], 0, s[70:71]
	s_mov_b32 m0, s38
	s_nop 0
	global_load_lds_dwordx4 v[142:143], off
	s_waitcnt vmcnt(8)
	s_waitcnt lgkmcnt(0)
	s_barrier
	s_setprio 1
	s_waitcnt lgkmcnt(0)
	v_mfma_f32_16x16x32_bf16 v[62:65], v[156:159], v[198:201], v[62:65]
	v_mfma_f32_16x16x32_bf16 v[58:61], v[164:167], v[198:201], v[58:61]
	v_mfma_f32_16x16x32_bf16 v[46:49], v[156:159], v[216:219], v[46:49]
	v_mfma_f32_16x16x32_bf16 v[42:45], v[164:167], v[216:219], v[42:45]
	v_mfma_f32_16x16x32_bf16 v[30:33], v[156:159], v[224:227], v[30:33]
	v_mfma_f32_16x16x32_bf16 v[26:29], v[164:167], v[224:227], v[26:29]
	v_mfma_f32_16x16x32_bf16 v[14:17], v[156:159], v[232:235], v[14:17]
	v_mfma_f32_16x16x32_bf16 v[10:13], v[164:167], v[232:235], v[10:13]
	v_mfma_f32_16x16x32_bf16 v[62:65], v[160:163], v[212:215], v[62:65]
	v_mfma_f32_16x16x32_bf16 v[58:61], v[178:181], v[212:215], v[58:61]
	v_mfma_f32_16x16x32_bf16 v[46:49], v[160:163], v[220:223], v[46:49]
	v_mfma_f32_16x16x32_bf16 v[42:45], v[178:181], v[220:223], v[42:45]
	v_mfma_f32_16x16x32_bf16 v[30:33], v[160:163], v[228:231], v[30:33]
	v_mfma_f32_16x16x32_bf16 v[26:29], v[178:181], v[228:231], v[26:29]
	v_mfma_f32_16x16x32_bf16 v[14:17], v[160:163], v[236:239], v[14:17]
	v_mfma_f32_16x16x32_bf16 v[10:13], v[178:181], v[236:239], v[10:13]
	s_setprio 0
	s_setprio 1
	v_mfma_f32_16x16x32_bf16 v[54:57], v[182:185], v[198:201], v[54:57]
	s_add_i32 s46, s46, 2
	v_mfma_f32_16x16x32_bf16 v[50:53], v[190:193], v[198:201], v[50:53]
	s_add_u32 s44, s44, 0x100
	v_mfma_f32_16x16x32_bf16 v[38:41], v[182:185], v[216:219], v[38:41]
	s_addc_u32 s45, s45, 0
	v_mfma_f32_16x16x32_bf16 v[34:37], v[190:193], v[216:219], v[34:37]
	s_add_u32 s26, s26, 0x100
	v_mfma_f32_16x16x32_bf16 v[22:25], v[182:185], v[224:227], v[22:25]
	s_addc_u32 s27, s27, 0
	v_mfma_f32_16x16x32_bf16 v[18:21], v[190:193], v[224:227], v[18:21]
	s_add_u32 s28, s26, 0xfff80080
	v_mfma_f32_16x16x32_bf16 v[6:9], v[182:185], v[232:235], v[6:9]
	s_addc_u32 s29, s27, -1
	v_mfma_f32_16x16x32_bf16 v[2:5], v[190:193], v[232:235], v[2:5]
	s_add_i32 s47, 0, 0x10000
	v_mfma_f32_16x16x32_bf16 v[54:57], v[186:189], v[212:215], v[54:57]
	s_cmp_eq_u32 s46, 28
	v_mfma_f32_16x16x32_bf16 v[50:53], v[194:197], v[212:215], v[50:53]
	s_cselect_b32 s31, s17, s29
	v_mfma_f32_16x16x32_bf16 v[38:41], v[186:189], v[220:223], v[38:41]
	s_cselect_b32 s30, s42, s28
	v_mfma_f32_16x16x32_bf16 v[34:37], v[194:197], v[220:223], v[34:37]
	s_cselect_b32 s29, s15, s45
	v_mfma_f32_16x16x32_bf16 v[22:25], v[186:189], v[228:231], v[22:25]
	s_cselect_b32 s28, s43, s44
	v_mfma_f32_16x16x32_bf16 v[18:21], v[194:197], v[228:231], v[18:21]
	s_add_i32 s50, 0, 0x14000
	v_mfma_f32_16x16x32_bf16 v[6:9], v[186:189], v[236:239], v[6:9]
	s_cmp_gt_u32 s46, 29
	v_mfma_f32_16x16x32_bf16 v[2:5], v[194:197], v[236:239], v[2:5]
	s_setprio 0
	s_barrier
	s_cbranch_scc0 .LBB0_173
	v_readlane_b32 s42, v251, 53
	s_and_b64 vcc, exec, s[12:13]
	v_readlane_b32 s43, v251, 54
	s_cbranch_vccz .LBB0_176
	s_barrier

; #define PG8_STAGE(bufoff, gbase, voff) do { _Pragma("unroll") for (int _i = 0; _i < 2; ++_i) \
;         __builtin_amdgcn_global_load_lds((const unsigned*)((const char*)(gbase) + (voff)[_i]), (LAS unsigned*)(lds + (bufoff) + ldsw + _i * 8192), 16, 0, 0); } while (0)
; #define PG8_LDA(dst, b, h) do { _Pragma("unroll") for (int m = 0; m < 4; ++m) _Pragma("unroll") for (int k = 0; k < 2; ++k) dst[m][k] = *(const LAS bf16x8*)(lds + PG8_SA(b, h) + aoff + m * 2048 + k * 1024); } while (0)
; #define PG8_LDB(dst, b, h) do { _Pragma("unroll") for (int n = 0; n < 2; ++n) _Pragma("unroll") for (int k = 0; k < 2; ++k) dst[n][k] = *(const LAS bf16x8*)(lds + PG8_SB(b, h) + boff + n * 2048 + k * 1024); } while (0)
; #define PG8_BAR __builtin_amdgcn_s_barrier()
; template <class Epi>
; __device__ __forceinline__ void gemm_phase(LAS unsigned char* lds, const Gemm g, const StaticOrder& S, const Epi& E, const int tid) {
;     ...
;         const bool has_next = S.next(ui + 1, nxt);
;         const char* nA = has_next ? (const char*)g.A + (size_t)nxt.pm * tstep : cA; const char* nB = has_next ? (const char*)g.Bt + (size_t)nxt.pn * tstep : cB;
;         for (int t = 0; t < ntt; t += 2) {
;             const bool last = (t == ntt - 2);
;             const bool s1 = Epi::TWO && (t >= nt), s2 = Epi::TWO && (t + 2 >= nt);
;             const char* a1 = (s1 ? cA2 + (size_t)(t - nt + 1) * kstep : cA + (size_t)(t + 1) * kstep);
;             const char* a2 = last ? nA : (s2 ? cA2 + (size_t)(t + 2 - nt) * kstep : cA + (size_t)(t + 2) * kstep);
;             const char* b2 = last ? nB : (s2 ? cB2 + (size_t)(t + 2 - nt) * kstep : cB + (size_t)(t + 2) * kstep);
;             const char* a3 = a2 + kstep; const char* b3 = b2 + kstep;
;             if constexpr (Epi::TWO) { if (t == nt) E.mid(acc, cur, wr, wc, fr, fq); }
;             if constexpr (SP2) {
;             PG8_LDB(B0, 0, 0); PG8_LDB(B1, 0, 1); PG8_SCHED; PG8_LDA(At, 0, 0); PG8_STAGE(PG8_SA(1, 1), a1 + hstep, voffA);
;             PG8_WAIT_V(8); PG8_WAIT_L(0); PG8_BAR; PG8_MMA(0, 0, At, B0); PG8_MMA(0, 1, At, B1); PG8_BAR; PG8_SCHED;
;     ...
; #pragma unroll
;         for (int a = 0; a < 2; ++a)
; #pragma unroll
;             for (int b = 0; b < 2; ++b)
; #pragma unroll
;                 for (int m = 0; m < 4; ++m)
; #pragma unroll
;                     for (int n = 0; n < 2; ++n) acc[a][b][m][n] = (f32x4){0.f, 0.f, 0.f, 0.f};
.LBB0_205:
	s_ashr_i32 s17, s16, 31
	s_lshl_b64 s[18:19], s[16:17], 18
	v_readlane_b32 s20, v251, 47
	v_readlane_b32 s21, v251, 48
	s_add_u32 s18, s20, s18
	s_addc_u32 s19, s21, s19
	s_and_b64 s[20:21], s[22:23], exec
	s_cselect_b32 s17, s19, s31
	s_cselect_b32 s27, s18, s30
	s_ashr_i32 s15, s14, 31
	s_lshl_b64 s[20:21], s[14:15], 18
	v_readlane_b32 s34, v251, 39
	v_readlane_b32 s35, v251, 40
	s_add_u32 s20, s34, s20
	s_addc_u32 s21, s35, s21
	s_and_b64 s[34:35], s[22:23], exec
	s_cselect_b32 s15, s21, s29
	s_cselect_b32 s33, s20, s28
	s_add_u32 s49, s28, 0x100
	s_addc_u32 s50, s29, 0
	s_add_u32 s28, s30, 0x20080
	v_mov_b32_e32 v2, 0
	s_addc_u32 s29, s31, 0
	s_mov_b32 s51, -2
	v_mov_b32_e32 v3, v2
	s_waitcnt lgkmcnt(0)
	v_mov_b32_e32 v4, v2
	v_mov_b32_e32 v5, v2
	v_mov_b32_e32 v6, v2
	v_mov_b32_e32 v7, v2
	v_mov_b32_e32 v8, v2
	v_mov_b32_e32 v9, v2
	v_mov_b32_e32 v34, v2
	v_mov_b32_e32 v35, v2
	v_mov_b32_e32 v36, v2
	v_mov_b32_e32 v37, v2
	v_mov_b32_e32 v38, v2
	v_mov_b32_e32 v39, v2
	v_mov_b32_e32 v40, v2
	v_mov_b32_e32 v41, v2
	v_mov_b32_e32 v66, v2
	v_mov_b32_e32 v67, v2
	v_mov_b32_e32 v68, v2
	v_mov_b32_e32 v69, v2
	v_mov_b32_e32 v70, v2
	v_mov_b32_e32 v71, v2
	v_mov_b32_e32 v72, v2
	v_mov_b32_e32 v73, v2
	v_mov_b32_e32 v82, v2
	v_mov_b32_e32 v83, v2
	v_mov_b32_e32 v84, v2
	v_mov_b32_e32 v85, v2
	v_mov_b32_e32 v86, v2
	v_mov_b32_e32 v87, v2
	v_mov_b32_e32 v88, v2
	v_mov_b32_e32 v89, v2
	v_mov_b32_e32 v10, v2
	v_mov_b32_e32 v11, v2
	v_mov_b32_e32 v12, v2
	v_mov_b32_e32 v13, v2
	v_mov_b32_e32 v14, v2
	v_mov_b32_e32 v15, v2
	v_mov_b32_e32 v16, v2
	v_mov_b32_e32 v17, v2
	v_mov_b32_e32 v58, v2
	v_mov_b32_e32 v59, v2
	v_mov_b32_e32 v60, v2
	v_mov_b32_e32 v61, v2
	v_mov_b32_e32 v62, v2
	v_mov_b32_e32 v63, v2
	v_mov_b32_e32 v64, v2
	v_mov_b32_e32 v65, v2
	v_mov_b32_e32 v74, v2
	v_mov_b32_e32 v75, v2
	v_mov_b32_e32 v76, v2
	v_mov_b32_e32 v77, v2
	v_mov_b32_e32 v78, v2
	v_mov_b32_e32 v79, v2
	v_mov_b32_e32 v80, v2
	v_mov_b32_e32 v81, v2
	v_mov_b32_e32 v90, v2
	v_mov_b32_e32 v91, v2
	v_mov_b32_e32 v92, v2
	v_mov_b32_e32 v93, v2
	v_mov_b32_e32 v94, v2
	v_mov_b32_e32 v95, v2
	v_mov_b32_e32 v96, v2
	v_mov_b32_e32 v97, v2
	v_mov_b32_e32 v98, v2
	v_mov_b32_e32 v99, v2
	v_mov_b32_e32 v100, v2
	v_mov_b32_e32 v101, v2
	v_mov_b32_e32 v102, v2
	v_mov_b32_e32 v103, v2
	v_mov_b32_e32 v104, v2
	v_mov_b32_e32 v105, v2
	v_mov_b32_e32 v114, v2
	v_mov_b32_e32 v115, v2
	v_mov_b32_e32 v116, v2
	v_mov_b32_e32 v117, v2
	v_mov_b32_e32 v118, v2
	v_mov_b32_e32 v119, v2
	v_mov_b32_e32 v120, v2
	v_mov_b32_e32 v121, v2
	v_mov_b32_e32 v130, v2
	v_mov_b32_e32 v131, v2
	v_mov_b32_e32 v132, v2
	v_mov_b32_e32 v133, v2
	v_mov_b32_e32 v134, v2
	v_mov_b32_e32 v135, v2
	v_mov_b32_e32 v136, v2
	v_mov_b32_e32 v137, v2
	v_mov_b32_e32 v146, v2
	v_mov_b32_e32 v147, v2
	v_mov_b32_e32 v148, v2
	v_mov_b32_e32 v149, v2
	v_mov_b32_e32 v150, v2
	v_mov_b32_e32 v151, v2
	v_mov_b32_e32 v152, v2
	v_mov_b32_e32 v153, v2
	v_mov_b32_e32 v106, v2
	v_mov_b32_e32 v107, v2
	v_mov_b32_e32 v108, v2
	v_mov_b32_e32 v109, v2
	v_mov_b32_e32 v110, v2
	v_mov_b32_e32 v111, v2
	v_mov_b32_e32 v112, v2
	v_mov_b32_e32 v113, v2
	v_mov_b32_e32 v122, v2
	v_mov_b32_e32 v123, v2
	v_mov_b32_e32 v124, v2
	v_mov_b32_e32 v125, v2
	v_mov_b32_e32 v126, v2
	v_mov_b32_e32 v127, v2
	v_mov_b32_e32 v128, v2
	v_mov_b32_e32 v129, v2
	v_mov_b32_e32 v138, v2
	v_mov_b32_e32 v139, v2
	v_mov_b32_e32 v140, v2
	v_mov_b32_e32 v141, v2
	v_mov_b32_e32 v142, v2
	v_mov_b32_e32 v143, v2
	v_mov_b32_e32 v144, v2
	v_mov_b32_e32 v145, v2
	v_mov_b32_e32 v154, v2
	v_mov_b32_e32 v155, v2
	v_mov_b32_e32 v156, v2
	v_mov_b32_e32 v157, v2
	v_mov_b32_e32 v158, v2
	v_mov_b32_e32 v159, v2
	v_mov_b32_e32 v160, v2
	v_mov_b32_e32 v161, v2
	s_add_u32 s30, s28, 0xfffe0080
	s_addc_u32 s31, s29, -1
	s_add_i32 s52, 0, 0x10000
	s_cmp_eq_u32 s51, 4
	s_cselect_b32 s35, s17, s31
	s_cselect_b32 s34, s27, s30
	s_cselect_b32 s31, s15, s50
	s_cselect_b32 s30, s33, s49
	s_add_i32 s54, 0, 0x14000
.LBB0_206:
	v_add_u32_e32 v30, s52, v193
	v_add_u32_e32 v54, s54, v193
	ds_read_b128 v[18:21], v30
	ds_read_b128 v[22:25], v30 offset:1024
	ds_read_b128 v[26:29], v30 offset:2048
	ds_read_b128 v[30:33], v30 offset:3072
	ds_read_b128 v[42:45], v54
	ds_read_b128 v[46:49], v54 offset:1024
	ds_read_b128 v[50:53], v54 offset:2048
	ds_read_b128 v[54:57], v54 offset:3072
	v_lshl_add_u64 v[172:173], s[28:29], 0, v[180:181]
	s_add_i32 m0, s37, 0xc000
	ds_read_b128 v[182:185], v199
	global_load_lds_dwordx4 v[172:173], off
	ds_read_b128 v[186:189], v199 offset:1024
	ds_read_b128 v[212:215], v199 offset:2048
	v_lshl_add_u64 v[172:173], s[28:29], 0, v[178:179]
	s_add_i32 m0, s37, 0xe000
	s_nop 0
	global_load_lds_dwordx4 v[172:173], off
	ds_read_b128 v[216:219], v199 offset:3072
	ds_read_b128 v[220:223], v199 offset:4096
	ds_read_b128 v[224:227], v199 offset:5120
	ds_read_b128 v[228:231], v199 offset:6144
	ds_read_b128 v[232:235], v199 offset:7168
	s_waitcnt vmcnt(8)
	s_waitcnt lgkmcnt(0)
	s_barrier
; #define PG8_STAGE(bufoff, gbase, voff) do { _Pragma("unroll") for (int _i = 0; _i < 2; ++_i) \
;         __builtin_amdgcn_global_load_lds((const unsigned*)((const char*)(gbase) + (voff)[_i]), (LAS unsigned*)(lds + (bufoff) + ldsw + _i * 8192), 16, 0, 0); } while (0)
; #define PG8_LDA(dst, b, h) do { _Pragma("unroll") for (int m = 0; m < 4; ++m) _Pragma("unroll") for (int k = 0; k < 2; ++k) dst[m][k] = *(const LAS bf16x8*)(lds + PG8_SA(b, h) + aoff + m * 2048 + k * 1024); } while (0)
; #define PG8_LDB(dst, b, h) do { _Pragma("unroll") for (int n = 0; n < 2; ++n) _Pragma("unroll") for (int k = 0; k < 2; ++k) dst[n][k] = *(const LAS bf16x8*)(lds + PG8_SB(b, h) + boff + n * 2048 + k * 1024); } while (0)
; #define PG8_MMA(ai, bj, At, Bt) do { __builtin_amdgcn_s_setprio(1); _Pragma("unroll") for (int m = 0; m < 4; ++m) _Pragma("unroll") for (int n = 0; n < 2; ++n) _Pragma("unroll") for (int k = 0; k < 2; ++k) \
;         acc[ai][bj][m][n] = __builtin_amdgcn_mfma_f32_16x16x32_bf16(Bt[n][k], At[m][k], acc[ai][bj][m][n], 0, 0, 0); __builtin_amdgcn_s_setprio(0); } while (0)
; #define PG8_WAIT_V(n) asm volatile("s_waitcnt vmcnt(" #n ")" ::: "memory")
; #define PG8_WAIT_L(n) asm volatile("s_waitcnt lgkmcnt(" #n ")" ::: "memory")
; #define PG8_BAR __builtin_amdgcn_s_barrier()
; #define PG8_SCHED __builtin_amdgcn_sched_barrier(0)
; template <class Epi>
; __device__ __forceinline__ void gemm_phase(LAS unsigned char* lds, const Gemm g, const StaticOrder& S, const Epi& E, const int tid) {
;     ...
;             PG8_WAIT_V(8); PG8_WAIT_L(0); PG8_BAR; PG8_MMA(0, 0, At, B0); PG8_MMA(0, 1, At, B1); PG8_BAR; PG8_SCHED;
;             PG8_LDA(At, 0, 1); PG8_STAGE(PG8_SB(0, 0), b2, voffB); PG8_STAGE(PG8_SB(0, 1), b2 + bhs, voffB); PG8_STAGE(PG8_SA(0, 0), a2, voffA);
;             PG8_WAIT_V(8); PG8_WAIT_L(0); PG8_BAR; PG8_MMA(1, 0, At, B0); PG8_MMA(1, 1, At, B1); PG8_BAR; PG8_SCHED;
;             PG8_LDB(B0, 1, 0); PG8_LDB(B1, 1, 1); PG8_SCHED; PG8_LDA(At, 1, 0); PG8_STAGE(PG8_SA(0, 1), a2 + hstep, voffA);
	s_setprio 1
	s_waitcnt lgkmcnt(0)
	v_mfma_f32_16x16x32_bf16 v[158:161], v[18:21], v[182:185], v[158:161]
	v_mfma_f32_16x16x32_bf16 v[154:157], v[26:29], v[182:185], v[154:157]
	v_mfma_f32_16x16x32_bf16 v[142:145], v[18:21], v[212:215], v[142:145]
	v_mfma_f32_16x16x32_bf16 v[138:141], v[26:29], v[212:215], v[138:141]
	v_mfma_f32_16x16x32_bf16 v[126:129], v[18:21], v[220:223], v[126:129]
	v_mfma_f32_16x16x32_bf16 v[122:125], v[26:29], v[220:223], v[122:125]
	v_mfma_f32_16x16x32_bf16 v[110:113], v[18:21], v[228:231], v[110:113]
	v_mfma_f32_16x16x32_bf16 v[106:109], v[26:29], v[228:231], v[106:109]
	v_mfma_f32_16x16x32_bf16 v[158:161], v[22:25], v[186:189], v[158:161]
	v_mfma_f32_16x16x32_bf16 v[154:157], v[30:33], v[186:189], v[154:157]
	v_mfma_f32_16x16x32_bf16 v[142:145], v[22:25], v[216:219], v[142:145]
	v_mfma_f32_16x16x32_bf16 v[138:141], v[30:33], v[216:219], v[138:141]
	v_mfma_f32_16x16x32_bf16 v[126:129], v[22:25], v[224:227], v[126:129]
	v_mfma_f32_16x16x32_bf16 v[122:125], v[30:33], v[224:227], v[122:125]
	v_mfma_f32_16x16x32_bf16 v[110:113], v[22:25], v[232:235], v[110:113]
	v_mfma_f32_16x16x32_bf16 v[106:109], v[30:33], v[232:235], v[106:109]
	s_setprio 0
	s_setprio 1
	v_mfma_f32_16x16x32_bf16 v[150:153], v[42:45], v[182:185], v[150:153]
	v_mfma_f32_16x16x32_bf16 v[146:149], v[50:53], v[182:185], v[146:149]
	v_mfma_f32_16x16x32_bf16 v[134:137], v[42:45], v[212:215], v[134:137]
	v_mfma_f32_16x16x32_bf16 v[130:133], v[50:53], v[212:215], v[130:133]
	v_mfma_f32_16x16x32_bf16 v[118:121], v[42:45], v[220:223], v[118:121]
	v_mfma_f32_16x16x32_bf16 v[114:117], v[50:53], v[220:223], v[114:117]
	v_mfma_f32_16x16x32_bf16 v[102:105], v[42:45], v[228:231], v[102:105]
	v_mfma_f32_16x16x32_bf16 v[98:101], v[50:53], v[228:231], v[98:101]
	v_mfma_f32_16x16x32_bf16 v[150:153], v[46:49], v[186:189], v[150:153]
	v_mfma_f32_16x16x32_bf16 v[146:149], v[54:57], v[186:189], v[146:149]
	v_mfma_f32_16x16x32_bf16 v[134:137], v[46:49], v[216:219], v[134:137]
	v_mfma_f32_16x16x32_bf16 v[130:133], v[54:57], v[216:219], v[130:133]
	v_mfma_f32_16x16x32_bf16 v[118:121], v[46:49], v[224:227], v[118:121]
	v_mfma_f32_16x16x32_bf16 v[114:117], v[54:57], v[224:227], v[114:117]
	v_mfma_f32_16x16x32_bf16 v[102:105], v[46:49], v[232:235], v[102:105]
	v_mfma_f32_16x16x32_bf16 v[98:101], v[54:57], v[232:235], v[98:101]
	s_setprio 0
	s_barrier
	s_add_i32 s52, s52, s36
	v_lshl_add_u64 v[172:173], s[30:31], 0, v[0:1]
	s_mov_b32 m0, s52
	ds_read_b128 v[182:185], v199 offset:16384
	global_load_lds_dwordx4 v[172:173], off
	ds_read_b128 v[186:189], v199 offset:17408
	ds_read_b128 v[212:215], v199 offset:18432
	s_add_i32 m0, s52, 0x2000
	s_add_u32 s52, s30, 0x2000
	v_lshl_add_u64 v[174:175], s[30:31], 0, v[166:167]
	s_addc_u32 s53, s31, 0
	s_add_i32 s54, s54, s36
	global_load_lds_dwordx4 v[174:175], off
	ds_read_b128 v[216:219], v199 offset:19456
	ds_read_b128 v[220:223], v199 offset:20480
	v_lshl_add_u64 v[176:177], s[52:53], 0, v[0:1]
	s_mov_b32 m0, s54
	v_lshl_add_u64 v[200:201], s[34:35], 0, v[164:165]
	global_load_lds_dwordx4 v[176:177], off
	ds_read_b128 v[224:227], v199 offset:21504
	ds_read_b128 v[228:231], v199 offset:22528
	v_lshl_add_u64 v[176:177], s[52:53], 0, v[166:167]
	s_add_i32 m0, s54, 0x2000
	s_nop 0
	global_load_lds_dwordx4 v[176:177], off
	ds_read_b128 v[232:235], v199 offset:23552
	v_lshl_add_u64 v[176:177], s[34:35], 0, v[162:163]
	s_mov_b32 m0, s37
	s_nop 0
	global_load_lds_dwordx4 v[176:177], off
	s_mov_b32 m0, s38
	s_nop 0
	global_load_lds_dwordx4 v[200:201], off
	s_waitcnt vmcnt(8)
	s_waitcnt lgkmcnt(0)
	s_barrier
	s_setprio 1
	s_waitcnt lgkmcnt(0)
	v_mfma_f32_16x16x32_bf16 v[94:97], v[18:21], v[182:185], v[94:97]
	v_mfma_f32_16x16x32_bf16 v[90:93], v[26:29], v[182:185], v[90:93]
	v_mfma_f32_16x16x32_bf16 v[78:81], v[18:21], v[212:215], v[78:81]
	v_mfma_f32_16x16x32_bf16 v[74:77], v[26:29], v[212:215], v[74:77]
	v_mfma_f32_16x16x32_bf16 v[62:65], v[18:21], v[220:223], v[62:65]
	v_mfma_f32_16x16x32_bf16 v[58:61], v[26:29], v[220:223], v[58:61]
	v_mfma_f32_16x16x32_bf16 v[14:17], v[18:21], v[228:231], v[14:17]
	v_mfma_f32_16x16x32_bf16 v[10:13], v[26:29], v[228:231], v[10:13]
	v_mfma_f32_16x16x32_bf16 v[94:97], v[22:25], v[186:189], v[94:97]
	v_mfma_f32_16x16x32_bf16 v[90:93], v[30:33], v[186:189], v[90:93]
	v_mfma_f32_16x16x32_bf16 v[78:81], v[22:25], v[216:219], v[78:81]
	v_mfma_f32_16x16x32_bf16 v[74:77], v[30:33], v[216:219], v[74:77]
	v_mfma_f32_16x16x32_bf16 v[62:65], v[22:25], v[224:227], v[62:65]
	v_mfma_f32_16x16x32_bf16 v[58:61], v[30:33], v[224:227], v[58:61]
	v_mfma_f32_16x16x32_bf16 v[14:17], v[22:25], v[232:235], v[14:17]
	v_mfma_f32_16x16x32_bf16 v[10:13], v[30:33], v[232:235], v[10:13]
	s_setprio 0
	s_setprio 1
	v_mfma_f32_16x16x32_bf16 v[38:41], v[42:45], v[220:223], v[38:41]
	v_mfma_f32_16x16x32_bf16 v[34:37], v[50:53], v[220:223], v[34:37]
	v_mfma_f32_16x16x32_bf16 v[6:9], v[42:45], v[228:231], v[6:9]
	v_mfma_f32_16x16x32_bf16 v[2:5], v[50:53], v[228:231], v[2:5]
	v_mfma_f32_16x16x32_bf16 v[18:21], v[42:45], v[182:185], v[86:89]
	v_mfma_f32_16x16x32_bf16 v[22:25], v[50:53], v[182:185], v[82:85]
	v_mfma_f32_16x16x32_bf16 v[26:29], v[42:45], v[212:215], v[70:73]
	v_mfma_f32_16x16x32_bf16 v[30:33], v[50:53], v[212:215], v[66:69]
	v_mfma_f32_16x16x32_bf16 v[38:41], v[46:49], v[224:227], v[38:41]
	v_mfma_f32_16x16x32_bf16 v[34:37], v[54:57], v[224:227], v[34:37]
	v_mfma_f32_16x16x32_bf16 v[6:9], v[46:49], v[232:235], v[6:9]
	v_mfma_f32_16x16x32_bf16 v[2:5], v[54:57], v[232:235], v[2:5]
	v_mfma_f32_16x16x32_bf16 v[18:21], v[46:49], v[186:189], v[18:21]
	v_mfma_f32_16x16x32_bf16 v[22:25], v[54:57], v[186:189], v[22:25]
	v_mfma_f32_16x16x32_bf16 v[26:29], v[46:49], v[216:219], v[26:29]
	v_mfma_f32_16x16x32_bf16 v[30:33], v[54:57], v[216:219], v[30:33]
	s_setprio 0
	s_barrier
; #define PG8_STAGE(bufoff, gbase, voff) do { _Pragma("unroll") for (int _i = 0; _i < 2; ++_i) \
;         __builtin_amdgcn_global_load_lds((const unsigned*)((const char*)(gbase) + (voff)[_i]), (LAS unsigned*)(lds + (bufoff) + ldsw + _i * 8192), 16, 0, 0); } while (0)
; #define PG8_LDA(dst, b, h) do { _Pragma("unroll") for (int m = 0; m < 4; ++m) _Pragma("unroll") for (int k = 0; k < 2; ++k) dst[m][k] = *(const LAS bf16x8*)(lds + PG8_SA(b, h) + aoff + m * 2048 + k * 1024); } while (0)
; #define PG8_LDB(dst, b, h) do { _Pragma("unroll") for (int n = 0; n < 2; ++n) _Pragma("unroll") for (int k = 0; k < 2; ++k) dst[n][k] = *(const LAS bf16x8*)(lds + PG8_SB(b, h) + boff + n * 2048 + k * 1024); } while (0)
; #define PG8_MMA(ai, bj, At, Bt) do { __builtin_amdgcn_s_setprio(1); _Pragma("unroll") for (int m = 0; m < 4; ++m) _Pragma("unroll") for (int n = 0; n < 2; ++n) _Pragma("unroll") for (int k = 0; k < 2; ++k) \
;         acc[ai][bj][m][n] = __builtin_amdgcn_mfma_f32_16x16x32_bf16(Bt[n][k], At[m][k], acc[ai][bj][m][n], 0, 0, 0); __builtin_amdgcn_s_setprio(0); } while (0)
; #define PG8_WAIT_V(n) asm volatile("s_waitcnt vmcnt(" #n ")" ::: "memory")
; #define PG8_WAIT_L(n) asm volatile("s_waitcnt lgkmcnt(" #n ")" ::: "memory")
; #define PG8_BAR __builtin_amdgcn_s_barrier()
; #define PG8_SCHED __builtin_amdgcn_sched_barrier(0)
; template <class Epi>
; __device__ __forceinline__ void gemm_phase(LAS unsigned char* lds, const Gemm g, const StaticOrder& S, const Epi& E, const int tid) {
;     ...
;             PG8_LDB(B0, 1, 0); PG8_LDB(B1, 1, 1); PG8_SCHED; PG8_LDA(At, 1, 0); PG8_STAGE(PG8_SA(0, 1), a2 + hstep, voffA);
;             PG8_WAIT_V(8); PG8_WAIT_L(0); PG8_BAR; PG8_MMA(0, 0, At, B0); PG8_MMA(0, 1, At, B1); PG8_BAR; PG8_SCHED;
	s_add_i32 s52, 0, 0x18000
	s_add_i32 s53, 0, 0x1c000
	v_add_u32_e32 v54, s52, v193
	v_add_u32_e32 v66, s53, v193
	ds_read_b128 v[42:45], v54
	ds_read_b128 v[46:49], v54 offset:1024
	ds_read_b128 v[50:53], v54 offset:2048
	ds_read_b128 v[54:57], v54 offset:3072
	ds_read_b128 v[182:185], v66
	ds_read_b128 v[186:189], v66 offset:1024
	ds_read_b128 v[212:215], v66 offset:2048
	ds_read_b128 v[216:219], v66 offset:3072
	s_add_u32 s34, s34, 0x20000
	s_addc_u32 s35, s35, 0
	s_mov_b32 m0, s39
	v_lshl_add_u64 v[236:237], s[34:35], 0, v[162:163]
	ds_read_b128 v[66:69], v199 offset:32768
	global_load_lds_dwordx4 v[236:237], off
	ds_read_b128 v[70:73], v199 offset:33792
	ds_read_b128 v[82:85], v199 offset:34816
	v_lshl_add_u64 v[236:237], s[34:35], 0, v[164:165]
	s_mov_b32 m0, s44
	s_nop 0
	global_load_lds_dwordx4 v[236:237], off
	ds_read_b128 v[86:89], v199 offset:35840
	ds_read_b128 v[220:223], v199 offset:36864
	ds_read_b128 v[224:227], v199 offset:37888
	ds_read_b128 v[228:231], v199 offset:38912
	ds_read_b128 v[232:235], v199 offset:39936
	s_waitcnt vmcnt(8)
	s_waitcnt lgkmcnt(0)
	s_barrier
	s_setprio 1
	s_waitcnt lgkmcnt(0)
	v_mfma_f32_16x16x32_bf16 v[158:161], v[42:45], v[66:69], v[158:161]
	v_mfma_f32_16x16x32_bf16 v[154:157], v[50:53], v[66:69], v[154:157]
	v_mfma_f32_16x16x32_bf16 v[142:145], v[42:45], v[82:85], v[142:145]
	v_mfma_f32_16x16x32_bf16 v[138:141], v[50:53], v[82:85], v[138:141]
	v_mfma_f32_16x16x32_bf16 v[126:129], v[42:45], v[220:223], v[126:129]
	v_mfma_f32_16x16x32_bf16 v[122:125], v[50:53], v[220:223], v[122:125]
	v_mfma_f32_16x16x32_bf16 v[110:113], v[42:45], v[228:231], v[110:113]
	v_mfma_f32_16x16x32_bf16 v[106:109], v[50:53], v[228:231], v[106:109]
	v_mfma_f32_16x16x32_bf16 v[158:161], v[46:49], v[70:73], v[158:161]
	v_mfma_f32_16x16x32_bf16 v[154:157], v[54:57], v[70:73], v[154:157]
	v_mfma_f32_16x16x32_bf16 v[142:145], v[46:49], v[86:89], v[142:145]
	v_mfma_f32_16x16x32_bf16 v[138:141], v[54:57], v[86:89], v[138:141]
	v_mfma_f32_16x16x32_bf16 v[126:129], v[46:49], v[224:227], v[126:129]
	v_mfma_f32_16x16x32_bf16 v[122:125], v[54:57], v[224:227], v[122:125]
	v_mfma_f32_16x16x32_bf16 v[110:113], v[46:49], v[232:235], v[110:113]
	v_mfma_f32_16x16x32_bf16 v[106:109], v[54:57], v[232:235], v[106:109]
	s_setprio 0
	s_setprio 1
	v_mfma_f32_16x16x32_bf16 v[150:153], v[182:185], v[66:69], v[150:153]
	v_mfma_f32_16x16x32_bf16 v[66:69], v[212:215], v[66:69], v[146:149]
	v_mfma_f32_16x16x32_bf16 v[146:149], v[216:219], v[70:73], v[66:69]
	v_mfma_f32_16x16x32_bf16 v[66:69], v[182:185], v[82:85], v[134:137]
	v_mfma_f32_16x16x32_bf16 v[134:137], v[186:189], v[86:89], v[66:69]
	v_mfma_f32_16x16x32_bf16 v[66:69], v[212:215], v[82:85], v[130:133]
	v_mfma_f32_16x16x32_bf16 v[130:133], v[216:219], v[86:89], v[66:69]
	v_mfma_f32_16x16x32_bf16 v[66:69], v[182:185], v[220:223], v[118:121]
	v_mfma_f32_16x16x32_bf16 v[118:121], v[186:189], v[224:227], v[66:69]
	v_mfma_f32_16x16x32_bf16 v[66:69], v[212:215], v[220:223], v[114:117]
	v_mfma_f32_16x16x32_bf16 v[114:117], v[216:219], v[224:227], v[66:69]
	v_mfma_f32_16x16x32_bf16 v[66:69], v[182:185], v[228:231], v[102:105]
	v_mfma_f32_16x16x32_bf16 v[102:105], v[186:189], v[232:235], v[66:69]
	v_mfma_f32_16x16x32_bf16 v[66:69], v[212:215], v[228:231], v[98:101]
	v_mfma_f32_16x16x32_bf16 v[150:153], v[186:189], v[70:73], v[150:153]
	v_mfma_f32_16x16x32_bf16 v[98:101], v[216:219], v[232:235], v[66:69]
	s_setprio 0
	s_barrier
; #define PG8_STAGE(bufoff, gbase, voff) do { _Pragma("unroll") for (int _i = 0; _i < 2; ++_i) \
;         __builtin_amdgcn_global_load_lds((const unsigned*)((const char*)(gbase) + (voff)[_i]), (LAS unsigned*)(lds + (bufoff) + ldsw + _i * 8192), 16, 0, 0); } while (0)
; #define PG8_LDA(dst, b, h) do { _Pragma("unroll") for (int m = 0; m < 4; ++m) _Pragma("unroll") for (int k = 0; k < 2; ++k) dst[m][k] = *(const LAS bf16x8*)(lds + PG8_SA(b, h) + aoff + m * 2048 + k * 1024); } while (0)
; #define PG8_MMA(ai, bj, At, Bt) do { __builtin_amdgcn_s_setprio(1); _Pragma("unroll") for (int m = 0; m < 4; ++m) _Pragma("unroll") for (int n = 0; n < 2; ++n) _Pragma("unroll") for (int k = 0; k < 2; ++k) \
;         acc[ai][bj][m][n] = __builtin_amdgcn_mfma_f32_16x16x32_bf16(Bt[n][k], At[m][k], acc[ai][bj][m][n], 0, 0, 0); __builtin_amdgcn_s_setprio(0); } while (0)
; #define PG8_WAIT_V(n) asm volatile("s_waitcnt vmcnt(" #n ")" ::: "memory")
; #define PG8_WAIT_L(n) asm volatile("s_waitcnt lgkmcnt(" #n ")" ::: "memory")
; #define PG8_BAR __builtin_amdgcn_s_barrier()
; #define PG8_SCHED __builtin_amdgcn_sched_barrier(0)
; template <class Epi>
; __device__ __forceinline__ void gemm_phase(LAS unsigned char* lds, const Gemm g, const StaticOrder& S, const Epi& E, const int tid) {
;     ...
;         for (int t = 0; t < ntt; t += 2) {
;             const bool last = (t == ntt - 2);
;             const bool s1 = Epi::TWO && (t >= nt), s2 = Epi::TWO && (t + 2 >= nt);
;             const char* a1 = (s1 ? cA2 + (size_t)(t - nt + 1) * kstep : cA + (size_t)(t + 1) * kstep);
;             const char* a2 = last ? nA : (s2 ? cA2 + (size_t)(t + 2 - nt) * kstep : cA + (size_t)(t + 2) * kstep);
;             const char* b2 = last ? nB : (s2 ? cB2 + (size_t)(t + 2 - nt) * kstep : cB + (size_t)(t + 2) * kstep);
;             const char* a3 = a2 + kstep; const char* b3 = b2 + kstep;
;     ...
;             PG8_LDA(At, 1, 1); PG8_STAGE(PG8_SB(1, 0), b3, voffB); PG8_STAGE(PG8_SB(1, 1), b3 + bhs, voffB); PG8_STAGE(PG8_SA(1, 0), a3, voffA);
;             PG8_WAIT_V(8); PG8_WAIT_L(0); PG8_BAR; PG8_MMA(1, 0, At, B0); PG8_MMA(1, 1, At, B1); PG8_BAR; PG8_SCHED;
	s_add_i32 s34, s52, s36
	v_lshl_add_u64 v[82:83], v[172:173], 0, s[70:71]
	s_mov_b32 m0, s34
	s_nop 0
	ds_read_b128 v[66:69], v199 offset:49152
	global_load_lds_dwordx4 v[82:83], off
	ds_read_b128 v[70:73], v199 offset:50176
	ds_read_b128 v[220:223], v199 offset:51200
	s_add_i32 m0, s34, 0x2000
	s_add_u32 s30, s30, 0x2080
	v_lshl_add_u64 v[82:83], v[174:175], 0, s[70:71]
	s_addc_u32 s31, s31, 0
	s_add_i32 s34, s53, s36
	global_load_lds_dwordx4 v[82:83], off
	ds_read_b128 v[224:227], v199 offset:52224
	ds_read_b128 v[228:231], v199 offset:53248
	v_lshl_add_u64 v[82:83], s[30:31], 0, v[0:1]
	s_mov_b32 m0, s34
	s_nop 0
	global_load_lds_dwordx4 v[82:83], off
	ds_read_b128 v[232:235], v199 offset:54272
	ds_read_b128 v[236:239], v199 offset:55296
	v_lshl_add_u64 v[82:83], s[30:31], 0, v[166:167]
	s_add_i32 m0, s34, 0x2000
	s_nop 0
	global_load_lds_dwordx4 v[82:83], off
	ds_read_b128 v[240:243], v199 offset:56320
	v_lshl_add_u64 v[82:83], v[176:177], 0, s[70:71]
	s_mov_b32 m0, s45
	s_nop 0
	global_load_lds_dwordx4 v[82:83], off
	v_lshl_add_u64 v[82:83], v[200:201], 0, s[70:71]
	s_mov_b32 m0, s46
	s_nop 0
	global_load_lds_dwordx4 v[82:83], off
	s_waitcnt vmcnt(8)
	s_waitcnt lgkmcnt(0)
	s_barrier
	s_setprio 1
	s_waitcnt lgkmcnt(0)
	v_mfma_f32_16x16x32_bf16 v[82:85], v[42:45], v[66:69], v[94:97]
	v_mfma_f32_16x16x32_bf16 v[94:97], v[46:49], v[70:73], v[82:85]
	v_mfma_f32_16x16x32_bf16 v[82:85], v[50:53], v[66:69], v[90:93]
	v_mfma_f32_16x16x32_bf16 v[78:81], v[42:45], v[220:223], v[78:81]
	v_mfma_f32_16x16x32_bf16 v[74:77], v[50:53], v[220:223], v[74:77]
	v_mfma_f32_16x16x32_bf16 v[62:65], v[42:45], v[228:231], v[62:65]
	v_mfma_f32_16x16x32_bf16 v[58:61], v[50:53], v[228:231], v[58:61]
	v_mfma_f32_16x16x32_bf16 v[14:17], v[42:45], v[236:239], v[14:17]
	v_mfma_f32_16x16x32_bf16 v[10:13], v[50:53], v[236:239], v[10:13]
	v_mfma_f32_16x16x32_bf16 v[90:93], v[54:57], v[70:73], v[82:85]
	v_mfma_f32_16x16x32_bf16 v[78:81], v[46:49], v[224:227], v[78:81]
	v_mfma_f32_16x16x32_bf16 v[74:77], v[54:57], v[224:227], v[74:77]
	v_mfma_f32_16x16x32_bf16 v[62:65], v[46:49], v[232:235], v[62:65]
	v_mfma_f32_16x16x32_bf16 v[58:61], v[54:57], v[232:235], v[58:61]
	v_mfma_f32_16x16x32_bf16 v[14:17], v[46:49], v[240:243], v[14:17]
	v_mfma_f32_16x16x32_bf16 v[10:13], v[54:57], v[240:243], v[10:13]
	s_setprio 0
	s_setprio 1
	v_mfma_f32_16x16x32_bf16 v[18:21], v[182:185], v[66:69], v[18:21]
	s_add_i32 s51, s51, 2
	v_mfma_f32_16x16x32_bf16 v[86:89], v[186:189], v[70:73], v[18:21]
	s_add_u32 s49, s49, 0x100
	v_mfma_f32_16x16x32_bf16 v[18:21], v[212:215], v[66:69], v[22:25]
	s_addc_u32 s50, s50, 0
	v_mfma_f32_16x16x32_bf16 v[82:85], v[216:219], v[70:73], v[18:21]
	s_add_u32 s28, s28, 0x100
	v_mfma_f32_16x16x32_bf16 v[18:21], v[182:185], v[220:223], v[26:29]
	s_addc_u32 s29, s29, 0
	v_mfma_f32_16x16x32_bf16 v[70:73], v[186:189], v[224:227], v[18:21]
	s_add_u32 s30, s28, 0xfffe0080
	v_mfma_f32_16x16x32_bf16 v[18:21], v[212:215], v[220:223], v[30:33]
	s_addc_u32 s31, s29, -1
	v_mfma_f32_16x16x32_bf16 v[66:69], v[216:219], v[224:227], v[18:21]
	s_add_i32 s52, 0, 0x10000
	v_mfma_f32_16x16x32_bf16 v[18:21], v[182:185], v[228:231], v[38:41]
	s_cmp_eq_u32 s51, 4
	v_mfma_f32_16x16x32_bf16 v[38:41], v[186:189], v[232:235], v[18:21]
	s_cselect_b32 s35, s17, s31
	v_mfma_f32_16x16x32_bf16 v[18:21], v[212:215], v[228:231], v[34:37]
	s_cselect_b32 s34, s27, s30
	v_mfma_f32_16x16x32_bf16 v[6:9], v[182:185], v[236:239], v[6:9]
	s_cselect_b32 s31, s15, s50
	v_mfma_f32_16x16x32_bf16 v[2:5], v[212:215], v[236:239], v[2:5]
	s_cselect_b32 s30, s33, s49
	v_mfma_f32_16x16x32_bf16 v[34:37], v[216:219], v[232:235], v[18:21]
	s_add_i32 s54, 0, 0x14000
	v_mfma_f32_16x16x32_bf16 v[6:9], v[186:189], v[240:243], v[6:9]
	s_cmp_gt_u32 s51, 5
	v_mfma_f32_16x16x32_bf16 v[2:5], v[216:219], v[240:243], v[2:5]
	s_setprio 0
	s_barrier
	s_cbranch_scc0 .LBB0_206
	s_and_b64 vcc, exec, s[12:13]
	s_cbranch_vccz .LBB0_209
	s_barrier

; #define PG8_STAGE(bufoff, gbase, voff) do { _Pragma("unroll") for (int _i = 0; _i < 2; ++_i) \
;         __builtin_amdgcn_global_load_lds((const unsigned*)((const char*)(gbase) + (voff)[_i]), (LAS unsigned*)(lds + (bufoff) + ldsw + _i * 8192), 16, 0, 0); } while (0)
; #define PG8_LDA(dst, b, h) do { _Pragma("unroll") for (int m = 0; m < 4; ++m) _Pragma("unroll") for (int k = 0; k < 2; ++k) dst[m][k] = *(const LAS bf16x8*)(lds + PG8_SA(b, h) + aoff + m * 2048 + k * 1024); } while (0)
; #define PG8_LDB(dst, b, h) do { _Pragma("unroll") for (int n = 0; n < 2; ++n) _Pragma("unroll") for (int k = 0; k < 2; ++k) dst[n][k] = *(const LAS bf16x8*)(lds + PG8_SB(b, h) + boff + n * 2048 + k * 1024); } while (0)
; #define PG8_BAR __builtin_amdgcn_s_barrier()
; template <class Epi>
; __device__ __forceinline__ void gemm_phase(LAS unsigned char* lds, const Gemm g, const StaticOrder& S, const Epi& E, const int tid) {
;     ...
;         const bool has_next = S.next(ui + 1, nxt);
;         const char* nA = has_next ? (const char*)g.A + (size_t)nxt.pm * tstep : cA; const char* nB = has_next ? (const char*)g.Bt + (size_t)nxt.pn * tstep : cB;
;         for (int t = 0; t < ntt; t += 2) {
;             const bool last = (t == ntt - 2);
;             const bool s1 = Epi::TWO && (t >= nt), s2 = Epi::TWO && (t + 2 >= nt);
;             const char* a1 = (s1 ? cA2 + (size_t)(t - nt + 1) * kstep : cA + (size_t)(t + 1) * kstep);
;             const char* a2 = last ? nA : (s2 ? cA2 + (size_t)(t + 2 - nt) * kstep : cA + (size_t)(t + 2) * kstep);
;             const char* b2 = last ? nB : (s2 ? cB2 + (size_t)(t + 2 - nt) * kstep : cB + (size_t)(t + 2) * kstep);
;             const char* a3 = a2 + kstep; const char* b3 = b2 + kstep;
;             if constexpr (Epi::TWO) { if (t == nt) E.mid(acc, cur, wr, wc, fr, fq); }
;             if constexpr (SP2) {
;             PG8_LDB(B0, 0, 0); PG8_LDB(B1, 0, 1); PG8_SCHED; PG8_LDA(At, 0, 0); PG8_STAGE(PG8_SA(1, 1), a1 + hstep, voffA);
;             PG8_WAIT_V(8); PG8_WAIT_L(0); PG8_BAR; PG8_MMA(0, 0, At, B0); PG8_MMA(0, 1, At, B1); PG8_BAR; PG8_SCHED;
;     ...
; #pragma unroll
;         for (int a = 0; a < 2; ++a)
; #pragma unroll
;             for (int b = 0; b < 2; ++b)
; #pragma unroll
;                 for (int m = 0; m < 4; ++m)
; #pragma unroll
;                     for (int n = 0; n < 2; ++n) acc[a][b][m][n] = (f32x4){0.f, 0.f, 0.f, 0.f};
.LBB0_260:
	s_ashr_i32 s19, s18, 31
	s_lshl_b64 s[20:21], s[18:19], 20
	v_readlane_b32 s22, v251, 31
	v_readlane_b32 s23, v251, 32
	s_add_u32 s20, s22, s20
	s_addc_u32 s21, s23, s21
	s_and_b64 s[22:23], s[24:25], exec
	s_cselect_b32 s19, s21, s31
	s_cselect_b32 s44, s20, s30
	s_ashr_i32 s17, s16, 31
	s_lshl_b64 s[22:23], s[16:17], 20
	v_readlane_b32 s34, v251, 37
	v_readlane_b32 s35, v251, 38
	s_add_u32 s22, s34, s22
	s_addc_u32 s23, s35, s23
	s_and_b64 s[34:35], s[24:25], exec
	s_cselect_b32 s17, s23, s29
	s_cselect_b32 s45, s22, s28
	s_add_u32 s46, s28, 0x100
	s_addc_u32 s47, s29, 0
	s_add_u32 s28, s30, 0x80080
	v_mov_b32_e32 v2, 0
	s_addc_u32 s29, s31, 0
	s_mov_b32 s48, -2
	v_mov_b32_e32 v3, v2
	v_mov_b32_e32 v4, v2
	v_mov_b32_e32 v5, v2
	v_mov_b32_e32 v6, v2
	v_mov_b32_e32 v7, v2
	v_mov_b32_e32 v8, v2
	v_mov_b32_e32 v9, v2
	v_mov_b32_e32 v18, v2
	v_mov_b32_e32 v19, v2
	v_mov_b32_e32 v20, v2
	v_mov_b32_e32 v21, v2
	v_mov_b32_e32 v22, v2
	v_mov_b32_e32 v23, v2
	v_mov_b32_e32 v24, v2
	v_mov_b32_e32 v25, v2
	v_mov_b32_e32 v34, v2
	v_mov_b32_e32 v35, v2
	v_mov_b32_e32 v36, v2
	v_mov_b32_e32 v37, v2
	v_mov_b32_e32 v38, v2
	v_mov_b32_e32 v39, v2
	v_mov_b32_e32 v40, v2
	v_mov_b32_e32 v41, v2
	v_mov_b32_e32 v50, v2
	v_mov_b32_e32 v51, v2
	v_mov_b32_e32 v52, v2
	v_mov_b32_e32 v53, v2
	v_mov_b32_e32 v54, v2
	v_mov_b32_e32 v55, v2
	v_mov_b32_e32 v56, v2
	v_mov_b32_e32 v57, v2
	v_mov_b32_e32 v10, v2
	v_mov_b32_e32 v11, v2
	v_mov_b32_e32 v12, v2
	v_mov_b32_e32 v13, v2
	v_mov_b32_e32 v14, v2
	v_mov_b32_e32 v15, v2
	v_mov_b32_e32 v16, v2
	v_mov_b32_e32 v17, v2
	v_mov_b32_e32 v26, v2
	v_mov_b32_e32 v27, v2
	v_mov_b32_e32 v28, v2
	v_mov_b32_e32 v29, v2
	v_mov_b32_e32 v30, v2
	v_mov_b32_e32 v31, v2
	v_mov_b32_e32 v32, v2
	v_mov_b32_e32 v33, v2
	v_mov_b32_e32 v42, v2
	v_mov_b32_e32 v43, v2
	v_mov_b32_e32 v44, v2
	v_mov_b32_e32 v45, v2
	v_mov_b32_e32 v46, v2
	v_mov_b32_e32 v47, v2
	v_mov_b32_e32 v48, v2
	v_mov_b32_e32 v49, v2
	v_mov_b32_e32 v58, v2
	v_mov_b32_e32 v59, v2
	v_mov_b32_e32 v60, v2
	v_mov_b32_e32 v61, v2
	v_mov_b32_e32 v62, v2
	v_mov_b32_e32 v63, v2
	v_mov_b32_e32 v64, v2
	v_mov_b32_e32 v65, v2
	v_mov_b32_e32 v66, v2
	v_mov_b32_e32 v67, v2
	v_mov_b32_e32 v68, v2
	v_mov_b32_e32 v69, v2
	v_mov_b32_e32 v70, v2
	v_mov_b32_e32 v71, v2
	v_mov_b32_e32 v72, v2
	v_mov_b32_e32 v73, v2
	v_mov_b32_e32 v82, v2
	v_mov_b32_e32 v83, v2
	v_mov_b32_e32 v84, v2
	v_mov_b32_e32 v85, v2
	v_mov_b32_e32 v86, v2
	v_mov_b32_e32 v87, v2
	v_mov_b32_e32 v88, v2
	v_mov_b32_e32 v89, v2
	v_mov_b32_e32 v98, v2
	v_mov_b32_e32 v99, v2
	v_mov_b32_e32 v100, v2
	v_mov_b32_e32 v101, v2
	v_mov_b32_e32 v102, v2
	v_mov_b32_e32 v103, v2
	v_mov_b32_e32 v104, v2
	v_mov_b32_e32 v105, v2
	v_mov_b32_e32 v114, v2
	v_mov_b32_e32 v115, v2
	v_mov_b32_e32 v116, v2
	v_mov_b32_e32 v117, v2
	v_mov_b32_e32 v118, v2
	v_mov_b32_e32 v119, v2
	v_mov_b32_e32 v120, v2
	v_mov_b32_e32 v121, v2
	v_mov_b32_e32 v74, v2
	v_mov_b32_e32 v75, v2
	v_mov_b32_e32 v76, v2
	v_mov_b32_e32 v77, v2
	v_mov_b32_e32 v78, v2
	v_mov_b32_e32 v79, v2
	v_mov_b32_e32 v80, v2
	v_mov_b32_e32 v81, v2
	v_mov_b32_e32 v90, v2
	v_mov_b32_e32 v91, v2
	v_mov_b32_e32 v92, v2
	v_mov_b32_e32 v93, v2
	v_mov_b32_e32 v94, v2
	v_mov_b32_e32 v95, v2
	v_mov_b32_e32 v96, v2
	v_mov_b32_e32 v97, v2
	v_mov_b32_e32 v106, v2
	v_mov_b32_e32 v107, v2
	v_mov_b32_e32 v108, v2
	v_mov_b32_e32 v109, v2
	v_mov_b32_e32 v110, v2
	v_mov_b32_e32 v111, v2
	v_mov_b32_e32 v112, v2
	v_mov_b32_e32 v113, v2
	v_mov_b32_e32 v122, v2
	v_mov_b32_e32 v123, v2
	v_mov_b32_e32 v124, v2
	v_mov_b32_e32 v125, v2
	v_mov_b32_e32 v126, v2
	v_mov_b32_e32 v127, v2
	v_mov_b32_e32 v128, v2
	v_mov_b32_e32 v129, v2
	s_add_u32 s30, s28, 0xfff80080
	s_addc_u32 s31, s29, -1
	s_add_i32 s49, 0, 0x10000
	s_cmp_eq_u32 s48, 28
	s_cselect_b32 s35, s19, s31
	s_cselect_b32 s34, s44, s30
	s_cselect_b32 s31, s17, s47
	s_cselect_b32 s30, s45, s46
	s_add_i32 s52, 0, 0x14000
.LBB0_261:
	v_add_u32_e32 v142, s49, v149
	ds_read_b128 v[156:159], v142
	ds_read_b128 v[160:163], v142 offset:1024
	ds_read_b128 v[164:167], v142 offset:2048
	ds_read_b128 v[178:181], v142 offset:3072
	v_add_u32_e32 v142, s52, v149
	ds_read_b128 v[182:185], v142
	ds_read_b128 v[186:189], v142 offset:1024
	ds_read_b128 v[190:193], v142 offset:2048
	ds_read_b128 v[194:197], v142 offset:3072
	v_lshl_add_u64 v[142:143], s[28:29], 0, v[140:141]
	s_add_i32 m0, s2, 0xc000
	ds_read_b128 v[198:201], v154
	global_load_lds_dwordx4 v[142:143], off
	ds_read_b128 v[212:215], v154 offset:1024
	ds_read_b128 v[216:219], v154 offset:2048
	v_lshl_add_u64 v[142:143], s[28:29], 0, v[138:139]
	s_add_i32 m0, s2, 0xe000
	s_nop 0
	global_load_lds_dwordx4 v[142:143], off
	ds_read_b128 v[220:223], v154 offset:3072
	ds_read_b128 v[224:227], v154 offset:4096
	ds_read_b128 v[228:231], v154 offset:5120
	ds_read_b128 v[232:235], v154 offset:6144
	ds_read_b128 v[236:239], v154 offset:7168
	s_waitcnt vmcnt(8)
	s_waitcnt lgkmcnt(0)
	s_barrier
; #define PG8_STAGE(bufoff, gbase, voff) do { _Pragma("unroll") for (int _i = 0; _i < 2; ++_i) \
;         __builtin_amdgcn_global_load_lds((const unsigned*)((const char*)(gbase) + (voff)[_i]), (LAS unsigned*)(lds + (bufoff) + ldsw + _i * 8192), 16, 0, 0); } while (0)
; #define PG8_LDA(dst, b, h) do { _Pragma("unroll") for (int m = 0; m < 4; ++m) _Pragma("unroll") for (int k = 0; k < 2; ++k) dst[m][k] = *(const LAS bf16x8*)(lds + PG8_SA(b, h) + aoff + m * 2048 + k * 1024); } while (0)
; #define PG8_LDB(dst, b, h) do { _Pragma("unroll") for (int n = 0; n < 2; ++n) _Pragma("unroll") for (int k = 0; k < 2; ++k) dst[n][k] = *(const LAS bf16x8*)(lds + PG8_SB(b, h) + boff + n * 2048 + k * 1024); } while (0)
; #define PG8_MMA(ai, bj, At, Bt) do { __builtin_amdgcn_s_setprio(1); _Pragma("unroll") for (int m = 0; m < 4; ++m) _Pragma("unroll") for (int n = 0; n < 2; ++n) _Pragma("unroll") for (int k = 0; k < 2; ++k) \
;         acc[ai][bj][m][n] = __builtin_amdgcn_mfma_f32_16x16x32_bf16(Bt[n][k], At[m][k], acc[ai][bj][m][n], 0, 0, 0); __builtin_amdgcn_s_setprio(0); } while (0)
; #define PG8_WAIT_V(n) asm volatile("s_waitcnt vmcnt(" #n ")" ::: "memory")
; #define PG8_WAIT_L(n) asm volatile("s_waitcnt lgkmcnt(" #n ")" ::: "memory")
; #define PG8_BAR __builtin_amdgcn_s_barrier()
; #define PG8_SCHED __builtin_amdgcn_sched_barrier(0)
; template <class Epi>
; __device__ __forceinline__ void gemm_phase(LAS unsigned char* lds, const Gemm g, const StaticOrder& S, const Epi& E, const int tid) {
;     ...
;             PG8_WAIT_V(8); PG8_WAIT_L(0); PG8_BAR; PG8_MMA(0, 0, At, B0); PG8_MMA(0, 1, At, B1); PG8_BAR; PG8_SCHED;
;             PG8_LDA(At, 0, 1); PG8_STAGE(PG8_SB(0, 0), b2, voffB); PG8_STAGE(PG8_SB(0, 1), b2 + bhs, voffB); PG8_STAGE(PG8_SA(0, 0), a2, voffA);
;             PG8_WAIT_V(8); PG8_WAIT_L(0); PG8_BAR; PG8_MMA(1, 0, At, B0); PG8_MMA(1, 1, At, B1); PG8_BAR; PG8_SCHED;
;             PG8_LDB(B0, 1, 0); PG8_LDB(B1, 1, 1); PG8_SCHED; PG8_LDA(At, 1, 0); PG8_STAGE(PG8_SA(0, 1), a2 + hstep, voffA);
	s_setprio 1
	s_waitcnt lgkmcnt(0)
	v_mfma_f32_16x16x32_bf16 v[126:129], v[156:159], v[198:201], v[126:129]
	v_mfma_f32_16x16x32_bf16 v[122:125], v[164:167], v[198:201], v[122:125]
	v_mfma_f32_16x16x32_bf16 v[110:113], v[156:159], v[216:219], v[110:113]
	v_mfma_f32_16x16x32_bf16 v[106:109], v[164:167], v[216:219], v[106:109]
	v_mfma_f32_16x16x32_bf16 v[94:97], v[156:159], v[224:227], v[94:97]
	v_mfma_f32_16x16x32_bf16 v[90:93], v[164:167], v[224:227], v[90:93]
	v_mfma_f32_16x16x32_bf16 v[78:81], v[156:159], v[232:235], v[78:81]
	v_mfma_f32_16x16x32_bf16 v[74:77], v[164:167], v[232:235], v[74:77]
	v_mfma_f32_16x16x32_bf16 v[126:129], v[160:163], v[212:215], v[126:129]
	v_mfma_f32_16x16x32_bf16 v[122:125], v[178:181], v[212:215], v[122:125]
	v_mfma_f32_16x16x32_bf16 v[110:113], v[160:163], v[220:223], v[110:113]
	v_mfma_f32_16x16x32_bf16 v[106:109], v[178:181], v[220:223], v[106:109]
	v_mfma_f32_16x16x32_bf16 v[94:97], v[160:163], v[228:231], v[94:97]
	v_mfma_f32_16x16x32_bf16 v[90:93], v[178:181], v[228:231], v[90:93]
	v_mfma_f32_16x16x32_bf16 v[78:81], v[160:163], v[236:239], v[78:81]
	v_mfma_f32_16x16x32_bf16 v[74:77], v[178:181], v[236:239], v[74:77]
	s_setprio 0
	s_setprio 1
	v_mfma_f32_16x16x32_bf16 v[118:121], v[182:185], v[198:201], v[118:121]
	v_mfma_f32_16x16x32_bf16 v[114:117], v[190:193], v[198:201], v[114:117]
	v_mfma_f32_16x16x32_bf16 v[102:105], v[182:185], v[216:219], v[102:105]
	v_mfma_f32_16x16x32_bf16 v[98:101], v[190:193], v[216:219], v[98:101]
	v_mfma_f32_16x16x32_bf16 v[86:89], v[182:185], v[224:227], v[86:89]
	v_mfma_f32_16x16x32_bf16 v[82:85], v[190:193], v[224:227], v[82:85]
	v_mfma_f32_16x16x32_bf16 v[70:73], v[182:185], v[232:235], v[70:73]
	v_mfma_f32_16x16x32_bf16 v[66:69], v[190:193], v[232:235], v[66:69]
	v_mfma_f32_16x16x32_bf16 v[118:121], v[186:189], v[212:215], v[118:121]
	v_mfma_f32_16x16x32_bf16 v[114:117], v[194:197], v[212:215], v[114:117]
	v_mfma_f32_16x16x32_bf16 v[102:105], v[186:189], v[220:223], v[102:105]
	v_mfma_f32_16x16x32_bf16 v[98:101], v[194:197], v[220:223], v[98:101]
	v_mfma_f32_16x16x32_bf16 v[86:89], v[186:189], v[228:231], v[86:89]
	v_mfma_f32_16x16x32_bf16 v[82:85], v[194:197], v[228:231], v[82:85]
	v_mfma_f32_16x16x32_bf16 v[70:73], v[186:189], v[236:239], v[70:73]
	v_mfma_f32_16x16x32_bf16 v[66:69], v[194:197], v[236:239], v[66:69]
	s_setprio 0
	s_barrier
	s_add_i32 s49, s49, s36
	v_lshl_add_u64 v[142:143], s[30:31], 0, v[0:1]
	s_mov_b32 m0, s49
	ds_read_b128 v[198:201], v154 offset:16384
	global_load_lds_dwordx4 v[142:143], off
	ds_read_b128 v[212:215], v154 offset:17408
	ds_read_b128 v[216:219], v154 offset:18432
	s_add_i32 m0, s49, 0x2000
	s_add_u32 s50, s30, 0x8000
	v_lshl_add_u64 v[168:169], s[30:31], 0, v[134:135]
	s_addc_u32 s51, s31, 0
	s_add_i32 s49, s52, s36
	global_load_lds_dwordx4 v[168:169], off
	ds_read_b128 v[220:223], v154 offset:19456
	ds_read_b128 v[224:227], v154 offset:20480
	v_lshl_add_u64 v[172:173], s[50:51], 0, v[0:1]
	s_mov_b32 m0, s49
	v_lshl_add_u64 v[174:175], s[34:35], 0, v[132:133]
	global_load_lds_dwordx4 v[172:173], off
	ds_read_b128 v[228:231], v154 offset:21504
	ds_read_b128 v[232:235], v154 offset:22528
	v_lshl_add_u64 v[172:173], s[50:51], 0, v[134:135]
	s_add_i32 m0, s49, 0x2000
	s_nop 0
	global_load_lds_dwordx4 v[172:173], off
	ds_read_b128 v[236:239], v154 offset:23552
	v_lshl_add_u64 v[172:173], s[34:35], 0, v[130:131]
	s_mov_b32 m0, s2
	s_nop 0
	global_load_lds_dwordx4 v[172:173], off
	s_mov_b32 m0, s27
	s_nop 0
	global_load_lds_dwordx4 v[174:175], off
	s_waitcnt vmcnt(8)
	s_waitcnt lgkmcnt(0)
	s_barrier
	s_setprio 1
	s_waitcnt lgkmcnt(0)
	v_mfma_f32_16x16x32_bf16 v[62:65], v[156:159], v[198:201], v[62:65]
	v_mfma_f32_16x16x32_bf16 v[58:61], v[164:167], v[198:201], v[58:61]
	v_mfma_f32_16x16x32_bf16 v[46:49], v[156:159], v[216:219], v[46:49]
	v_mfma_f32_16x16x32_bf16 v[42:45], v[164:167], v[216:219], v[42:45]
	v_mfma_f32_16x16x32_bf16 v[30:33], v[156:159], v[224:227], v[30:33]
	v_mfma_f32_16x16x32_bf16 v[26:29], v[164:167], v[224:227], v[26:29]
	v_mfma_f32_16x16x32_bf16 v[14:17], v[156:159], v[232:235], v[14:17]
	v_mfma_f32_16x16x32_bf16 v[10:13], v[164:167], v[232:235], v[10:13]
	v_mfma_f32_16x16x32_bf16 v[62:65], v[160:163], v[212:215], v[62:65]
	v_mfma_f32_16x16x32_bf16 v[58:61], v[178:181], v[212:215], v[58:61]
	v_mfma_f32_16x16x32_bf16 v[46:49], v[160:163], v[220:223], v[46:49]
	v_mfma_f32_16x16x32_bf16 v[42:45], v[178:181], v[220:223], v[42:45]
	v_mfma_f32_16x16x32_bf16 v[30:33], v[160:163], v[228:231], v[30:33]
	v_mfma_f32_16x16x32_bf16 v[26:29], v[178:181], v[228:231], v[26:29]
	v_mfma_f32_16x16x32_bf16 v[14:17], v[160:163], v[236:239], v[14:17]
	v_mfma_f32_16x16x32_bf16 v[10:13], v[178:181], v[236:239], v[10:13]
	s_setprio 0
	s_setprio 1
	v_mfma_f32_16x16x32_bf16 v[54:57], v[182:185], v[198:201], v[54:57]
	v_mfma_f32_16x16x32_bf16 v[50:53], v[190:193], v[198:201], v[50:53]
	v_mfma_f32_16x16x32_bf16 v[38:41], v[182:185], v[216:219], v[38:41]
	v_mfma_f32_16x16x32_bf16 v[34:37], v[190:193], v[216:219], v[34:37]
	v_mfma_f32_16x16x32_bf16 v[22:25], v[182:185], v[224:227], v[22:25]
	v_mfma_f32_16x16x32_bf16 v[18:21], v[190:193], v[224:227], v[18:21]
	v_mfma_f32_16x16x32_bf16 v[6:9], v[182:185], v[232:235], v[6:9]
	v_mfma_f32_16x16x32_bf16 v[2:5], v[190:193], v[232:235], v[2:5]
	v_mfma_f32_16x16x32_bf16 v[54:57], v[186:189], v[212:215], v[54:57]
	v_mfma_f32_16x16x32_bf16 v[50:53], v[194:197], v[212:215], v[50:53]
	v_mfma_f32_16x16x32_bf16 v[38:41], v[186:189], v[220:223], v[38:41]
	v_mfma_f32_16x16x32_bf16 v[34:37], v[194:197], v[220:223], v[34:37]
	v_mfma_f32_16x16x32_bf16 v[22:25], v[186:189], v[228:231], v[22:25]
	v_mfma_f32_16x16x32_bf16 v[18:21], v[194:197], v[228:231], v[18:21]
	v_mfma_f32_16x16x32_bf16 v[6:9], v[186:189], v[236:239], v[6:9]
	v_mfma_f32_16x16x32_bf16 v[2:5], v[194:197], v[236:239], v[2:5]
	s_setprio 0
	s_barrier
; #define PG8_STAGE(bufoff, gbase, voff) do { _Pragma("unroll") for (int _i = 0; _i < 2; ++_i) \
;         __builtin_amdgcn_global_load_lds((const unsigned*)((const char*)(gbase) + (voff)[_i]), (LAS unsigned*)(lds + (bufoff) + ldsw + _i * 8192), 16, 0, 0); } while (0)
; #define PG8_LDA(dst, b, h) do { _Pragma("unroll") for (int m = 0; m < 4; ++m) _Pragma("unroll") for (int k = 0; k < 2; ++k) dst[m][k] = *(const LAS bf16x8*)(lds + PG8_SA(b, h) + aoff + m * 2048 + k * 1024); } while (0)
; #define PG8_LDB(dst, b, h) do { _Pragma("unroll") for (int n = 0; n < 2; ++n) _Pragma("unroll") for (int k = 0; k < 2; ++k) dst[n][k] = *(const LAS bf16x8*)(lds + PG8_SB(b, h) + boff + n * 2048 + k * 1024); } while (0)
; #define PG8_MMA(ai, bj, At, Bt) do { __builtin_amdgcn_s_setprio(1); _Pragma("unroll") for (int m = 0; m < 4; ++m) _Pragma("unroll") for (int n = 0; n < 2; ++n) _Pragma("unroll") for (int k = 0; k < 2; ++k) \
;         acc[ai][bj][m][n] = __builtin_amdgcn_mfma_f32_16x16x32_bf16(Bt[n][k], At[m][k], acc[ai][bj][m][n], 0, 0, 0); __builtin_amdgcn_s_setprio(0); } while (0)
; #define PG8_WAIT_V(n) asm volatile("s_waitcnt vmcnt(" #n ")" ::: "memory")
; #define PG8_WAIT_L(n) asm volatile("s_waitcnt lgkmcnt(" #n ")" ::: "memory")
; #define PG8_BAR __builtin_amdgcn_s_barrier()
; #define PG8_SCHED __builtin_amdgcn_sched_barrier(0)
; template <class Epi>
; __device__ __forceinline__ void gemm_phase(LAS unsigned char* lds, const Gemm g, const StaticOrder& S, const Epi& E, const int tid) {
;     ...
;             PG8_LDB(B0, 1, 0); PG8_LDB(B1, 1, 1); PG8_SCHED; PG8_LDA(At, 1, 0); PG8_STAGE(PG8_SA(0, 1), a2 + hstep, voffA);
;             PG8_WAIT_V(8); PG8_WAIT_L(0); PG8_BAR; PG8_MMA(0, 0, At, B0); PG8_MMA(0, 1, At, B1); PG8_BAR; PG8_SCHED;
	s_add_i32 s49, 0, 0x18000
	v_add_u32_e32 v155, s49, v149
	s_add_i32 s50, 0, 0x1c000
	ds_read_b128 v[156:159], v155
	ds_read_b128 v[160:163], v155 offset:1024
	ds_read_b128 v[164:167], v155 offset:2048
	ds_read_b128 v[178:181], v155 offset:3072
	v_add_u32_e32 v155, s50, v149
	ds_read_b128 v[182:185], v155
	ds_read_b128 v[186:189], v155 offset:1024
	ds_read_b128 v[190:193], v155 offset:2048
	ds_read_b128 v[194:197], v155 offset:3072
	s_add_u32 s34, s34, 0x80000
	s_addc_u32 s35, s35, 0
	s_mov_b32 m0, s37
	v_lshl_add_u64 v[176:177], s[34:35], 0, v[130:131]
	ds_read_b128 v[198:201], v154 offset:32768
	global_load_lds_dwordx4 v[176:177], off
	ds_read_b128 v[212:215], v154 offset:33792
	ds_read_b128 v[216:219], v154 offset:34816
	v_lshl_add_u64 v[176:177], s[34:35], 0, v[132:133]
	s_mov_b32 m0, s38
	s_nop 0
	global_load_lds_dwordx4 v[176:177], off
	ds_read_b128 v[220:223], v154 offset:35840
	ds_read_b128 v[224:227], v154 offset:36864
	ds_read_b128 v[228:231], v154 offset:37888
	ds_read_b128 v[232:235], v154 offset:38912
	ds_read_b128 v[236:239], v154 offset:39936
	s_waitcnt vmcnt(8)
	s_waitcnt lgkmcnt(0)
	s_barrier
	s_setprio 1
	s_waitcnt lgkmcnt(0)
	v_mfma_f32_16x16x32_bf16 v[126:129], v[156:159], v[198:201], v[126:129]
	v_mfma_f32_16x16x32_bf16 v[122:125], v[164:167], v[198:201], v[122:125]
	v_mfma_f32_16x16x32_bf16 v[110:113], v[156:159], v[216:219], v[110:113]
	v_mfma_f32_16x16x32_bf16 v[106:109], v[164:167], v[216:219], v[106:109]
	v_mfma_f32_16x16x32_bf16 v[94:97], v[156:159], v[224:227], v[94:97]
	v_mfma_f32_16x16x32_bf16 v[90:93], v[164:167], v[224:227], v[90:93]
	v_mfma_f32_16x16x32_bf16 v[78:81], v[156:159], v[232:235], v[78:81]
	v_mfma_f32_16x16x32_bf16 v[74:77], v[164:167], v[232:235], v[74:77]
	v_mfma_f32_16x16x32_bf16 v[126:129], v[160:163], v[212:215], v[126:129]
	v_mfma_f32_16x16x32_bf16 v[122:125], v[178:181], v[212:215], v[122:125]
	v_mfma_f32_16x16x32_bf16 v[110:113], v[160:163], v[220:223], v[110:113]
	v_mfma_f32_16x16x32_bf16 v[106:109], v[178:181], v[220:223], v[106:109]
	v_mfma_f32_16x16x32_bf16 v[94:97], v[160:163], v[228:231], v[94:97]
	v_mfma_f32_16x16x32_bf16 v[90:93], v[178:181], v[228:231], v[90:93]
	v_mfma_f32_16x16x32_bf16 v[78:81], v[160:163], v[236:239], v[78:81]
	v_mfma_f32_16x16x32_bf16 v[74:77], v[178:181], v[236:239], v[74:77]
	s_setprio 0
	s_setprio 1
	v_mfma_f32_16x16x32_bf16 v[118:121], v[182:185], v[198:201], v[118:121]
	v_mfma_f32_16x16x32_bf16 v[114:117], v[190:193], v[198:201], v[114:117]
	v_mfma_f32_16x16x32_bf16 v[102:105], v[182:185], v[216:219], v[102:105]
	v_mfma_f32_16x16x32_bf16 v[98:101], v[190:193], v[216:219], v[98:101]
	v_mfma_f32_16x16x32_bf16 v[86:89], v[182:185], v[224:227], v[86:89]
	v_mfma_f32_16x16x32_bf16 v[82:85], v[190:193], v[224:227], v[82:85]
	v_mfma_f32_16x16x32_bf16 v[70:73], v[182:185], v[232:235], v[70:73]
	v_mfma_f32_16x16x32_bf16 v[66:69], v[190:193], v[232:235], v[66:69]
	v_mfma_f32_16x16x32_bf16 v[118:121], v[186:189], v[212:215], v[118:121]
	v_mfma_f32_16x16x32_bf16 v[114:117], v[194:197], v[212:215], v[114:117]
	v_mfma_f32_16x16x32_bf16 v[102:105], v[186:189], v[220:223], v[102:105]
	v_mfma_f32_16x16x32_bf16 v[98:101], v[194:197], v[220:223], v[98:101]
	v_mfma_f32_16x16x32_bf16 v[86:89], v[186:189], v[228:231], v[86:89]
	v_mfma_f32_16x16x32_bf16 v[82:85], v[194:197], v[228:231], v[82:85]
	v_mfma_f32_16x16x32_bf16 v[70:73], v[186:189], v[236:239], v[70:73]
	v_mfma_f32_16x16x32_bf16 v[66:69], v[194:197], v[236:239], v[66:69]
	s_setprio 0
	s_barrier
; #define PG8_STAGE(bufoff, gbase, voff) do { _Pragma("unroll") for (int _i = 0; _i < 2; ++_i) \
;         __builtin_amdgcn_global_load_lds((const unsigned*)((const char*)(gbase) + (voff)[_i]), (LAS unsigned*)(lds + (bufoff) + ldsw + _i * 8192), 16, 0, 0); } while (0)
; #define PG8_LDA(dst, b, h) do { _Pragma("unroll") for (int m = 0; m < 4; ++m) _Pragma("unroll") for (int k = 0; k < 2; ++k) dst[m][k] = *(const LAS bf16x8*)(lds + PG8_SA(b, h) + aoff + m * 2048 + k * 1024); } while (0)
; #define PG8_MMA(ai, bj, At, Bt) do { __builtin_amdgcn_s_setprio(1); _Pragma("unroll") for (int m = 0; m < 4; ++m) _Pragma("unroll") for (int n = 0; n < 2; ++n) _Pragma("unroll") for (int k = 0; k < 2; ++k) \
;         acc[ai][bj][m][n] = __builtin_amdgcn_mfma_f32_16x16x32_bf16(Bt[n][k], At[m][k], acc[ai][bj][m][n], 0, 0, 0); __builtin_amdgcn_s_setprio(0); } while (0)
; #define PG8_WAIT_V(n) asm volatile("s_waitcnt vmcnt(" #n ")" ::: "memory")
; #define PG8_WAIT_L(n) asm volatile("s_waitcnt lgkmcnt(" #n ")" ::: "memory")
; #define PG8_BAR __builtin_amdgcn_s_barrier()
; #define PG8_SCHED __builtin_amdgcn_sched_barrier(0)
; template <class Epi>
; __device__ __forceinline__ void gemm_phase(LAS unsigned char* lds, const Gemm g, const StaticOrder& S, const Epi& E, const int tid) {
;     ...
;         for (int t = 0; t < ntt; t += 2) {
;             const bool last = (t == ntt - 2);
;             const bool s1 = Epi::TWO && (t >= nt), s2 = Epi::TWO && (t + 2 >= nt);
;             const char* a1 = (s1 ? cA2 + (size_t)(t - nt + 1) * kstep : cA + (size_t)(t + 1) * kstep);
;             const char* a2 = last ? nA : (s2 ? cA2 + (size_t)(t + 2 - nt) * kstep : cA + (size_t)(t + 2) * kstep);
;             const char* b2 = last ? nB : (s2 ? cB2 + (size_t)(t + 2 - nt) * kstep : cB + (size_t)(t + 2) * kstep);
;             const char* a3 = a2 + kstep; const char* b3 = b2 + kstep;
;     ...
;             PG8_LDA(At, 1, 1); PG8_STAGE(PG8_SB(1, 0), b3, voffB); PG8_STAGE(PG8_SB(1, 1), b3 + bhs, voffB); PG8_STAGE(PG8_SA(1, 0), a3, voffA);
;             PG8_WAIT_V(8); PG8_WAIT_L(0); PG8_BAR; PG8_MMA(1, 0, At, B0); PG8_MMA(1, 1, At, B1); PG8_BAR; PG8_SCHED;
	s_add_i32 s34, s49, s36
	v_lshl_add_u64 v[142:143], v[142:143], 0, s[70:71]
	s_mov_b32 m0, s34
	ds_read_b128 v[198:201], v154 offset:49152
	global_load_lds_dwordx4 v[142:143], off
	ds_read_b128 v[212:215], v154 offset:50176
	ds_read_b128 v[216:219], v154 offset:51200
	s_add_i32 m0, s34, 0x2000
	s_add_u32 s30, s30, 0x8080
	v_lshl_add_u64 v[142:143], v[168:169], 0, s[70:71]
	s_addc_u32 s31, s31, 0
	s_add_i32 s34, s50, s36
	global_load_lds_dwordx4 v[142:143], off
	ds_read_b128 v[220:223], v154 offset:52224
	ds_read_b128 v[224:227], v154 offset:53248
	v_lshl_add_u64 v[142:143], s[30:31], 0, v[0:1]
	s_mov_b32 m0, s34
	s_nop 0
	global_load_lds_dwordx4 v[142:143], off
	ds_read_b128 v[228:231], v154 offset:54272
	ds_read_b128 v[232:235], v154 offset:55296
	v_lshl_add_u64 v[142:143], s[30:31], 0, v[134:135]
	s_add_i32 m0, s34, 0x2000
	s_nop 0
	global_load_lds_dwordx4 v[142:143], off
	ds_read_b128 v[236:239], v154 offset:56320
	v_lshl_add_u64 v[142:143], v[172:173], 0, s[70:71]
	s_mov_b32 m0, s39
	s_nop 0
	global_load_lds_dwordx4 v[142:143], off
	v_lshl_add_u64 v[142:143], v[174:175], 0, s[70:71]
	s_mov_b32 m0, s40
	s_nop 0
	global_load_lds_dwordx4 v[142:143], off
	s_waitcnt vmcnt(8)
	s_waitcnt lgkmcnt(0)
	s_barrier
	s_setprio 1
	s_waitcnt lgkmcnt(0)
	v_mfma_f32_16x16x32_bf16 v[62:65], v[156:159], v[198:201], v[62:65]
	v_mfma_f32_16x16x32_bf16 v[58:61], v[164:167], v[198:201], v[58:61]
	v_mfma_f32_16x16x32_bf16 v[46:49], v[156:159], v[216:219], v[46:49]
	v_mfma_f32_16x16x32_bf16 v[42:45], v[164:167], v[216:219], v[42:45]
	v_mfma_f32_16x16x32_bf16 v[30:33], v[156:159], v[224:227], v[30:33]
	v_mfma_f32_16x16x32_bf16 v[26:29], v[164:167], v[224:227], v[26:29]
	v_mfma_f32_16x16x32_bf16 v[14:17], v[156:159], v[232:235], v[14:17]
	v_mfma_f32_16x16x32_bf16 v[10:13], v[164:167], v[232:235], v[10:13]
	v_mfma_f32_16x16x32_bf16 v[62:65], v[160:163], v[212:215], v[62:65]
	v_mfma_f32_16x16x32_bf16 v[58:61], v[178:181], v[212:215], v[58:61]
	v_mfma_f32_16x16x32_bf16 v[46:49], v[160:163], v[220:223], v[46:49]
	v_mfma_f32_16x16x32_bf16 v[42:45], v[178:181], v[220:223], v[42:45]
	v_mfma_f32_16x16x32_bf16 v[30:33], v[160:163], v[228:231], v[30:33]
	v_mfma_f32_16x16x32_bf16 v[26:29], v[178:181], v[228:231], v[26:29]
	v_mfma_f32_16x16x32_bf16 v[14:17], v[160:163], v[236:239], v[14:17]
	v_mfma_f32_16x16x32_bf16 v[10:13], v[178:181], v[236:239], v[10:13]
	s_setprio 0
	s_setprio 1
	v_mfma_f32_16x16x32_bf16 v[54:57], v[182:185], v[198:201], v[54:57]
	s_add_i32 s48, s48, 2
	v_mfma_f32_16x16x32_bf16 v[50:53], v[190:193], v[198:201], v[50:53]
	s_add_u32 s46, s46, 0x100
	v_mfma_f32_16x16x32_bf16 v[38:41], v[182:185], v[216:219], v[38:41]
	s_addc_u32 s47, s47, 0
	v_mfma_f32_16x16x32_bf16 v[34:37], v[190:193], v[216:219], v[34:37]
	s_add_u32 s28, s28, 0x100
	v_mfma_f32_16x16x32_bf16 v[22:25], v[182:185], v[224:227], v[22:25]
	s_addc_u32 s29, s29, 0
	v_mfma_f32_16x16x32_bf16 v[18:21], v[190:193], v[224:227], v[18:21]
	s_add_u32 s30, s28, 0xfff80080
	v_mfma_f32_16x16x32_bf16 v[6:9], v[182:185], v[232:235], v[6:9]
	s_addc_u32 s31, s29, -1
	v_mfma_f32_16x16x32_bf16 v[2:5], v[190:193], v[232:235], v[2:5]
	s_add_i32 s49, 0, 0x10000
	v_mfma_f32_16x16x32_bf16 v[54:57], v[186:189], v[212:215], v[54:57]
	s_cmp_eq_u32 s48, 28
	v_mfma_f32_16x16x32_bf16 v[50:53], v[194:197], v[212:215], v[50:53]
	s_cselect_b32 s35, s19, s31
	v_mfma_f32_16x16x32_bf16 v[38:41], v[186:189], v[220:223], v[38:41]
	s_cselect_b32 s34, s44, s30
	v_mfma_f32_16x16x32_bf16 v[34:37], v[194:197], v[220:223], v[34:37]
	s_cselect_b32 s31, s17, s47
	v_mfma_f32_16x16x32_bf16 v[22:25], v[186:189], v[228:231], v[22:25]
	s_cselect_b32 s30, s45, s46
	v_mfma_f32_16x16x32_bf16 v[18:21], v[194:197], v[228:231], v[18:21]
	s_add_i32 s52, 0, 0x14000
	v_mfma_f32_16x16x32_bf16 v[6:9], v[186:189], v[236:239], v[6:9]
	s_cmp_gt_u32 s48, 29
	v_mfma_f32_16x16x32_bf16 v[2:5], v[194:197], v[236:239], v[2:5]
	s_setprio 0
	s_barrier
	s_cbranch_scc0 .LBB0_261
	s_and_b64 vcc, exec, s[14:15]
	s_cbranch_vccz .LBB0_264
	s_barrier

; #define PG8_STAGE(bufoff, gbase, voff) do { _Pragma("unroll") for (int _i = 0; _i < 2; ++_i) \
;         __builtin_amdgcn_global_load_lds((const unsigned*)((const char*)(gbase) + (voff)[_i]), (LAS unsigned*)(lds + (bufoff) + ldsw + _i * 8192), 16, 0, 0); } while (0)
; #define PG8_LDA(dst, b, h) do { _Pragma("unroll") for (int m = 0; m < 4; ++m) _Pragma("unroll") for (int k = 0; k < 2; ++k) dst[m][k] = *(const LAS bf16x8*)(lds + PG8_SA(b, h) + aoff + m * 2048 + k * 1024); } while (0)
; #define PG8_LDB(dst, b, h) do { _Pragma("unroll") for (int n = 0; n < 2; ++n) _Pragma("unroll") for (int k = 0; k < 2; ++k) dst[n][k] = *(const LAS bf16x8*)(lds + PG8_SB(b, h) + boff + n * 2048 + k * 1024); } while (0)
; #define PG8_BAR __builtin_amdgcn_s_barrier()
; template <class Epi>
; __device__ __forceinline__ void gemm_phase(LAS unsigned char* lds, const Gemm g, const StaticOrder& S, const Epi& E, const int tid) {
;     ...
;         const bool has_next = S.next(ui + 1, nxt);
;         const char* nA = has_next ? (const char*)g.A + (size_t)nxt.pm * tstep : cA; const char* nB = has_next ? (const char*)g.Bt + (size_t)nxt.pn * tstep : cB;
;         for (int t = 0; t < ntt; t += 2) {
;             const bool last = (t == ntt - 2);
;             const bool s1 = Epi::TWO && (t >= nt), s2 = Epi::TWO && (t + 2 >= nt);
;             const char* a1 = (s1 ? cA2 + (size_t)(t - nt + 1) * kstep : cA + (size_t)(t + 1) * kstep);
;             const char* a2 = last ? nA : (s2 ? cA2 + (size_t)(t + 2 - nt) * kstep : cA + (size_t)(t + 2) * kstep);
;             const char* b2 = last ? nB : (s2 ? cB2 + (size_t)(t + 2 - nt) * kstep : cB + (size_t)(t + 2) * kstep);
;             const char* a3 = a2 + kstep; const char* b3 = b2 + kstep;
;             if constexpr (Epi::TWO) { if (t == nt) E.mid(acc, cur, wr, wc, fr, fq); }
;             if constexpr (SP2) {
;             PG8_LDB(B0, 0, 0); PG8_LDB(B1, 0, 1); PG8_SCHED; PG8_LDA(At, 0, 0); PG8_STAGE(PG8_SA(1, 1), a1 + hstep, voffA);
;             PG8_WAIT_V(8); PG8_WAIT_L(0); PG8_BAR; PG8_MMA(0, 0, At, B0); PG8_MMA(0, 1, At, B1); PG8_BAR; PG8_SCHED;
;     ...
; #pragma unroll
;         for (int a = 0; a < 2; ++a)
; #pragma unroll
;             for (int b = 0; b < 2; ++b)
; #pragma unroll
;                 for (int m = 0; m < 4; ++m)
; #pragma unroll
;                     for (int n = 0; n < 2; ++n) acc[a][b][m][n] = (f32x4){0.f, 0.f, 0.f, 0.f};
.LBB0_313:
	s_ashr_i32 s27, s26, 31
	s_lshl_b64 s[6:7], s[26:27], 20
	v_readlane_b32 s28, v251, 43
	v_readlane_b32 s29, v251, 44
	s_add_u32 s28, s28, s6
	s_addc_u32 s29, s29, s7
	s_and_b64 s[6:7], s[34:35], exec
	s_cselect_b32 s27, s29, s43
	s_cselect_b32 s39, s28, s42
	s_ashr_i32 s25, s24, 31
	s_lshl_b64 s[6:7], s[24:25], 20
	s_add_u32 s30, s52, s6
	s_addc_u32 s31, s53, s7
	s_and_b64 s[6:7], s[34:35], exec
	s_cselect_b32 s25, s31, s41
	s_cselect_b32 s52, s30, s40
	s_add_u32 s53, s40, 0x100
	s_addc_u32 s54, s41, 0
	s_add_u32 s6, s42, 0x80080
	v_mov_b32_e32 v2, 0
	s_addc_u32 s7, s43, 0
	s_mov_b32 s55, -2
	v_mov_b32_e32 v3, v2
	s_waitcnt lgkmcnt(0)
	v_mov_b32_e32 v4, v2
	v_mov_b32_e32 v5, v2
	v_mov_b32_e32 v6, v2
	v_mov_b32_e32 v7, v2
	v_mov_b32_e32 v8, v2
	v_mov_b32_e32 v9, v2
	v_mov_b32_e32 v18, v2
	v_mov_b32_e32 v19, v2
	v_mov_b32_e32 v20, v2
	v_mov_b32_e32 v21, v2
	v_mov_b32_e32 v22, v2
	v_mov_b32_e32 v23, v2
	v_mov_b32_e32 v24, v2
	v_mov_b32_e32 v25, v2
	v_mov_b32_e32 v50, v2
	v_mov_b32_e32 v51, v2
	v_mov_b32_e32 v52, v2
	v_mov_b32_e32 v53, v2
	v_mov_b32_e32 v54, v2
	v_mov_b32_e32 v55, v2
	v_mov_b32_e32 v56, v2
	v_mov_b32_e32 v57, v2
	v_mov_b32_e32 v82, v2
	v_mov_b32_e32 v83, v2
	v_mov_b32_e32 v84, v2
	v_mov_b32_e32 v85, v2
	v_mov_b32_e32 v86, v2
	v_mov_b32_e32 v87, v2
	v_mov_b32_e32 v88, v2
	v_mov_b32_e32 v89, v2
	v_mov_b32_e32 v10, v2
	v_mov_b32_e32 v11, v2
	v_mov_b32_e32 v12, v2
	v_mov_b32_e32 v13, v2
	v_mov_b32_e32 v14, v2
	v_mov_b32_e32 v15, v2
	v_mov_b32_e32 v16, v2
	v_mov_b32_e32 v17, v2
	v_mov_b32_e32 v26, v2
	v_mov_b32_e32 v27, v2
	v_mov_b32_e32 v28, v2
	v_mov_b32_e32 v29, v2
	v_mov_b32_e32 v30, v2
	v_mov_b32_e32 v31, v2
	v_mov_b32_e32 v32, v2
	v_mov_b32_e32 v33, v2
	v_mov_b32_e32 v74, v2
	v_mov_b32_e32 v75, v2
	v_mov_b32_e32 v76, v2
	v_mov_b32_e32 v77, v2
	v_mov_b32_e32 v78, v2
	v_mov_b32_e32 v79, v2
	v_mov_b32_e32 v80, v2
	v_mov_b32_e32 v81, v2
	v_mov_b32_e32 v90, v2
	v_mov_b32_e32 v91, v2
	v_mov_b32_e32 v92, v2
	v_mov_b32_e32 v93, v2
	v_mov_b32_e32 v94, v2
	v_mov_b32_e32 v95, v2
	v_mov_b32_e32 v96, v2
	v_mov_b32_e32 v97, v2
	v_mov_b32_e32 v98, v2
	v_mov_b32_e32 v99, v2
	v_mov_b32_e32 v100, v2
	v_mov_b32_e32 v101, v2
	v_mov_b32_e32 v102, v2
	v_mov_b32_e32 v103, v2
	v_mov_b32_e32 v104, v2
	v_mov_b32_e32 v105, v2
	v_mov_b32_e32 v114, v2
	v_mov_b32_e32 v115, v2
	v_mov_b32_e32 v116, v2
	v_mov_b32_e32 v117, v2
	v_mov_b32_e32 v118, v2
	v_mov_b32_e32 v119, v2
	v_mov_b32_e32 v120, v2
	v_mov_b32_e32 v121, v2
	v_mov_b32_e32 v130, v2
	v_mov_b32_e32 v131, v2
	v_mov_b32_e32 v132, v2
	v_mov_b32_e32 v133, v2
	v_mov_b32_e32 v134, v2
	v_mov_b32_e32 v135, v2
	v_mov_b32_e32 v136, v2
	v_mov_b32_e32 v137, v2
	v_mov_b32_e32 v146, v2
	v_mov_b32_e32 v147, v2
	v_mov_b32_e32 v148, v2
	v_mov_b32_e32 v149, v2
	v_mov_b32_e32 v150, v2
	v_mov_b32_e32 v151, v2
	v_mov_b32_e32 v152, v2
	v_mov_b32_e32 v153, v2
	v_mov_b32_e32 v106, v2
	v_mov_b32_e32 v107, v2
	v_mov_b32_e32 v108, v2
	v_mov_b32_e32 v109, v2
	v_mov_b32_e32 v110, v2
	v_mov_b32_e32 v111, v2
	v_mov_b32_e32 v112, v2
	v_mov_b32_e32 v113, v2
	v_mov_b32_e32 v122, v2
	v_mov_b32_e32 v123, v2
	v_mov_b32_e32 v124, v2
	v_mov_b32_e32 v125, v2
	v_mov_b32_e32 v126, v2
	v_mov_b32_e32 v127, v2
	v_mov_b32_e32 v128, v2
	v_mov_b32_e32 v129, v2
	v_mov_b32_e32 v138, v2
	v_mov_b32_e32 v139, v2
	v_mov_b32_e32 v140, v2
	v_mov_b32_e32 v141, v2
	v_mov_b32_e32 v142, v2
	v_mov_b32_e32 v143, v2
	v_mov_b32_e32 v144, v2
	v_mov_b32_e32 v145, v2
	v_mov_b32_e32 v154, v2
	v_mov_b32_e32 v155, v2
	v_mov_b32_e32 v156, v2
	v_mov_b32_e32 v157, v2
	v_mov_b32_e32 v158, v2
	v_mov_b32_e32 v159, v2
	v_mov_b32_e32 v160, v2
	v_mov_b32_e32 v161, v2
	s_add_u32 s40, s6, 0xfff80080
	s_addc_u32 s41, s7, -1
	s_add_i32 s56, 0, 0x10000
	s_cmp_eq_u32 s55, 28
	s_cselect_b32 s43, s27, s41
	s_cselect_b32 s42, s39, s40
	s_cselect_b32 s41, s25, s54
	s_cselect_b32 s40, s52, s53
	s_add_i32 s58, 0, 0x14000
.LBB0_314:
	v_add_u32_e32 v46, s56, v212
	v_add_u32_e32 v70, s58, v212
	ds_read_b128 v[34:37], v46
	ds_read_b128 v[38:41], v46 offset:1024
	ds_read_b128 v[42:45], v46 offset:2048
	ds_read_b128 v[46:49], v46 offset:3072
	ds_read_b128 v[58:61], v70
	ds_read_b128 v[62:65], v70 offset:1024
	ds_read_b128 v[66:69], v70 offset:2048
	ds_read_b128 v[70:73], v70 offset:3072
	v_lshl_add_u64 v[172:173], s[6:7], 0, v[188:189]
	s_add_i32 m0, s44, 0xc000
	ds_read_b128 v[162:165], v220
	global_load_lds_dwordx4 v[172:173], off
	ds_read_b128 v[166:169], v220 offset:1024
	ds_read_b128 v[190:193], v220 offset:2048
	v_lshl_add_u64 v[172:173], s[6:7], 0, v[186:187]
	s_add_i32 m0, s44, 0xe000
	s_nop 0
	global_load_lds_dwordx4 v[172:173], off
	ds_read_b128 v[194:197], v220 offset:3072
	ds_read_b128 v[198:201], v220 offset:4096
	ds_read_b128 v[222:225], v220 offset:5120
	ds_read_b128 v[226:229], v220 offset:6144
	ds_read_b128 v[230:233], v220 offset:7168
	s_waitcnt vmcnt(8)
	s_waitcnt lgkmcnt(0)
	s_barrier
; #define PG8_STAGE(bufoff, gbase, voff) do { _Pragma("unroll") for (int _i = 0; _i < 2; ++_i) \
;         __builtin_amdgcn_global_load_lds((const unsigned*)((const char*)(gbase) + (voff)[_i]), (LAS unsigned*)(lds + (bufoff) + ldsw + _i * 8192), 16, 0, 0); } while (0)
; #define PG8_LDA(dst, b, h) do { _Pragma("unroll") for (int m = 0; m < 4; ++m) _Pragma("unroll") for (int k = 0; k < 2; ++k) dst[m][k] = *(const LAS bf16x8*)(lds + PG8_SA(b, h) + aoff + m * 2048 + k * 1024); } while (0)
; #define PG8_LDB(dst, b, h) do { _Pragma("unroll") for (int n = 0; n < 2; ++n) _Pragma("unroll") for (int k = 0; k < 2; ++k) dst[n][k] = *(const LAS bf16x8*)(lds + PG8_SB(b, h) + boff + n * 2048 + k * 1024); } while (0)
; #define PG8_MMA(ai, bj, At, Bt) do { __builtin_amdgcn_s_setprio(1); _Pragma("unroll") for (int m = 0; m < 4; ++m) _Pragma("unroll") for (int n = 0; n < 2; ++n) _Pragma("unroll") for (int k = 0; k < 2; ++k) \
;         acc[ai][bj][m][n] = __builtin_amdgcn_mfma_f32_16x16x32_bf16(Bt[n][k], At[m][k], acc[ai][bj][m][n], 0, 0, 0); __builtin_amdgcn_s_setprio(0); } while (0)
; #define PG8_WAIT_V(n) asm volatile("s_waitcnt vmcnt(" #n ")" ::: "memory")
; #define PG8_WAIT_L(n) asm volatile("s_waitcnt lgkmcnt(" #n ")" ::: "memory")
; #define PG8_BAR __builtin_amdgcn_s_barrier()
; #define PG8_SCHED __builtin_amdgcn_sched_barrier(0)
; template <class Epi>
; __device__ __forceinline__ void gemm_phase(LAS unsigned char* lds, const Gemm g, const StaticOrder& S, const Epi& E, const int tid) {
;     ...
;             PG8_WAIT_V(8); PG8_WAIT_L(0); PG8_BAR; PG8_MMA(0, 0, At, B0); PG8_MMA(0, 1, At, B1); PG8_BAR; PG8_SCHED;
;             PG8_LDA(At, 0, 1); PG8_STAGE(PG8_SB(0, 0), b2, voffB); PG8_STAGE(PG8_SB(0, 1), b2 + bhs, voffB); PG8_STAGE(PG8_SA(0, 0), a2, voffA);
;             PG8_WAIT_V(8); PG8_WAIT_L(0); PG8_BAR; PG8_MMA(1, 0, At, B0); PG8_MMA(1, 1, At, B1); PG8_BAR; PG8_SCHED;
;             PG8_LDB(B0, 1, 0); PG8_LDB(B1, 1, 1); PG8_SCHED; PG8_LDA(At, 1, 0); PG8_STAGE(PG8_SA(0, 1), a2 + hstep, voffA);
	s_setprio 1
	s_waitcnt lgkmcnt(0)
	v_mfma_f32_16x16x32_bf16 v[158:161], v[34:37], v[162:165], v[158:161]
	v_mfma_f32_16x16x32_bf16 v[154:157], v[42:45], v[162:165], v[154:157]
	v_mfma_f32_16x16x32_bf16 v[142:145], v[34:37], v[190:193], v[142:145]
	v_mfma_f32_16x16x32_bf16 v[138:141], v[42:45], v[190:193], v[138:141]
	v_mfma_f32_16x16x32_bf16 v[126:129], v[34:37], v[198:201], v[126:129]
	v_mfma_f32_16x16x32_bf16 v[122:125], v[42:45], v[198:201], v[122:125]
	v_mfma_f32_16x16x32_bf16 v[110:113], v[34:37], v[226:229], v[110:113]
	v_mfma_f32_16x16x32_bf16 v[106:109], v[42:45], v[226:229], v[106:109]
	v_mfma_f32_16x16x32_bf16 v[158:161], v[38:41], v[166:169], v[158:161]
	v_mfma_f32_16x16x32_bf16 v[154:157], v[46:49], v[166:169], v[154:157]
	v_mfma_f32_16x16x32_bf16 v[142:145], v[38:41], v[194:197], v[142:145]
	v_mfma_f32_16x16x32_bf16 v[138:141], v[46:49], v[194:197], v[138:141]
	v_mfma_f32_16x16x32_bf16 v[126:129], v[38:41], v[222:225], v[126:129]
	v_mfma_f32_16x16x32_bf16 v[122:125], v[46:49], v[222:225], v[122:125]
	v_mfma_f32_16x16x32_bf16 v[110:113], v[38:41], v[230:233], v[110:113]
	v_mfma_f32_16x16x32_bf16 v[106:109], v[46:49], v[230:233], v[106:109]
	s_setprio 0
	s_setprio 1
	v_mfma_f32_16x16x32_bf16 v[150:153], v[58:61], v[162:165], v[150:153]
	v_mfma_f32_16x16x32_bf16 v[146:149], v[66:69], v[162:165], v[146:149]
	v_mfma_f32_16x16x32_bf16 v[134:137], v[58:61], v[190:193], v[134:137]
	v_mfma_f32_16x16x32_bf16 v[130:133], v[66:69], v[190:193], v[130:133]
	v_mfma_f32_16x16x32_bf16 v[118:121], v[58:61], v[198:201], v[118:121]
	v_mfma_f32_16x16x32_bf16 v[114:117], v[66:69], v[198:201], v[114:117]
	v_mfma_f32_16x16x32_bf16 v[102:105], v[58:61], v[226:229], v[102:105]
	v_mfma_f32_16x16x32_bf16 v[98:101], v[66:69], v[226:229], v[98:101]
	v_mfma_f32_16x16x32_bf16 v[150:153], v[62:65], v[166:169], v[150:153]
	v_mfma_f32_16x16x32_bf16 v[146:149], v[70:73], v[166:169], v[146:149]
	v_mfma_f32_16x16x32_bf16 v[134:137], v[62:65], v[194:197], v[134:137]
	v_mfma_f32_16x16x32_bf16 v[130:133], v[70:73], v[194:197], v[130:133]
	v_mfma_f32_16x16x32_bf16 v[118:121], v[62:65], v[222:225], v[118:121]
	v_mfma_f32_16x16x32_bf16 v[114:117], v[70:73], v[222:225], v[114:117]
	v_mfma_f32_16x16x32_bf16 v[102:105], v[62:65], v[230:233], v[102:105]
	v_mfma_f32_16x16x32_bf16 v[98:101], v[70:73], v[230:233], v[98:101]
	s_setprio 0
	s_barrier
	s_add_i32 s56, s56, s33
	v_lshl_add_u64 v[172:173], s[40:41], 0, v[0:1]
	s_mov_b32 m0, s56
	ds_read_b128 v[162:165], v220 offset:16384
	global_load_lds_dwordx4 v[172:173], off
	ds_read_b128 v[166:169], v220 offset:17408
	ds_read_b128 v[190:193], v220 offset:18432
	s_add_i32 m0, s56, 0x2000
	s_add_u32 s56, s40, 0x8000
	v_lshl_add_u64 v[174:175], s[40:41], 0, v[182:183]
	s_addc_u32 s57, s41, 0
	s_add_i32 s58, s58, s33
	global_load_lds_dwordx4 v[174:175], off
	ds_read_b128 v[194:197], v220 offset:19456
	ds_read_b128 v[198:201], v220 offset:20480
	v_lshl_add_u64 v[176:177], s[56:57], 0, v[0:1]
	s_mov_b32 m0, s58
	v_lshl_add_u64 v[238:239], s[42:43], 0, v[180:181]
	global_load_lds_dwordx4 v[176:177], off
	ds_read_b128 v[222:225], v220 offset:21504
	ds_read_b128 v[226:229], v220 offset:22528
	v_lshl_add_u64 v[176:177], s[56:57], 0, v[182:183]
	s_add_i32 m0, s58, 0x2000
	s_nop 0
	global_load_lds_dwordx4 v[176:177], off
	ds_read_b128 v[230:233], v220 offset:23552
	v_lshl_add_u64 v[176:177], s[42:43], 0, v[178:179]
	s_mov_b32 m0, s44
	s_nop 0
	global_load_lds_dwordx4 v[176:177], off
	s_mov_b32 m0, s45
	s_nop 0
	global_load_lds_dwordx4 v[238:239], off
	s_waitcnt vmcnt(8)
	s_waitcnt lgkmcnt(0)
	s_barrier
	s_setprio 1
	s_waitcnt lgkmcnt(0)
	v_mfma_f32_16x16x32_bf16 v[94:97], v[34:37], v[162:165], v[94:97]
	v_mfma_f32_16x16x32_bf16 v[90:93], v[42:45], v[162:165], v[90:93]
	v_mfma_f32_16x16x32_bf16 v[78:81], v[34:37], v[190:193], v[78:81]
	v_mfma_f32_16x16x32_bf16 v[74:77], v[42:45], v[190:193], v[74:77]
	v_mfma_f32_16x16x32_bf16 v[30:33], v[34:37], v[198:201], v[30:33]
	v_mfma_f32_16x16x32_bf16 v[26:29], v[42:45], v[198:201], v[26:29]
	v_mfma_f32_16x16x32_bf16 v[14:17], v[34:37], v[226:229], v[14:17]
	v_mfma_f32_16x16x32_bf16 v[10:13], v[42:45], v[226:229], v[10:13]
	v_mfma_f32_16x16x32_bf16 v[94:97], v[38:41], v[166:169], v[94:97]
	v_mfma_f32_16x16x32_bf16 v[90:93], v[46:49], v[166:169], v[90:93]
	v_mfma_f32_16x16x32_bf16 v[78:81], v[38:41], v[194:197], v[78:81]
	v_mfma_f32_16x16x32_bf16 v[74:77], v[46:49], v[194:197], v[74:77]
	v_mfma_f32_16x16x32_bf16 v[30:33], v[38:41], v[222:225], v[30:33]
	v_mfma_f32_16x16x32_bf16 v[26:29], v[46:49], v[222:225], v[26:29]
	v_mfma_f32_16x16x32_bf16 v[14:17], v[38:41], v[230:233], v[14:17]
	v_mfma_f32_16x16x32_bf16 v[10:13], v[46:49], v[230:233], v[10:13]
	s_setprio 0
	s_setprio 1
	v_mfma_f32_16x16x32_bf16 v[22:25], v[58:61], v[198:201], v[22:25]
	v_mfma_f32_16x16x32_bf16 v[18:21], v[66:69], v[198:201], v[18:21]
	v_mfma_f32_16x16x32_bf16 v[6:9], v[58:61], v[226:229], v[6:9]
	v_mfma_f32_16x16x32_bf16 v[2:5], v[66:69], v[226:229], v[2:5]
	v_mfma_f32_16x16x32_bf16 v[34:37], v[58:61], v[162:165], v[86:89]
	v_mfma_f32_16x16x32_bf16 v[38:41], v[66:69], v[162:165], v[82:85]
	v_mfma_f32_16x16x32_bf16 v[42:45], v[58:61], v[190:193], v[54:57]
	v_mfma_f32_16x16x32_bf16 v[46:49], v[66:69], v[190:193], v[50:53]
	v_mfma_f32_16x16x32_bf16 v[22:25], v[62:65], v[222:225], v[22:25]
	v_mfma_f32_16x16x32_bf16 v[18:21], v[70:73], v[222:225], v[18:21]
	v_mfma_f32_16x16x32_bf16 v[6:9], v[62:65], v[230:233], v[6:9]
	v_mfma_f32_16x16x32_bf16 v[2:5], v[70:73], v[230:233], v[2:5]
	v_mfma_f32_16x16x32_bf16 v[34:37], v[62:65], v[166:169], v[34:37]
	v_mfma_f32_16x16x32_bf16 v[38:41], v[70:73], v[166:169], v[38:41]
	v_mfma_f32_16x16x32_bf16 v[42:45], v[62:65], v[194:197], v[42:45]
	v_mfma_f32_16x16x32_bf16 v[46:49], v[70:73], v[194:197], v[46:49]
	s_setprio 0
	s_barrier
; #define PG8_STAGE(bufoff, gbase, voff) do { _Pragma("unroll") for (int _i = 0; _i < 2; ++_i) \
;         __builtin_amdgcn_global_load_lds((const unsigned*)((const char*)(gbase) + (voff)[_i]), (LAS unsigned*)(lds + (bufoff) + ldsw + _i * 8192), 16, 0, 0); } while (0)
; #define PG8_LDA(dst, b, h) do { _Pragma("unroll") for (int m = 0; m < 4; ++m) _Pragma("unroll") for (int k = 0; k < 2; ++k) dst[m][k] = *(const LAS bf16x8*)(lds + PG8_SA(b, h) + aoff + m * 2048 + k * 1024); } while (0)
; #define PG8_LDB(dst, b, h) do { _Pragma("unroll") for (int n = 0; n < 2; ++n) _Pragma("unroll") for (int k = 0; k < 2; ++k) dst[n][k] = *(const LAS bf16x8*)(lds + PG8_SB(b, h) + boff + n * 2048 + k * 1024); } while (0)
; #define PG8_MMA(ai, bj, At, Bt) do { __builtin_amdgcn_s_setprio(1); _Pragma("unroll") for (int m = 0; m < 4; ++m) _Pragma("unroll") for (int n = 0; n < 2; ++n) _Pragma("unroll") for (int k = 0; k < 2; ++k) \
;         acc[ai][bj][m][n] = __builtin_amdgcn_mfma_f32_16x16x32_bf16(Bt[n][k], At[m][k], acc[ai][bj][m][n], 0, 0, 0); __builtin_amdgcn_s_setprio(0); } while (0)
; #define PG8_WAIT_V(n) asm volatile("s_waitcnt vmcnt(" #n ")" ::: "memory")
; #define PG8_WAIT_L(n) asm volatile("s_waitcnt lgkmcnt(" #n ")" ::: "memory")
; #define PG8_BAR __builtin_amdgcn_s_barrier()
; #define PG8_SCHED __builtin_amdgcn_sched_barrier(0)
; template <class Epi>
; __device__ __forceinline__ void gemm_phase(LAS unsigned char* lds, const Gemm g, const StaticOrder& S, const Epi& E, const int tid) {
;     ...
;             PG8_LDB(B0, 1, 0); PG8_LDB(B1, 1, 1); PG8_SCHED; PG8_LDA(At, 1, 0); PG8_STAGE(PG8_SA(0, 1), a2 + hstep, voffA);
;             PG8_WAIT_V(8); PG8_WAIT_L(0); PG8_BAR; PG8_MMA(0, 0, At, B0); PG8_MMA(0, 1, At, B1); PG8_BAR; PG8_SCHED;
	s_add_i32 s56, 0, 0x18000
	s_add_i32 s57, 0, 0x1c000
	v_add_u32_e32 v62, s56, v212
	v_add_u32_e32 v82, s57, v212
	ds_read_b128 v[50:53], v62
	ds_read_b128 v[54:57], v62 offset:1024
	ds_read_b128 v[58:61], v62 offset:2048
	ds_read_b128 v[62:65], v62 offset:3072
	ds_read_b128 v[66:69], v82
	ds_read_b128 v[70:73], v82 offset:1024
	ds_read_b128 v[162:165], v82 offset:2048
	ds_read_b128 v[166:169], v82 offset:3072
	s_add_u32 s42, s42, 0x80000
	s_addc_u32 s43, s43, 0
	s_mov_b32 m0, s46
	v_lshl_add_u64 v[234:235], s[42:43], 0, v[178:179]
	ds_read_b128 v[82:85], v220 offset:32768
	global_load_lds_dwordx4 v[234:235], off
	ds_read_b128 v[86:89], v220 offset:33792
	ds_read_b128 v[190:193], v220 offset:34816
	v_lshl_add_u64 v[234:235], s[42:43], 0, v[180:181]
	s_mov_b32 m0, s47
	s_nop 0
	global_load_lds_dwordx4 v[234:235], off
	ds_read_b128 v[194:197], v220 offset:35840
	ds_read_b128 v[198:201], v220 offset:36864
	ds_read_b128 v[222:225], v220 offset:37888
	ds_read_b128 v[226:229], v220 offset:38912
	ds_read_b128 v[230:233], v220 offset:39936
	s_waitcnt vmcnt(8)
	s_waitcnt lgkmcnt(0)
	s_barrier
	s_setprio 1
	s_waitcnt lgkmcnt(0)
	v_mfma_f32_16x16x32_bf16 v[158:161], v[50:53], v[82:85], v[158:161]
	v_mfma_f32_16x16x32_bf16 v[154:157], v[58:61], v[82:85], v[154:157]
	v_mfma_f32_16x16x32_bf16 v[142:145], v[50:53], v[190:193], v[142:145]
	v_mfma_f32_16x16x32_bf16 v[138:141], v[58:61], v[190:193], v[138:141]
	v_mfma_f32_16x16x32_bf16 v[126:129], v[50:53], v[198:201], v[126:129]
	v_mfma_f32_16x16x32_bf16 v[122:125], v[58:61], v[198:201], v[122:125]
	v_mfma_f32_16x16x32_bf16 v[110:113], v[50:53], v[226:229], v[110:113]
	v_mfma_f32_16x16x32_bf16 v[106:109], v[58:61], v[226:229], v[106:109]
	v_mfma_f32_16x16x32_bf16 v[158:161], v[54:57], v[86:89], v[158:161]
	v_mfma_f32_16x16x32_bf16 v[154:157], v[62:65], v[86:89], v[154:157]
	v_mfma_f32_16x16x32_bf16 v[142:145], v[54:57], v[194:197], v[142:145]
	v_mfma_f32_16x16x32_bf16 v[138:141], v[62:65], v[194:197], v[138:141]
	v_mfma_f32_16x16x32_bf16 v[126:129], v[54:57], v[222:225], v[126:129]
	v_mfma_f32_16x16x32_bf16 v[122:125], v[62:65], v[222:225], v[122:125]
	v_mfma_f32_16x16x32_bf16 v[110:113], v[54:57], v[230:233], v[110:113]
	v_mfma_f32_16x16x32_bf16 v[106:109], v[62:65], v[230:233], v[106:109]
	s_setprio 0
	s_setprio 1
	v_mfma_f32_16x16x32_bf16 v[150:153], v[66:69], v[82:85], v[150:153]
	v_mfma_f32_16x16x32_bf16 v[82:85], v[162:165], v[82:85], v[146:149]
	v_mfma_f32_16x16x32_bf16 v[146:149], v[166:169], v[86:89], v[82:85]
	v_mfma_f32_16x16x32_bf16 v[82:85], v[66:69], v[190:193], v[134:137]
	v_mfma_f32_16x16x32_bf16 v[134:137], v[70:73], v[194:197], v[82:85]
	v_mfma_f32_16x16x32_bf16 v[82:85], v[162:165], v[190:193], v[130:133]
	v_mfma_f32_16x16x32_bf16 v[130:133], v[166:169], v[194:197], v[82:85]
	v_mfma_f32_16x16x32_bf16 v[82:85], v[66:69], v[198:201], v[118:121]
	v_mfma_f32_16x16x32_bf16 v[118:121], v[70:73], v[222:225], v[82:85]
	v_mfma_f32_16x16x32_bf16 v[82:85], v[162:165], v[198:201], v[114:117]
	v_mfma_f32_16x16x32_bf16 v[114:117], v[166:169], v[222:225], v[82:85]
	v_mfma_f32_16x16x32_bf16 v[82:85], v[66:69], v[226:229], v[102:105]
	v_mfma_f32_16x16x32_bf16 v[102:105], v[70:73], v[230:233], v[82:85]
	v_mfma_f32_16x16x32_bf16 v[82:85], v[162:165], v[226:229], v[98:101]
	v_mfma_f32_16x16x32_bf16 v[150:153], v[70:73], v[86:89], v[150:153]
	v_mfma_f32_16x16x32_bf16 v[98:101], v[166:169], v[230:233], v[82:85]
	s_setprio 0
	s_barrier
; #define PG8_STAGE(bufoff, gbase, voff) do { _Pragma("unroll") for (int _i = 0; _i < 2; ++_i) \
;         __builtin_amdgcn_global_load_lds((const unsigned*)((const char*)(gbase) + (voff)[_i]), (LAS unsigned*)(lds + (bufoff) + ldsw + _i * 8192), 16, 0, 0); } while (0)
; #define PG8_LDA(dst, b, h) do { _Pragma("unroll") for (int m = 0; m < 4; ++m) _Pragma("unroll") for (int k = 0; k < 2; ++k) dst[m][k] = *(const LAS bf16x8*)(lds + PG8_SA(b, h) + aoff + m * 2048 + k * 1024); } while (0)
; #define PG8_MMA(ai, bj, At, Bt) do { __builtin_amdgcn_s_setprio(1); _Pragma("unroll") for (int m = 0; m < 4; ++m) _Pragma("unroll") for (int n = 0; n < 2; ++n) _Pragma("unroll") for (int k = 0; k < 2; ++k) \
;         acc[ai][bj][m][n] = __builtin_amdgcn_mfma_f32_16x16x32_bf16(Bt[n][k], At[m][k], acc[ai][bj][m][n], 0, 0, 0); __builtin_amdgcn_s_setprio(0); } while (0)
; #define PG8_WAIT_V(n) asm volatile("s_waitcnt vmcnt(" #n ")" ::: "memory")
; #define PG8_WAIT_L(n) asm volatile("s_waitcnt lgkmcnt(" #n ")" ::: "memory")
; #define PG8_BAR __builtin_amdgcn_s_barrier()
; #define PG8_SCHED __builtin_amdgcn_sched_barrier(0)
; template <class Epi>
; __device__ __forceinline__ void gemm_phase(LAS unsigned char* lds, const Gemm g, const StaticOrder& S, const Epi& E, const int tid) {
;     ...
;         for (int t = 0; t < ntt; t += 2) {
;             const bool last = (t == ntt - 2);
;             const bool s1 = Epi::TWO && (t >= nt), s2 = Epi::TWO && (t + 2 >= nt);
;             const char* a1 = (s1 ? cA2 + (size_t)(t - nt + 1) * kstep : cA + (size_t)(t + 1) * kstep);
;             const char* a2 = last ? nA : (s2 ? cA2 + (size_t)(t + 2 - nt) * kstep : cA + (size_t)(t + 2) * kstep);
;             const char* b2 = last ? nB : (s2 ? cB2 + (size_t)(t + 2 - nt) * kstep : cB + (size_t)(t + 2) * kstep);
;             const char* a3 = a2 + kstep; const char* b3 = b2 + kstep;
;     ...
;             PG8_LDA(At, 1, 1); PG8_STAGE(PG8_SB(1, 0), b3, voffB); PG8_STAGE(PG8_SB(1, 1), b3 + bhs, voffB); PG8_STAGE(PG8_SA(1, 0), a3, voffA);
;             PG8_WAIT_V(8); PG8_WAIT_L(0); PG8_BAR; PG8_MMA(1, 0, At, B0); PG8_MMA(1, 1, At, B1); PG8_BAR; PG8_SCHED;
	s_add_i32 s42, s56, s33
	v_lshl_add_u64 v[86:87], v[172:173], 0, s[70:71]
	s_mov_b32 m0, s42
	s_nop 0
	ds_read_b128 v[82:85], v220 offset:49152
	global_load_lds_dwordx4 v[86:87], off
	ds_read_b128 v[190:193], v220 offset:50176
	ds_read_b128 v[194:197], v220 offset:51200
	s_add_i32 m0, s42, 0x2000
	s_add_u32 s40, s40, 0x8080
	v_lshl_add_u64 v[86:87], v[174:175], 0, s[70:71]
	s_addc_u32 s41, s41, 0
	s_add_i32 s42, s57, s33
	global_load_lds_dwordx4 v[86:87], off
	ds_read_b128 v[198:201], v220 offset:52224
	ds_read_b128 v[222:225], v220 offset:53248
	v_lshl_add_u64 v[86:87], s[40:41], 0, v[0:1]
	s_mov_b32 m0, s42
	s_nop 0
	global_load_lds_dwordx4 v[86:87], off
	ds_read_b128 v[226:229], v220 offset:54272
	ds_read_b128 v[230:233], v220 offset:55296
	v_lshl_add_u64 v[86:87], s[40:41], 0, v[182:183]
	s_add_i32 m0, s42, 0x2000
	s_nop 0
	global_load_lds_dwordx4 v[86:87], off
	ds_read_b128 v[234:237], v220 offset:56320
	v_lshl_add_u64 v[86:87], v[176:177], 0, s[70:71]
	s_mov_b32 m0, s48
	s_nop 0
	global_load_lds_dwordx4 v[86:87], off
	v_lshl_add_u64 v[86:87], v[238:239], 0, s[70:71]
	s_mov_b32 m0, s49
	s_nop 0
	global_load_lds_dwordx4 v[86:87], off
	s_waitcnt vmcnt(8)
	s_waitcnt lgkmcnt(0)
	s_barrier
	s_setprio 1
	s_waitcnt lgkmcnt(0)
	v_mfma_f32_16x16x32_bf16 v[86:89], v[50:53], v[82:85], v[94:97]
	v_mfma_f32_16x16x32_bf16 v[94:97], v[54:57], v[190:193], v[86:89]
	v_mfma_f32_16x16x32_bf16 v[86:89], v[58:61], v[82:85], v[90:93]
	v_mfma_f32_16x16x32_bf16 v[78:81], v[50:53], v[194:197], v[78:81]
	v_mfma_f32_16x16x32_bf16 v[74:77], v[58:61], v[194:197], v[74:77]
	v_mfma_f32_16x16x32_bf16 v[30:33], v[50:53], v[222:225], v[30:33]
	v_mfma_f32_16x16x32_bf16 v[26:29], v[58:61], v[222:225], v[26:29]
	v_mfma_f32_16x16x32_bf16 v[14:17], v[50:53], v[230:233], v[14:17]
	v_mfma_f32_16x16x32_bf16 v[10:13], v[58:61], v[230:233], v[10:13]
	v_mfma_f32_16x16x32_bf16 v[90:93], v[62:65], v[190:193], v[86:89]
	v_mfma_f32_16x16x32_bf16 v[78:81], v[54:57], v[198:201], v[78:81]
	v_mfma_f32_16x16x32_bf16 v[74:77], v[62:65], v[198:201], v[74:77]
	v_mfma_f32_16x16x32_bf16 v[30:33], v[54:57], v[226:229], v[30:33]
	v_mfma_f32_16x16x32_bf16 v[26:29], v[62:65], v[226:229], v[26:29]
	v_mfma_f32_16x16x32_bf16 v[14:17], v[54:57], v[234:237], v[14:17]
	v_mfma_f32_16x16x32_bf16 v[10:13], v[62:65], v[234:237], v[10:13]
	s_setprio 0
	s_setprio 1
	v_mfma_f32_16x16x32_bf16 v[34:37], v[66:69], v[82:85], v[34:37]
	s_add_i32 s55, s55, 2
	v_mfma_f32_16x16x32_bf16 v[86:89], v[70:73], v[190:193], v[34:37]
	s_add_u32 s53, s53, 0x100
	v_mfma_f32_16x16x32_bf16 v[34:37], v[162:165], v[82:85], v[38:41]
	s_addc_u32 s54, s54, 0
	v_mfma_f32_16x16x32_bf16 v[82:85], v[166:169], v[190:193], v[34:37]
	s_add_u32 s6, s6, 0x100
	v_mfma_f32_16x16x32_bf16 v[34:37], v[66:69], v[194:197], v[42:45]
	s_addc_u32 s7, s7, 0
	v_mfma_f32_16x16x32_bf16 v[54:57], v[70:73], v[198:201], v[34:37]
	s_add_u32 s40, s6, 0xfff80080
	v_mfma_f32_16x16x32_bf16 v[34:37], v[162:165], v[194:197], v[46:49]
	s_addc_u32 s41, s7, -1
	v_mfma_f32_16x16x32_bf16 v[22:25], v[66:69], v[222:225], v[22:25]
	s_add_i32 s56, 0, 0x10000
	v_mfma_f32_16x16x32_bf16 v[18:21], v[162:165], v[222:225], v[18:21]
	s_cmp_eq_u32 s55, 28
	v_mfma_f32_16x16x32_bf16 v[6:9], v[66:69], v[230:233], v[6:9]
	s_cselect_b32 s43, s27, s41
	v_mfma_f32_16x16x32_bf16 v[2:5], v[162:165], v[230:233], v[2:5]
	s_cselect_b32 s42, s39, s40
	v_mfma_f32_16x16x32_bf16 v[50:53], v[166:169], v[198:201], v[34:37]
	s_cselect_b32 s41, s25, s54
	v_mfma_f32_16x16x32_bf16 v[22:25], v[70:73], v[226:229], v[22:25]
	s_cselect_b32 s40, s52, s53
	v_mfma_f32_16x16x32_bf16 v[18:21], v[166:169], v[226:229], v[18:21]
	s_add_i32 s58, 0, 0x14000
	v_mfma_f32_16x16x32_bf16 v[6:9], v[70:73], v[234:237], v[6:9]
	s_cmp_gt_u32 s55, 29
	v_mfma_f32_16x16x32_bf16 v[2:5], v[166:169], v[234:237], v[2:5]
	s_setprio 0
	s_barrier
	s_cbranch_scc0 .LBB0_314
	s_and_b64 vcc, exec, s[22:23]
	s_cbranch_vccz .LBB0_317
	s_barrier

; #define PG8_STAGE(bufoff, gbase, voff) do { _Pragma("unroll") for (int _i = 0; _i < 2; ++_i) \
;         __builtin_amdgcn_global_load_lds((const unsigned*)((const char*)(gbase) + (voff)[_i]), (LAS unsigned*)(lds + (bufoff) + ldsw + _i * 8192), 16, 0, 0); } while (0)
; #define PG8_LDA(dst, b, h) do { _Pragma("unroll") for (int m = 0; m < 4; ++m) _Pragma("unroll") for (int k = 0; k < 2; ++k) dst[m][k] = *(const LAS bf16x8*)(lds + PG8_SA(b, h) + aoff + m * 2048 + k * 1024); } while (0)
; #define PG8_LDB(dst, b, h) do { _Pragma("unroll") for (int n = 0; n < 2; ++n) _Pragma("unroll") for (int k = 0; k < 2; ++k) dst[n][k] = *(const LAS bf16x8*)(lds + PG8_SB(b, h) + boff + n * 2048 + k * 1024); } while (0)
; #define PG8_BAR __builtin_amdgcn_s_barrier()
; template <class Epi>
; __device__ __forceinline__ void gemm_phase(LAS unsigned char* lds, const Gemm g, const StaticOrder& S, const Epi& E, const int tid) {
;     ...
;         const bool has_next = S.next(ui + 1, nxt);
;         const char* nA = has_next ? (const char*)g.A + (size_t)nxt.pm * tstep : cA; const char* nB = has_next ? (const char*)g.Bt + (size_t)nxt.pn * tstep : cB;
;         for (int t = 0; t < ntt; t += 2) {
;             const bool last = (t == ntt - 2);
;             const bool s1 = Epi::TWO && (t >= nt), s2 = Epi::TWO && (t + 2 >= nt);
;             const char* a1 = (s1 ? cA2 + (size_t)(t - nt + 1) * kstep : cA + (size_t)(t + 1) * kstep);
;             const char* a2 = last ? nA : (s2 ? cA2 + (size_t)(t + 2 - nt) * kstep : cA + (size_t)(t + 2) * kstep);
;             const char* b2 = last ? nB : (s2 ? cB2 + (size_t)(t + 2 - nt) * kstep : cB + (size_t)(t + 2) * kstep);
;             const char* a3 = a2 + kstep; const char* b3 = b2 + kstep;
;             if constexpr (Epi::TWO) { if (t == nt) E.mid(acc, cur, wr, wc, fr, fq); }
;             if constexpr (SP2) {
;             PG8_LDB(B0, 0, 0); PG8_LDB(B1, 0, 1); PG8_SCHED; PG8_LDA(At, 0, 0); PG8_STAGE(PG8_SA(1, 1), a1 + hstep, voffA);
;             PG8_WAIT_V(8); PG8_WAIT_L(0); PG8_BAR; PG8_MMA(0, 0, At, B0); PG8_MMA(0, 1, At, B1); PG8_BAR; PG8_SCHED;
;     ...
; #pragma unroll
;         for (int a = 0; a < 2; ++a)
; #pragma unroll
;             for (int b = 0; b < 2; ++b)
; #pragma unroll
;                 for (int m = 0; m < 4; ++m)
; #pragma unroll
;                     for (int n = 0; n < 2; ++n) acc[a][b][m][n] = (f32x4){0.f, 0.f, 0.f, 0.f};
.LBB0_545:
	s_ashr_i32 s19, s18, 31
	s_lshl_b64 s[20:21], s[18:19], 20
	v_readlane_b32 s22, v251, 31
	v_readlane_b32 s23, v251, 32
	s_add_u32 s20, s22, s20
	s_addc_u32 s21, s23, s21
	s_and_b64 s[22:23], s[24:25], exec
	s_cselect_b32 s19, s21, s29
	s_cselect_b32 s31, s20, s28
	s_ashr_i32 s17, s16, 31
	s_lshl_b64 s[22:23], s[16:17], 20
	v_readlane_b32 s34, v251, 53
	v_readlane_b32 s35, v251, 54
	s_add_u32 s22, s34, s22
	s_addc_u32 s23, s35, s23
	s_and_b64 s[34:35], s[24:25], exec
	s_cselect_b32 s17, s23, s27
	s_cselect_b32 s33, s22, s26
	s_add_u32 s37, s26, 0x100
	s_addc_u32 s38, s27, 0
	s_add_u32 s26, s28, 0x80080
	v_mov_b32_e32 v2, 0
	s_addc_u32 s27, s29, 0
	s_mov_b32 s39, -2
	v_mov_b32_e32 v3, v2
	s_waitcnt lgkmcnt(0)
	v_mov_b32_e32 v4, v2
	v_mov_b32_e32 v5, v2
	v_mov_b32_e32 v6, v2
	v_mov_b32_e32 v7, v2
	v_mov_b32_e32 v8, v2
	v_mov_b32_e32 v9, v2
	v_mov_b32_e32 v18, v2
	v_mov_b32_e32 v19, v2
	v_mov_b32_e32 v20, v2
	v_mov_b32_e32 v21, v2
	v_mov_b32_e32 v22, v2
	v_mov_b32_e32 v23, v2
	v_mov_b32_e32 v24, v2
	v_mov_b32_e32 v25, v2
	v_mov_b32_e32 v34, v2
	v_mov_b32_e32 v35, v2
	v_mov_b32_e32 v36, v2
	v_mov_b32_e32 v37, v2
	v_mov_b32_e32 v38, v2
	v_mov_b32_e32 v39, v2
	v_mov_b32_e32 v40, v2
	v_mov_b32_e32 v41, v2
	v_mov_b32_e32 v50, v2
	v_mov_b32_e32 v51, v2
	v_mov_b32_e32 v52, v2
	v_mov_b32_e32 v53, v2
	v_mov_b32_e32 v54, v2
	v_mov_b32_e32 v55, v2
	v_mov_b32_e32 v56, v2
	v_mov_b32_e32 v57, v2
	v_mov_b32_e32 v10, v2
	v_mov_b32_e32 v11, v2
	v_mov_b32_e32 v12, v2
	v_mov_b32_e32 v13, v2
	v_mov_b32_e32 v14, v2
	v_mov_b32_e32 v15, v2
	v_mov_b32_e32 v16, v2
	v_mov_b32_e32 v17, v2
	v_mov_b32_e32 v26, v2
	v_mov_b32_e32 v27, v2
	v_mov_b32_e32 v28, v2
	v_mov_b32_e32 v29, v2
	v_mov_b32_e32 v30, v2
	v_mov_b32_e32 v31, v2
	v_mov_b32_e32 v32, v2
	v_mov_b32_e32 v33, v2
	v_mov_b32_e32 v42, v2
	v_mov_b32_e32 v43, v2
	v_mov_b32_e32 v44, v2
	v_mov_b32_e32 v45, v2
	v_mov_b32_e32 v46, v2
	v_mov_b32_e32 v47, v2
	v_mov_b32_e32 v48, v2
	v_mov_b32_e32 v49, v2
	v_mov_b32_e32 v58, v2
	v_mov_b32_e32 v59, v2
	v_mov_b32_e32 v60, v2
	v_mov_b32_e32 v61, v2
	v_mov_b32_e32 v62, v2
	v_mov_b32_e32 v63, v2
	v_mov_b32_e32 v64, v2
	v_mov_b32_e32 v65, v2
	v_mov_b32_e32 v66, v2
	v_mov_b32_e32 v67, v2
	v_mov_b32_e32 v68, v2
	v_mov_b32_e32 v69, v2
	v_mov_b32_e32 v70, v2
	v_mov_b32_e32 v71, v2
	v_mov_b32_e32 v72, v2
	v_mov_b32_e32 v73, v2
	v_mov_b32_e32 v82, v2
	v_mov_b32_e32 v83, v2
	v_mov_b32_e32 v84, v2
	v_mov_b32_e32 v85, v2
	v_mov_b32_e32 v86, v2
	v_mov_b32_e32 v87, v2
	v_mov_b32_e32 v88, v2
	v_mov_b32_e32 v89, v2
	v_mov_b32_e32 v98, v2
	v_mov_b32_e32 v99, v2
	v_mov_b32_e32 v100, v2
	v_mov_b32_e32 v101, v2
	v_mov_b32_e32 v102, v2
	v_mov_b32_e32 v103, v2
	v_mov_b32_e32 v104, v2
	v_mov_b32_e32 v105, v2
	v_mov_b32_e32 v114, v2
	v_mov_b32_e32 v115, v2
	v_mov_b32_e32 v116, v2
	v_mov_b32_e32 v117, v2
	v_mov_b32_e32 v118, v2
	v_mov_b32_e32 v119, v2
	v_mov_b32_e32 v120, v2
	v_mov_b32_e32 v121, v2
	v_mov_b32_e32 v74, v2
	v_mov_b32_e32 v75, v2
	v_mov_b32_e32 v76, v2
	v_mov_b32_e32 v77, v2
	v_mov_b32_e32 v78, v2
	v_mov_b32_e32 v79, v2
	v_mov_b32_e32 v80, v2
	v_mov_b32_e32 v81, v2
	v_mov_b32_e32 v90, v2
	v_mov_b32_e32 v91, v2
	v_mov_b32_e32 v92, v2
	v_mov_b32_e32 v93, v2
	v_mov_b32_e32 v94, v2
	v_mov_b32_e32 v95, v2
	v_mov_b32_e32 v96, v2
	v_mov_b32_e32 v97, v2
	v_mov_b32_e32 v106, v2
	v_mov_b32_e32 v107, v2
	v_mov_b32_e32 v108, v2
	v_mov_b32_e32 v109, v2
	v_mov_b32_e32 v110, v2
	v_mov_b32_e32 v111, v2
	v_mov_b32_e32 v112, v2
	v_mov_b32_e32 v113, v2
	v_mov_b32_e32 v122, v2
	v_mov_b32_e32 v123, v2
	v_mov_b32_e32 v124, v2
	v_mov_b32_e32 v125, v2
	v_mov_b32_e32 v126, v2
	v_mov_b32_e32 v127, v2
	v_mov_b32_e32 v128, v2
	v_mov_b32_e32 v129, v2
	s_add_u32 s28, s26, 0xfff80080
	s_addc_u32 s29, s27, -1
	s_add_i32 s44, 0, 0x10000
	s_cmp_eq_u32 s39, 28
	s_cselect_b32 s35, s19, s29
	s_cselect_b32 s34, s31, s28
	s_cselect_b32 s29, s17, s38
	s_cselect_b32 s28, s33, s37
	s_add_i32 s46, 0, 0x14000
.LBB0_546:
	v_add_u32_e32 v0, s44, v149
	ds_read_b128 v[150:153], v0
	ds_read_b128 v[154:157], v0 offset:1024
	ds_read_b128 v[158:161], v0 offset:2048
	ds_read_b128 v[186:189], v0 offset:3072
	v_add_u32_e32 v0, s46, v149
	ds_read_b128 v[190:193], v0
	ds_read_b128 v[194:197], v0 offset:1024
	ds_read_b128 v[198:201], v0 offset:2048
	ds_read_b128 v[212:215], v0 offset:3072
	v_lshl_add_u64 v[162:163], s[26:27], 0, v[146:147]
	s_add_i32 m0, s57, 0xc000
	ds_read_b128 v[216:219], v184
	global_load_lds_dwordx4 v[162:163], off
	ds_read_b128 v[220:223], v184 offset:1024
	ds_read_b128 v[224:227], v184 offset:2048
	v_lshl_add_u64 v[162:163], s[26:27], 0, v[144:145]
	s_add_i32 m0, s57, 0xe000
	s_nop 0
	global_load_lds_dwordx4 v[162:163], off
	ds_read_b128 v[228:231], v184 offset:3072
	ds_read_b128 v[232:235], v184 offset:4096
	ds_read_b128 v[236:239], v184 offset:5120
	ds_read_b128 v[240:243], v184 offset:6144
	ds_read_b128 v[244:247], v184 offset:7168
	s_waitcnt vmcnt(8)
	s_waitcnt lgkmcnt(0)
	s_barrier
; #define PG8_STAGE(bufoff, gbase, voff) do { _Pragma("unroll") for (int _i = 0; _i < 2; ++_i) \
;         __builtin_amdgcn_global_load_lds((const unsigned*)((const char*)(gbase) + (voff)[_i]), (LAS unsigned*)(lds + (bufoff) + ldsw + _i * 8192), 16, 0, 0); } while (0)
; #define PG8_LDA(dst, b, h) do { _Pragma("unroll") for (int m = 0; m < 4; ++m) _Pragma("unroll") for (int k = 0; k < 2; ++k) dst[m][k] = *(const LAS bf16x8*)(lds + PG8_SA(b, h) + aoff + m * 2048 + k * 1024); } while (0)
; #define PG8_LDB(dst, b, h) do { _Pragma("unroll") for (int n = 0; n < 2; ++n) _Pragma("unroll") for (int k = 0; k < 2; ++k) dst[n][k] = *(const LAS bf16x8*)(lds + PG8_SB(b, h) + boff + n * 2048 + k * 1024); } while (0)
; #define PG8_MMA(ai, bj, At, Bt) do { __builtin_amdgcn_s_setprio(1); _Pragma("unroll") for (int m = 0; m < 4; ++m) _Pragma("unroll") for (int n = 0; n < 2; ++n) _Pragma("unroll") for (int k = 0; k < 2; ++k) \
;         acc[ai][bj][m][n] = __builtin_amdgcn_mfma_f32_16x16x32_bf16(Bt[n][k], At[m][k], acc[ai][bj][m][n], 0, 0, 0); __builtin_amdgcn_s_setprio(0); } while (0)
; #define PG8_WAIT_V(n) asm volatile("s_waitcnt vmcnt(" #n ")" ::: "memory")
; #define PG8_WAIT_L(n) asm volatile("s_waitcnt lgkmcnt(" #n ")" ::: "memory")
; #define PG8_BAR __builtin_amdgcn_s_barrier()
; #define PG8_SCHED __builtin_amdgcn_sched_barrier(0)
; template <class Epi>
; __device__ __forceinline__ void gemm_phase(LAS unsigned char* lds, const Gemm g, const StaticOrder& S, const Epi& E, const int tid) {
;     ...
;             PG8_WAIT_V(8); PG8_WAIT_L(0); PG8_BAR; PG8_MMA(0, 0, At, B0); PG8_MMA(0, 1, At, B1); PG8_BAR; PG8_SCHED;
;             PG8_LDA(At, 0, 1); PG8_STAGE(PG8_SB(0, 0), b2, voffB); PG8_STAGE(PG8_SB(0, 1), b2 + bhs, voffB); PG8_STAGE(PG8_SA(0, 0), a2, voffA);
;             PG8_WAIT_V(8); PG8_WAIT_L(0); PG8_BAR; PG8_MMA(1, 0, At, B0); PG8_MMA(1, 1, At, B1); PG8_BAR; PG8_SCHED;
;             PG8_LDB(B0, 1, 0); PG8_LDB(B1, 1, 1); PG8_SCHED; PG8_LDA(At, 1, 0); PG8_STAGE(PG8_SA(0, 1), a2 + hstep, voffA);
	s_setprio 1
	s_waitcnt lgkmcnt(0)
	v_mfma_f32_16x16x32_bf16 v[126:129], v[150:153], v[216:219], v[126:129]
	v_mfma_f32_16x16x32_bf16 v[122:125], v[158:161], v[216:219], v[122:125]
	v_mfma_f32_16x16x32_bf16 v[110:113], v[150:153], v[224:227], v[110:113]
	v_mfma_f32_16x16x32_bf16 v[106:109], v[158:161], v[224:227], v[106:109]
	v_mfma_f32_16x16x32_bf16 v[94:97], v[150:153], v[232:235], v[94:97]
	v_mfma_f32_16x16x32_bf16 v[90:93], v[158:161], v[232:235], v[90:93]
	v_mfma_f32_16x16x32_bf16 v[78:81], v[150:153], v[240:243], v[78:81]
	v_mfma_f32_16x16x32_bf16 v[74:77], v[158:161], v[240:243], v[74:77]
	v_mfma_f32_16x16x32_bf16 v[126:129], v[154:157], v[220:223], v[126:129]
	v_mfma_f32_16x16x32_bf16 v[122:125], v[186:189], v[220:223], v[122:125]
	v_mfma_f32_16x16x32_bf16 v[110:113], v[154:157], v[228:231], v[110:113]
	v_mfma_f32_16x16x32_bf16 v[106:109], v[186:189], v[228:231], v[106:109]
	v_mfma_f32_16x16x32_bf16 v[94:97], v[154:157], v[236:239], v[94:97]
	v_mfma_f32_16x16x32_bf16 v[90:93], v[186:189], v[236:239], v[90:93]
	v_mfma_f32_16x16x32_bf16 v[78:81], v[154:157], v[244:247], v[78:81]
	v_mfma_f32_16x16x32_bf16 v[74:77], v[186:189], v[244:247], v[74:77]
	s_setprio 0
	s_setprio 1
	v_mfma_f32_16x16x32_bf16 v[118:121], v[190:193], v[216:219], v[118:121]
	v_mfma_f32_16x16x32_bf16 v[114:117], v[198:201], v[216:219], v[114:117]
	v_mfma_f32_16x16x32_bf16 v[102:105], v[190:193], v[224:227], v[102:105]
	v_mfma_f32_16x16x32_bf16 v[98:101], v[198:201], v[224:227], v[98:101]
	v_mfma_f32_16x16x32_bf16 v[86:89], v[190:193], v[232:235], v[86:89]
	v_mfma_f32_16x16x32_bf16 v[82:85], v[198:201], v[232:235], v[82:85]
	v_mfma_f32_16x16x32_bf16 v[70:73], v[190:193], v[240:243], v[70:73]
	v_mfma_f32_16x16x32_bf16 v[66:69], v[198:201], v[240:243], v[66:69]
	v_mfma_f32_16x16x32_bf16 v[118:121], v[194:197], v[220:223], v[118:121]
	v_mfma_f32_16x16x32_bf16 v[114:117], v[212:215], v[220:223], v[114:117]
	v_mfma_f32_16x16x32_bf16 v[102:105], v[194:197], v[228:231], v[102:105]
	v_mfma_f32_16x16x32_bf16 v[98:101], v[212:215], v[228:231], v[98:101]
	v_mfma_f32_16x16x32_bf16 v[86:89], v[194:197], v[236:239], v[86:89]
	v_mfma_f32_16x16x32_bf16 v[82:85], v[212:215], v[236:239], v[82:85]
	v_mfma_f32_16x16x32_bf16 v[70:73], v[194:197], v[244:247], v[70:73]
	v_mfma_f32_16x16x32_bf16 v[66:69], v[212:215], v[244:247], v[66:69]
	s_setprio 0
	s_barrier
	s_add_i32 s44, s44, s56
	v_lshl_add_u64 v[162:163], s[28:29], 0, v[132:133]
	s_mov_b32 m0, s44
	ds_read_b128 v[216:219], v184 offset:16384
	global_load_lds_dwordx4 v[162:163], off
	ds_read_b128 v[220:223], v184 offset:17408
	ds_read_b128 v[224:227], v184 offset:18432
	s_add_i32 m0, s44, 0x2000
	s_add_u32 s44, s28, 0x8000
	v_lshl_add_u64 v[248:249], s[28:29], 0, v[136:137]
	s_addc_u32 s45, s29, 0
	s_add_i32 s46, s46, s56
	global_load_lds_dwordx4 v[248:249], off
	ds_read_b128 v[228:231], v184 offset:19456
	ds_read_b128 v[232:235], v184 offset:20480
	v_lshl_add_u64 v[172:173], s[44:45], 0, v[132:133]
	s_mov_b32 m0, s46
	v_lshl_add_u64 v[174:175], s[34:35], 0, v[134:135]
	global_load_lds_dwordx4 v[172:173], off
	ds_read_b128 v[236:239], v184 offset:21504
	ds_read_b128 v[240:243], v184 offset:22528
	v_lshl_add_u64 v[172:173], s[44:45], 0, v[136:137]
	s_add_i32 m0, s46, 0x2000
	s_nop 0
	global_load_lds_dwordx4 v[172:173], off
	ds_read_b128 v[244:247], v184 offset:23552
	v_lshl_add_u64 v[172:173], s[34:35], 0, v[130:131]
	s_mov_b32 m0, s57
	s_nop 0
	global_load_lds_dwordx4 v[172:173], off
	s_mov_b32 m0, s58
	s_nop 0
	global_load_lds_dwordx4 v[174:175], off
	s_waitcnt vmcnt(8)
	s_waitcnt lgkmcnt(0)
	s_barrier
	s_setprio 1
	s_waitcnt lgkmcnt(0)
	v_mfma_f32_16x16x32_bf16 v[62:65], v[150:153], v[216:219], v[62:65]
	v_mfma_f32_16x16x32_bf16 v[58:61], v[158:161], v[216:219], v[58:61]
	v_mfma_f32_16x16x32_bf16 v[46:49], v[150:153], v[224:227], v[46:49]
	v_mfma_f32_16x16x32_bf16 v[42:45], v[158:161], v[224:227], v[42:45]
	v_mfma_f32_16x16x32_bf16 v[30:33], v[150:153], v[232:235], v[30:33]
	v_mfma_f32_16x16x32_bf16 v[26:29], v[158:161], v[232:235], v[26:29]
	v_mfma_f32_16x16x32_bf16 v[14:17], v[150:153], v[240:243], v[14:17]
	v_mfma_f32_16x16x32_bf16 v[10:13], v[158:161], v[240:243], v[10:13]
	v_mfma_f32_16x16x32_bf16 v[62:65], v[154:157], v[220:223], v[62:65]
	v_mfma_f32_16x16x32_bf16 v[58:61], v[186:189], v[220:223], v[58:61]
	v_mfma_f32_16x16x32_bf16 v[46:49], v[154:157], v[228:231], v[46:49]
	v_mfma_f32_16x16x32_bf16 v[42:45], v[186:189], v[228:231], v[42:45]
	v_mfma_f32_16x16x32_bf16 v[30:33], v[154:157], v[236:239], v[30:33]
	v_mfma_f32_16x16x32_bf16 v[26:29], v[186:189], v[236:239], v[26:29]
	v_mfma_f32_16x16x32_bf16 v[14:17], v[154:157], v[244:247], v[14:17]
	v_mfma_f32_16x16x32_bf16 v[10:13], v[186:189], v[244:247], v[10:13]
	s_setprio 0
	s_setprio 1
	v_mfma_f32_16x16x32_bf16 v[54:57], v[190:193], v[216:219], v[54:57]
	v_mfma_f32_16x16x32_bf16 v[50:53], v[198:201], v[216:219], v[50:53]
	v_mfma_f32_16x16x32_bf16 v[38:41], v[190:193], v[224:227], v[38:41]
	v_mfma_f32_16x16x32_bf16 v[34:37], v[198:201], v[224:227], v[34:37]
	v_mfma_f32_16x16x32_bf16 v[22:25], v[190:193], v[232:235], v[22:25]
	v_mfma_f32_16x16x32_bf16 v[18:21], v[198:201], v[232:235], v[18:21]
	v_mfma_f32_16x16x32_bf16 v[6:9], v[190:193], v[240:243], v[6:9]
	v_mfma_f32_16x16x32_bf16 v[2:5], v[198:201], v[240:243], v[2:5]
	v_mfma_f32_16x16x32_bf16 v[54:57], v[194:197], v[220:223], v[54:57]
	v_mfma_f32_16x16x32_bf16 v[50:53], v[212:215], v[220:223], v[50:53]
	v_mfma_f32_16x16x32_bf16 v[38:41], v[194:197], v[228:231], v[38:41]
	v_mfma_f32_16x16x32_bf16 v[34:37], v[212:215], v[228:231], v[34:37]
	v_mfma_f32_16x16x32_bf16 v[22:25], v[194:197], v[236:239], v[22:25]
	v_mfma_f32_16x16x32_bf16 v[18:21], v[212:215], v[236:239], v[18:21]
	v_mfma_f32_16x16x32_bf16 v[6:9], v[194:197], v[244:247], v[6:9]
	v_mfma_f32_16x16x32_bf16 v[2:5], v[212:215], v[244:247], v[2:5]
	s_setprio 0
	s_barrier
; #define PG8_STAGE(bufoff, gbase, voff) do { _Pragma("unroll") for (int _i = 0; _i < 2; ++_i) \
;         __builtin_amdgcn_global_load_lds((const unsigned*)((const char*)(gbase) + (voff)[_i]), (LAS unsigned*)(lds + (bufoff) + ldsw + _i * 8192), 16, 0, 0); } while (0)
; #define PG8_LDA(dst, b, h) do { _Pragma("unroll") for (int m = 0; m < 4; ++m) _Pragma("unroll") for (int k = 0; k < 2; ++k) dst[m][k] = *(const LAS bf16x8*)(lds + PG8_SA(b, h) + aoff + m * 2048 + k * 1024); } while (0)
; #define PG8_LDB(dst, b, h) do { _Pragma("unroll") for (int n = 0; n < 2; ++n) _Pragma("unroll") for (int k = 0; k < 2; ++k) dst[n][k] = *(const LAS bf16x8*)(lds + PG8_SB(b, h) + boff + n * 2048 + k * 1024); } while (0)
; #define PG8_MMA(ai, bj, At, Bt) do { __builtin_amdgcn_s_setprio(1); _Pragma("unroll") for (int m = 0; m < 4; ++m) _Pragma("unroll") for (int n = 0; n < 2; ++n) _Pragma("unroll") for (int k = 0; k < 2; ++k) \
;         acc[ai][bj][m][n] = __builtin_amdgcn_mfma_f32_16x16x32_bf16(Bt[n][k], At[m][k], acc[ai][bj][m][n], 0, 0, 0); __builtin_amdgcn_s_setprio(0); } while (0)
; #define PG8_WAIT_V(n) asm volatile("s_waitcnt vmcnt(" #n ")" ::: "memory")
; #define PG8_WAIT_L(n) asm volatile("s_waitcnt lgkmcnt(" #n ")" ::: "memory")
; #define PG8_BAR __builtin_amdgcn_s_barrier()
; #define PG8_SCHED __builtin_amdgcn_sched_barrier(0)
; template <class Epi>
; __device__ __forceinline__ void gemm_phase(LAS unsigned char* lds, const Gemm g, const StaticOrder& S, const Epi& E, const int tid) {
;     ...
;             PG8_LDB(B0, 1, 0); PG8_LDB(B1, 1, 1); PG8_SCHED; PG8_LDA(At, 1, 0); PG8_STAGE(PG8_SA(0, 1), a2 + hstep, voffA);
;             PG8_WAIT_V(8); PG8_WAIT_L(0); PG8_BAR; PG8_MMA(0, 0, At, B0); PG8_MMA(0, 1, At, B1); PG8_BAR; PG8_SCHED;
	s_add_i32 s44, 0, 0x18000
	v_add_u32_e32 v0, s44, v149
	s_add_i32 s45, 0, 0x1c000
	ds_read_b128 v[150:153], v0
	ds_read_b128 v[154:157], v0 offset:1024
	ds_read_b128 v[158:161], v0 offset:2048
	ds_read_b128 v[186:189], v0 offset:3072
	v_add_u32_e32 v0, s45, v149
	ds_read_b128 v[190:193], v0
	ds_read_b128 v[194:197], v0 offset:1024
	ds_read_b128 v[198:201], v0 offset:2048
	ds_read_b128 v[212:215], v0 offset:3072
	s_add_u32 s34, s34, 0x80000
	s_addc_u32 s35, s35, 0
	s_mov_b32 m0, s59
	v_lshl_add_u64 v[176:177], s[34:35], 0, v[130:131]
	ds_read_b128 v[216:219], v184 offset:32768
	global_load_lds_dwordx4 v[176:177], off
	ds_read_b128 v[220:223], v184 offset:33792
	ds_read_b128 v[224:227], v184 offset:34816
	v_lshl_add_u64 v[176:177], s[34:35], 0, v[134:135]
	s_mov_b32 m0, s60
	s_nop 0
	global_load_lds_dwordx4 v[176:177], off
	ds_read_b128 v[228:231], v184 offset:35840
	ds_read_b128 v[232:235], v184 offset:36864
	ds_read_b128 v[236:239], v184 offset:37888
	ds_read_b128 v[240:243], v184 offset:38912
	ds_read_b128 v[244:247], v184 offset:39936
	s_waitcnt vmcnt(8)
	s_waitcnt lgkmcnt(0)
	s_barrier
	s_setprio 1
	s_waitcnt lgkmcnt(0)
	v_mfma_f32_16x16x32_bf16 v[126:129], v[150:153], v[216:219], v[126:129]
	v_mfma_f32_16x16x32_bf16 v[122:125], v[158:161], v[216:219], v[122:125]
	v_mfma_f32_16x16x32_bf16 v[110:113], v[150:153], v[224:227], v[110:113]
	v_mfma_f32_16x16x32_bf16 v[106:109], v[158:161], v[224:227], v[106:109]
	v_mfma_f32_16x16x32_bf16 v[94:97], v[150:153], v[232:235], v[94:97]
	v_mfma_f32_16x16x32_bf16 v[90:93], v[158:161], v[232:235], v[90:93]
	v_mfma_f32_16x16x32_bf16 v[78:81], v[150:153], v[240:243], v[78:81]
	v_mfma_f32_16x16x32_bf16 v[74:77], v[158:161], v[240:243], v[74:77]
	v_mfma_f32_16x16x32_bf16 v[126:129], v[154:157], v[220:223], v[126:129]
	v_mfma_f32_16x16x32_bf16 v[122:125], v[186:189], v[220:223], v[122:125]
	v_mfma_f32_16x16x32_bf16 v[110:113], v[154:157], v[228:231], v[110:113]
	v_mfma_f32_16x16x32_bf16 v[106:109], v[186:189], v[228:231], v[106:109]
	v_mfma_f32_16x16x32_bf16 v[94:97], v[154:157], v[236:239], v[94:97]
	v_mfma_f32_16x16x32_bf16 v[90:93], v[186:189], v[236:239], v[90:93]
	v_mfma_f32_16x16x32_bf16 v[78:81], v[154:157], v[244:247], v[78:81]
	v_mfma_f32_16x16x32_bf16 v[74:77], v[186:189], v[244:247], v[74:77]
	s_setprio 0
	s_setprio 1
	v_mfma_f32_16x16x32_bf16 v[118:121], v[190:193], v[216:219], v[118:121]
	v_mfma_f32_16x16x32_bf16 v[114:117], v[198:201], v[216:219], v[114:117]
	v_mfma_f32_16x16x32_bf16 v[102:105], v[190:193], v[224:227], v[102:105]
	v_mfma_f32_16x16x32_bf16 v[98:101], v[198:201], v[224:227], v[98:101]
	v_mfma_f32_16x16x32_bf16 v[86:89], v[190:193], v[232:235], v[86:89]
	v_mfma_f32_16x16x32_bf16 v[82:85], v[198:201], v[232:235], v[82:85]
	v_mfma_f32_16x16x32_bf16 v[70:73], v[190:193], v[240:243], v[70:73]
	v_mfma_f32_16x16x32_bf16 v[66:69], v[198:201], v[240:243], v[66:69]
	v_mfma_f32_16x16x32_bf16 v[118:121], v[194:197], v[220:223], v[118:121]
	v_mfma_f32_16x16x32_bf16 v[114:117], v[212:215], v[220:223], v[114:117]
	v_mfma_f32_16x16x32_bf16 v[102:105], v[194:197], v[228:231], v[102:105]
	v_mfma_f32_16x16x32_bf16 v[98:101], v[212:215], v[228:231], v[98:101]
	v_mfma_f32_16x16x32_bf16 v[86:89], v[194:197], v[236:239], v[86:89]
	v_mfma_f32_16x16x32_bf16 v[82:85], v[212:215], v[236:239], v[82:85]
	v_mfma_f32_16x16x32_bf16 v[70:73], v[194:197], v[244:247], v[70:73]
	v_mfma_f32_16x16x32_bf16 v[66:69], v[212:215], v[244:247], v[66:69]
	s_setprio 0
	s_barrier
; #define PG8_STAGE(bufoff, gbase, voff) do { _Pragma("unroll") for (int _i = 0; _i < 2; ++_i) \
;         __builtin_amdgcn_global_load_lds((const unsigned*)((const char*)(gbase) + (voff)[_i]), (LAS unsigned*)(lds + (bufoff) + ldsw + _i * 8192), 16, 0, 0); } while (0)
; #define PG8_LDA(dst, b, h) do { _Pragma("unroll") for (int m = 0; m < 4; ++m) _Pragma("unroll") for (int k = 0; k < 2; ++k) dst[m][k] = *(const LAS bf16x8*)(lds + PG8_SA(b, h) + aoff + m * 2048 + k * 1024); } while (0)
; #define PG8_MMA(ai, bj, At, Bt) do { __builtin_amdgcn_s_setprio(1); _Pragma("unroll") for (int m = 0; m < 4; ++m) _Pragma("unroll") for (int n = 0; n < 2; ++n) _Pragma("unroll") for (int k = 0; k < 2; ++k) \
;         acc[ai][bj][m][n] = __builtin_amdgcn_mfma_f32_16x16x32_bf16(Bt[n][k], At[m][k], acc[ai][bj][m][n], 0, 0, 0); __builtin_amdgcn_s_setprio(0); } while (0)
; #define PG8_WAIT_V(n) asm volatile("s_waitcnt vmcnt(" #n ")" ::: "memory")
; #define PG8_WAIT_L(n) asm volatile("s_waitcnt lgkmcnt(" #n ")" ::: "memory")
; #define PG8_BAR __builtin_amdgcn_s_barrier()
; #define PG8_SCHED __builtin_amdgcn_sched_barrier(0)
; template <class Epi>
; __device__ __forceinline__ void gemm_phase(LAS unsigned char* lds, const Gemm g, const StaticOrder& S, const Epi& E, const int tid) {
;     ...
;         for (int t = 0; t < ntt; t += 2) {
;             const bool last = (t == ntt - 2);
;             const bool s1 = Epi::TWO && (t >= nt), s2 = Epi::TWO && (t + 2 >= nt);
;             const char* a1 = (s1 ? cA2 + (size_t)(t - nt + 1) * kstep : cA + (size_t)(t + 1) * kstep);
;             const char* a2 = last ? nA : (s2 ? cA2 + (size_t)(t + 2 - nt) * kstep : cA + (size_t)(t + 2) * kstep);
;             const char* b2 = last ? nB : (s2 ? cB2 + (size_t)(t + 2 - nt) * kstep : cB + (size_t)(t + 2) * kstep);
;             const char* a3 = a2 + kstep; const char* b3 = b2 + kstep;
;     ...
;             PG8_LDA(At, 1, 1); PG8_STAGE(PG8_SB(1, 0), b3, voffB); PG8_STAGE(PG8_SB(1, 1), b3 + bhs, voffB); PG8_STAGE(PG8_SA(1, 0), a3, voffA);
;             PG8_WAIT_V(8); PG8_WAIT_L(0); PG8_BAR; PG8_MMA(1, 0, At, B0); PG8_MMA(1, 1, At, B1); PG8_BAR; PG8_SCHED;
	s_add_i32 s34, s44, s56
	v_lshl_add_u64 v[162:163], v[162:163], 0, s[70:71]
	s_mov_b32 m0, s34
	ds_read_b128 v[216:219], v184 offset:49152
	global_load_lds_dwordx4 v[162:163], off
	ds_read_b128 v[220:223], v184 offset:50176
	ds_read_b128 v[224:227], v184 offset:51200
	s_add_i32 m0, s34, 0x2000
	s_add_u32 s28, s28, 0x8080
	v_lshl_add_u64 v[162:163], v[248:249], 0, s[70:71]
	s_addc_u32 s29, s29, 0
	s_add_i32 s34, s45, s56
	global_load_lds_dwordx4 v[162:163], off
	ds_read_b128 v[228:231], v184 offset:52224
	ds_read_b128 v[232:235], v184 offset:53248
	v_lshl_add_u64 v[162:163], s[28:29], 0, v[132:133]
	s_mov_b32 m0, s34
	s_nop 0
	global_load_lds_dwordx4 v[162:163], off
	ds_read_b128 v[236:239], v184 offset:54272
	ds_read_b128 v[240:243], v184 offset:55296
	v_lshl_add_u64 v[162:163], s[28:29], 0, v[136:137]
	s_add_i32 m0, s34, 0x2000
	s_nop 0
	global_load_lds_dwordx4 v[162:163], off
	ds_read_b128 v[244:247], v184 offset:56320
	v_lshl_add_u64 v[162:163], v[172:173], 0, s[70:71]
	s_mov_b32 m0, s61
	s_nop 0
	global_load_lds_dwordx4 v[162:163], off
	v_lshl_add_u64 v[162:163], v[174:175], 0, s[70:71]
	s_mov_b32 m0, s62
	s_nop 0
	global_load_lds_dwordx4 v[162:163], off
	s_waitcnt vmcnt(8)
	s_waitcnt lgkmcnt(0)
	s_barrier
	s_setprio 1
	s_waitcnt lgkmcnt(0)
	v_mfma_f32_16x16x32_bf16 v[62:65], v[150:153], v[216:219], v[62:65]
	v_mfma_f32_16x16x32_bf16 v[58:61], v[158:161], v[216:219], v[58:61]
	v_mfma_f32_16x16x32_bf16 v[46:49], v[150:153], v[224:227], v[46:49]
	v_mfma_f32_16x16x32_bf16 v[42:45], v[158:161], v[224:227], v[42:45]
	v_mfma_f32_16x16x32_bf16 v[30:33], v[150:153], v[232:235], v[30:33]
	v_mfma_f32_16x16x32_bf16 v[26:29], v[158:161], v[232:235], v[26:29]
	v_mfma_f32_16x16x32_bf16 v[14:17], v[150:153], v[240:243], v[14:17]
	v_mfma_f32_16x16x32_bf16 v[10:13], v[158:161], v[240:243], v[10:13]
	v_mfma_f32_16x16x32_bf16 v[62:65], v[154:157], v[220:223], v[62:65]
	v_mfma_f32_16x16x32_bf16 v[58:61], v[186:189], v[220:223], v[58:61]
	v_mfma_f32_16x16x32_bf16 v[46:49], v[154:157], v[228:231], v[46:49]
	v_mfma_f32_16x16x32_bf16 v[42:45], v[186:189], v[228:231], v[42:45]
	v_mfma_f32_16x16x32_bf16 v[30:33], v[154:157], v[236:239], v[30:33]
	v_mfma_f32_16x16x32_bf16 v[26:29], v[186:189], v[236:239], v[26:29]
	v_mfma_f32_16x16x32_bf16 v[14:17], v[154:157], v[244:247], v[14:17]
	v_mfma_f32_16x16x32_bf16 v[10:13], v[186:189], v[244:247], v[10:13]
	s_setprio 0
	s_setprio 1
	v_mfma_f32_16x16x32_bf16 v[54:57], v[190:193], v[216:219], v[54:57]
	s_add_i32 s39, s39, 2
	v_mfma_f32_16x16x32_bf16 v[50:53], v[198:201], v[216:219], v[50:53]
	s_add_u32 s37, s37, 0x100
	v_mfma_f32_16x16x32_bf16 v[38:41], v[190:193], v[224:227], v[38:41]
	s_addc_u32 s38, s38, 0
	v_mfma_f32_16x16x32_bf16 v[34:37], v[198:201], v[224:227], v[34:37]
	s_add_u32 s26, s26, 0x100
	v_mfma_f32_16x16x32_bf16 v[22:25], v[190:193], v[232:235], v[22:25]
	s_addc_u32 s27, s27, 0
	v_mfma_f32_16x16x32_bf16 v[18:21], v[198:201], v[232:235], v[18:21]
	s_add_u32 s28, s26, 0xfff80080
	v_mfma_f32_16x16x32_bf16 v[6:9], v[190:193], v[240:243], v[6:9]
	s_addc_u32 s29, s27, -1
	v_mfma_f32_16x16x32_bf16 v[2:5], v[198:201], v[240:243], v[2:5]
	s_add_i32 s44, 0, 0x10000
	v_mfma_f32_16x16x32_bf16 v[54:57], v[194:197], v[220:223], v[54:57]
	s_cmp_eq_u32 s39, 28
	v_mfma_f32_16x16x32_bf16 v[50:53], v[212:215], v[220:223], v[50:53]
	s_cselect_b32 s35, s19, s29
	v_mfma_f32_16x16x32_bf16 v[38:41], v[194:197], v[228:231], v[38:41]
	s_cselect_b32 s34, s31, s28
	v_mfma_f32_16x16x32_bf16 v[34:37], v[212:215], v[228:231], v[34:37]
	s_cselect_b32 s29, s17, s38
	v_mfma_f32_16x16x32_bf16 v[22:25], v[194:197], v[236:239], v[22:25]
	s_cselect_b32 s28, s33, s37
	v_mfma_f32_16x16x32_bf16 v[18:21], v[212:215], v[236:239], v[18:21]
	s_add_i32 s46, 0, 0x14000
	v_mfma_f32_16x16x32_bf16 v[6:9], v[194:197], v[244:247], v[6:9]
	s_cmp_gt_u32 s39, 29
	v_mfma_f32_16x16x32_bf16 v[2:5], v[212:215], v[244:247], v[2:5]
	s_setprio 0
	s_barrier
	s_cbranch_scc0 .LBB0_546
	s_and_b64 vcc, exec, s[14:15]
	s_cbranch_vccz .LBB0_549
	s_barrier

; #define PG8_STAGE(bufoff, gbase, voff) do { _Pragma("unroll") for (int _i = 0; _i < 2; ++_i) \
;         __builtin_amdgcn_global_load_lds((const unsigned*)((const char*)(gbase) + (voff)[_i]), (LAS unsigned*)(lds + (bufoff) + ldsw + _i * 8192), 16, 0, 0); } while (0)
; #define PG8_LDA(dst, b, h) do { _Pragma("unroll") for (int m = 0; m < 4; ++m) _Pragma("unroll") for (int k = 0; k < 2; ++k) dst[m][k] = *(const LAS bf16x8*)(lds + PG8_SA(b, h) + aoff + m * 2048 + k * 1024); } while (0)
; #define PG8_LDB(dst, b, h) do { _Pragma("unroll") for (int n = 0; n < 2; ++n) _Pragma("unroll") for (int k = 0; k < 2; ++k) dst[n][k] = *(const LAS bf16x8*)(lds + PG8_SB(b, h) + boff + n * 2048 + k * 1024); } while (0)
; #define PG8_BAR __builtin_amdgcn_s_barrier()
; template <class Epi>
; __device__ __forceinline__ void gemm_phase(LAS unsigned char* lds, const Gemm g, const StaticOrder& S, const Epi& E, const int tid) {
;     ...
;         const bool has_next = S.next(ui + 1, nxt);
;         const char* nA = has_next ? (const char*)g.A + (size_t)nxt.pm * tstep : cA; const char* nB = has_next ? (const char*)g.Bt + (size_t)nxt.pn * tstep : cB;
;         for (int t = 0; t < ntt; t += 2) {
;             const bool last = (t == ntt - 2);
;             const bool s1 = Epi::TWO && (t >= nt), s2 = Epi::TWO && (t + 2 >= nt);
;             const char* a1 = (s1 ? cA2 + (size_t)(t - nt + 1) * kstep : cA + (size_t)(t + 1) * kstep);
;             const char* a2 = last ? nA : (s2 ? cA2 + (size_t)(t + 2 - nt) * kstep : cA + (size_t)(t + 2) * kstep);
;             const char* b2 = last ? nB : (s2 ? cB2 + (size_t)(t + 2 - nt) * kstep : cB + (size_t)(t + 2) * kstep);
;             const char* a3 = a2 + kstep; const char* b3 = b2 + kstep;
;             if constexpr (Epi::TWO) { if (t == nt) E.mid(acc, cur, wr, wc, fr, fq); }
;             if constexpr (SP2) {
;             PG8_LDB(B0, 0, 0); PG8_LDB(B1, 0, 1); PG8_SCHED; PG8_LDA(At, 0, 0); PG8_STAGE(PG8_SA(1, 1), a1 + hstep, voffA);
;             PG8_WAIT_V(8); PG8_WAIT_L(0); PG8_BAR; PG8_MMA(0, 0, At, B0); PG8_MMA(0, 1, At, B1); PG8_BAR; PG8_SCHED;
;     ...
; #pragma unroll
;         for (int a = 0; a < 2; ++a)
; #pragma unroll
;             for (int b = 0; b < 2; ++b)
; #pragma unroll
;                 for (int m = 0; m < 4; ++m)
; #pragma unroll
;                     for (int n = 0; n < 2; ++n) acc[a][b][m][n] = (f32x4){0.f, 0.f, 0.f, 0.f};
.LBB0_843:
	s_ashr_i32 s15, s14, 31
	s_lshl_b64 s[18:19], s[14:15], 20
	s_add_u32 s18, s2, s18
	s_addc_u32 s19, s33, s19
	s_and_b64 s[20:21], s[16:17], exec
	s_cselect_b32 s15, s19, s29
	s_cselect_b32 s43, s18, s28
	s_ashr_i32 s13, s12, 31
	s_lshl_b64 s[20:21], s[12:13], 20
	s_add_u32 s20, s8, s20
	s_addc_u32 s21, s9, s21
	s_and_b64 s[30:31], s[16:17], exec
	s_cselect_b32 s13, s21, s27
	s_cselect_b32 s44, s20, s26
	s_add_u32 s45, s26, 0x100
	s_addc_u32 s46, s27, 0
	s_add_u32 s26, s28, 0x80080
	v_mov_b32_e32 v2, 0
	s_addc_u32 s27, s29, 0
	s_mov_b32 s47, -2
	v_mov_b32_e32 v3, v2
	v_mov_b32_e32 v4, v2
	v_mov_b32_e32 v5, v2
	v_mov_b32_e32 v6, v2
	v_mov_b32_e32 v7, v2
	v_mov_b32_e32 v8, v2
	v_mov_b32_e32 v9, v2
	v_mov_b32_e32 v10, v2
	v_mov_b32_e32 v11, v2
	v_mov_b32_e32 v12, v2
	v_mov_b32_e32 v13, v2
	v_mov_b32_e32 v18, v2
	v_mov_b32_e32 v19, v2
	v_mov_b32_e32 v20, v2
	v_mov_b32_e32 v21, v2
	v_mov_b32_e32 v26, v2
	v_mov_b32_e32 v27, v2
	v_mov_b32_e32 v28, v2
	v_mov_b32_e32 v29, v2
	v_mov_b32_e32 v34, v2
	v_mov_b32_e32 v35, v2
	v_mov_b32_e32 v36, v2
	v_mov_b32_e32 v37, v2
	v_mov_b32_e32 v42, v2
	v_mov_b32_e32 v43, v2
	v_mov_b32_e32 v44, v2
	v_mov_b32_e32 v45, v2
	v_mov_b32_e32 v50, v2
	v_mov_b32_e32 v51, v2
	v_mov_b32_e32 v52, v2
	v_mov_b32_e32 v53, v2
	v_mov_b32_e32 v14, v2
	v_mov_b32_e32 v15, v2
	v_mov_b32_e32 v16, v2
	v_mov_b32_e32 v17, v2
	v_mov_b32_e32 v22, v2
	v_mov_b32_e32 v23, v2
	v_mov_b32_e32 v24, v2
	v_mov_b32_e32 v25, v2
	v_mov_b32_e32 v30, v2
	v_mov_b32_e32 v31, v2
	v_mov_b32_e32 v32, v2
	v_mov_b32_e32 v33, v2
	v_mov_b32_e32 v38, v2
	v_mov_b32_e32 v39, v2
	v_mov_b32_e32 v40, v2
	v_mov_b32_e32 v41, v2
	v_mov_b32_e32 v46, v2
	v_mov_b32_e32 v47, v2
	v_mov_b32_e32 v48, v2
	v_mov_b32_e32 v49, v2
	v_mov_b32_e32 v54, v2
	v_mov_b32_e32 v55, v2
	v_mov_b32_e32 v56, v2
	v_mov_b32_e32 v57, v2
	v_mov_b32_e32 v58, v2
	v_mov_b32_e32 v59, v2
	v_mov_b32_e32 v60, v2
	v_mov_b32_e32 v61, v2
	v_mov_b32_e32 v62, v2
	v_mov_b32_e32 v63, v2
	v_mov_b32_e32 v64, v2
	v_mov_b32_e32 v65, v2
	v_mov_b32_e32 v66, v2
	v_mov_b32_e32 v67, v2
	v_mov_b32_e32 v68, v2
	v_mov_b32_e32 v69, v2
	v_mov_b32_e32 v70, v2
	v_mov_b32_e32 v71, v2
	v_mov_b32_e32 v72, v2
	v_mov_b32_e32 v73, v2
	v_mov_b32_e32 v74, v2
	v_mov_b32_e32 v75, v2
	v_mov_b32_e32 v76, v2
	v_mov_b32_e32 v77, v2
	v_mov_b32_e32 v82, v2
	v_mov_b32_e32 v83, v2
	v_mov_b32_e32 v84, v2
	v_mov_b32_e32 v85, v2
	v_mov_b32_e32 v90, v2
	v_mov_b32_e32 v91, v2
	v_mov_b32_e32 v92, v2
	v_mov_b32_e32 v93, v2
	v_mov_b32_e32 v98, v2
	v_mov_b32_e32 v99, v2
	v_mov_b32_e32 v100, v2
	v_mov_b32_e32 v101, v2
	v_mov_b32_e32 v106, v2
	v_mov_b32_e32 v107, v2
	v_mov_b32_e32 v108, v2
	v_mov_b32_e32 v109, v2
	v_mov_b32_e32 v114, v2
	v_mov_b32_e32 v115, v2
	v_mov_b32_e32 v116, v2
	v_mov_b32_e32 v117, v2
	v_mov_b32_e32 v78, v2
	v_mov_b32_e32 v79, v2
	v_mov_b32_e32 v80, v2
	v_mov_b32_e32 v81, v2
	v_mov_b32_e32 v86, v2
	v_mov_b32_e32 v87, v2
	v_mov_b32_e32 v88, v2
	v_mov_b32_e32 v89, v2
	v_mov_b32_e32 v94, v2
	v_mov_b32_e32 v95, v2
	v_mov_b32_e32 v96, v2
	v_mov_b32_e32 v97, v2
	v_mov_b32_e32 v102, v2
	v_mov_b32_e32 v103, v2
	v_mov_b32_e32 v104, v2
	v_mov_b32_e32 v105, v2
	v_mov_b32_e32 v110, v2
	v_mov_b32_e32 v111, v2
	v_mov_b32_e32 v112, v2
	v_mov_b32_e32 v113, v2
	v_mov_b32_e32 v118, v2
	v_mov_b32_e32 v119, v2
	v_mov_b32_e32 v120, v2
	v_mov_b32_e32 v121, v2
	v_mov_b32_e32 v122, v2
	v_mov_b32_e32 v123, v2
	v_mov_b32_e32 v124, v2
	v_mov_b32_e32 v125, v2
	v_mov_b32_e32 v126, v2
	v_mov_b32_e32 v127, v2
	v_mov_b32_e32 v128, v2
	v_mov_b32_e32 v129, v2
	s_add_u32 s28, s26, 0xfff80080
	s_addc_u32 s29, s27, -1
	s_add_i32 s48, 0, 0x10000
	s_cmp_eq_u32 s47, 28
	s_cselect_b32 s31, s15, s29
	s_cselect_b32 s30, s43, s28
	s_cselect_b32 s29, s13, s46
	s_cselect_b32 s28, s44, s45
	s_add_i32 s50, 0, 0x14000
.LBB0_844:
	v_add_u32_e32 v145, s48, v142
	ds_read_b128 v[146:149], v145
	ds_read_b128 v[150:153], v145 offset:1024
	ds_read_b128 v[154:157], v145 offset:2048
	ds_read_b128 v[158:161], v145 offset:3072
	v_add_u32_e32 v145, s50, v142
	ds_read_b128 v[162:165], v145
	ds_read_b128 v[166:169], v145 offset:1024
	ds_read_b128 v[178:181], v145 offset:2048
	ds_read_b128 v[182:185], v145 offset:3072
	v_lshl_add_u64 v[172:173], s[26:27], 0, v[138:139]
	s_add_i32 m0, s23, 0xc000
	ds_read_b128 v[186:189], v144
	global_load_lds_dwordx4 v[172:173], off
	ds_read_b128 v[190:193], v144 offset:1024
	ds_read_b128 v[194:197], v144 offset:2048
	v_lshl_add_u64 v[172:173], s[26:27], 0, v[136:137]
	s_add_i32 m0, s23, 0xe000
	s_nop 0
	global_load_lds_dwordx4 v[172:173], off
	ds_read_b128 v[198:201], v144 offset:3072
	ds_read_b128 v[212:215], v144 offset:4096
	ds_read_b128 v[216:219], v144 offset:5120
	ds_read_b128 v[220:223], v144 offset:6144
	ds_read_b128 v[224:227], v144 offset:7168
	s_waitcnt vmcnt(8)
	s_waitcnt lgkmcnt(0)
	s_barrier
; #define PG8_STAGE(bufoff, gbase, voff) do { _Pragma("unroll") for (int _i = 0; _i < 2; ++_i) \
;         __builtin_amdgcn_global_load_lds((const unsigned*)((const char*)(gbase) + (voff)[_i]), (LAS unsigned*)(lds + (bufoff) + ldsw + _i * 8192), 16, 0, 0); } while (0)
; #define PG8_LDA(dst, b, h) do { _Pragma("unroll") for (int m = 0; m < 4; ++m) _Pragma("unroll") for (int k = 0; k < 2; ++k) dst[m][k] = *(const LAS bf16x8*)(lds + PG8_SA(b, h) + aoff + m * 2048 + k * 1024); } while (0)
; #define PG8_MMA(ai, bj, At, Bt) do { __builtin_amdgcn_s_setprio(1); _Pragma("unroll") for (int m = 0; m < 4; ++m) _Pragma("unroll") for (int n = 0; n < 2; ++n) _Pragma("unroll") for (int k = 0; k < 2; ++k) \
;         acc[ai][bj][m][n] = __builtin_amdgcn_mfma_f32_16x16x32_bf16(Bt[n][k], At[m][k], acc[ai][bj][m][n], 0, 0, 0); __builtin_amdgcn_s_setprio(0); } while (0)
; #define PG8_WAIT_V(n) asm volatile("s_waitcnt vmcnt(" #n ")" ::: "memory")
; #define PG8_WAIT_L(n) asm volatile("s_waitcnt lgkmcnt(" #n ")" ::: "memory")
; #define PG8_BAR __builtin_amdgcn_s_barrier()
; #define PG8_SCHED __builtin_amdgcn_sched_barrier(0)
; template <class Epi>
; __device__ __forceinline__ void gemm_phase(LAS unsigned char* lds, const Gemm g, const StaticOrder& S, const Epi& E, const int tid) {
;     ...
;             PG8_WAIT_V(8); PG8_WAIT_L(0); PG8_BAR; PG8_MMA(0, 0, At, B0); PG8_MMA(0, 1, At, B1); PG8_BAR; PG8_SCHED;
;             PG8_LDA(At, 0, 1); PG8_STAGE(PG8_SB(0, 0), b2, voffB); PG8_STAGE(PG8_SB(0, 1), b2 + bhs, voffB); PG8_STAGE(PG8_SA(0, 0), a2, voffA);
;             PG8_WAIT_V(8); PG8_WAIT_L(0); PG8_BAR; PG8_MMA(1, 0, At, B0); PG8_MMA(1, 1, At, B1); PG8_BAR; PG8_SCHED;
	s_setprio 1
	s_waitcnt lgkmcnt(0)
	v_mfma_f32_16x16x32_bf16 v[126:129], v[146:149], v[186:189], v[126:129]
	v_mfma_f32_16x16x32_bf16 v[122:125], v[154:157], v[186:189], v[122:125]
	v_mfma_f32_16x16x32_bf16 v[118:121], v[146:149], v[194:197], v[118:121]
	v_mfma_f32_16x16x32_bf16 v[110:113], v[154:157], v[194:197], v[110:113]
	v_mfma_f32_16x16x32_bf16 v[102:105], v[146:149], v[212:215], v[102:105]
	v_mfma_f32_16x16x32_bf16 v[94:97], v[154:157], v[212:215], v[94:97]
	v_mfma_f32_16x16x32_bf16 v[86:89], v[146:149], v[220:223], v[86:89]
	v_mfma_f32_16x16x32_bf16 v[78:81], v[154:157], v[220:223], v[78:81]
	v_mfma_f32_16x16x32_bf16 v[126:129], v[150:153], v[190:193], v[126:129]
	v_mfma_f32_16x16x32_bf16 v[122:125], v[158:161], v[190:193], v[122:125]
	v_mfma_f32_16x16x32_bf16 v[118:121], v[150:153], v[198:201], v[118:121]
	v_mfma_f32_16x16x32_bf16 v[110:113], v[158:161], v[198:201], v[110:113]
	v_mfma_f32_16x16x32_bf16 v[102:105], v[150:153], v[216:219], v[102:105]
	v_mfma_f32_16x16x32_bf16 v[94:97], v[158:161], v[216:219], v[94:97]
	v_mfma_f32_16x16x32_bf16 v[86:89], v[150:153], v[224:227], v[86:89]
	v_mfma_f32_16x16x32_bf16 v[78:81], v[158:161], v[224:227], v[78:81]
	s_setprio 0
	s_setprio 1
	v_mfma_f32_16x16x32_bf16 v[114:117], v[162:165], v[186:189], v[114:117]
	v_mfma_f32_16x16x32_bf16 v[106:109], v[178:181], v[186:189], v[106:109]
	v_mfma_f32_16x16x32_bf16 v[98:101], v[162:165], v[194:197], v[98:101]
	v_mfma_f32_16x16x32_bf16 v[90:93], v[178:181], v[194:197], v[90:93]
	v_mfma_f32_16x16x32_bf16 v[82:85], v[162:165], v[212:215], v[82:85]
	v_mfma_f32_16x16x32_bf16 v[74:77], v[178:181], v[212:215], v[74:77]
	v_mfma_f32_16x16x32_bf16 v[70:73], v[162:165], v[220:223], v[70:73]
	v_mfma_f32_16x16x32_bf16 v[66:69], v[178:181], v[220:223], v[66:69]
	v_mfma_f32_16x16x32_bf16 v[114:117], v[166:169], v[190:193], v[114:117]
	v_mfma_f32_16x16x32_bf16 v[106:109], v[182:185], v[190:193], v[106:109]
	v_mfma_f32_16x16x32_bf16 v[98:101], v[166:169], v[198:201], v[98:101]
	v_mfma_f32_16x16x32_bf16 v[90:93], v[182:185], v[198:201], v[90:93]
	v_mfma_f32_16x16x32_bf16 v[82:85], v[166:169], v[216:219], v[82:85]
	v_mfma_f32_16x16x32_bf16 v[74:77], v[182:185], v[216:219], v[74:77]
	v_mfma_f32_16x16x32_bf16 v[70:73], v[166:169], v[224:227], v[70:73]
	v_mfma_f32_16x16x32_bf16 v[66:69], v[182:185], v[224:227], v[66:69]
	s_setprio 0
	s_barrier
	s_add_i32 s48, s48, s37
	v_lshl_add_u64 v[172:173], s[28:29], 0, v[0:1]
	s_mov_b32 m0, s48
	ds_read_b128 v[186:189], v144 offset:16384
	global_load_lds_dwordx4 v[172:173], off
	ds_read_b128 v[190:193], v144 offset:17408
	ds_read_b128 v[194:197], v144 offset:18432
	s_add_i32 m0, s48, 0x2000
	s_add_u32 s48, s28, 0x8000
	v_lshl_add_u64 v[174:175], s[28:29], 0, v[134:135]
	s_addc_u32 s49, s29, 0
	s_add_i32 s50, s50, s37
	global_load_lds_dwordx4 v[174:175], off
	ds_read_b128 v[198:201], v144 offset:19456
	ds_read_b128 v[212:215], v144 offset:20480
	v_lshl_add_u64 v[176:177], s[48:49], 0, v[0:1]
	s_mov_b32 m0, s50
	v_lshl_add_u64 v[228:229], s[30:31], 0, v[132:133]
	global_load_lds_dwordx4 v[176:177], off
	ds_read_b128 v[216:219], v144 offset:21504
	ds_read_b128 v[220:223], v144 offset:22528
	v_lshl_add_u64 v[176:177], s[48:49], 0, v[134:135]
	s_add_i32 m0, s50, 0x2000
	s_nop 0
	global_load_lds_dwordx4 v[176:177], off
	ds_read_b128 v[224:227], v144 offset:23552
	v_lshl_add_u64 v[176:177], s[30:31], 0, v[130:131]
	s_mov_b32 m0, s23
	s_nop 0
	global_load_lds_dwordx4 v[176:177], off
	s_mov_b32 m0, s25
	s_nop 0
	global_load_lds_dwordx4 v[228:229], off
	s_waitcnt vmcnt(8)
	s_waitcnt lgkmcnt(0)
	s_barrier
	s_setprio 1
	s_waitcnt lgkmcnt(0)
	v_mfma_f32_16x16x32_bf16 v[62:65], v[146:149], v[186:189], v[62:65]
	v_mfma_f32_16x16x32_bf16 v[58:61], v[154:157], v[186:189], v[58:61]
	v_mfma_f32_16x16x32_bf16 v[54:57], v[146:149], v[194:197], v[54:57]
	v_mfma_f32_16x16x32_bf16 v[46:49], v[154:157], v[194:197], v[46:49]
	v_mfma_f32_16x16x32_bf16 v[38:41], v[146:149], v[212:215], v[38:41]
	v_mfma_f32_16x16x32_bf16 v[30:33], v[154:157], v[212:215], v[30:33]
	v_mfma_f32_16x16x32_bf16 v[22:25], v[146:149], v[220:223], v[22:25]
	v_mfma_f32_16x16x32_bf16 v[14:17], v[154:157], v[220:223], v[14:17]
	v_mfma_f32_16x16x32_bf16 v[62:65], v[150:153], v[190:193], v[62:65]
	v_mfma_f32_16x16x32_bf16 v[58:61], v[158:161], v[190:193], v[58:61]
	v_mfma_f32_16x16x32_bf16 v[54:57], v[150:153], v[198:201], v[54:57]
	v_mfma_f32_16x16x32_bf16 v[46:49], v[158:161], v[198:201], v[46:49]
	v_mfma_f32_16x16x32_bf16 v[38:41], v[150:153], v[216:219], v[38:41]
	v_mfma_f32_16x16x32_bf16 v[30:33], v[158:161], v[216:219], v[30:33]
	v_mfma_f32_16x16x32_bf16 v[22:25], v[150:153], v[224:227], v[22:25]
	v_mfma_f32_16x16x32_bf16 v[14:17], v[158:161], v[224:227], v[14:17]
	s_setprio 0
	s_setprio 1
	v_mfma_f32_16x16x32_bf16 v[50:53], v[162:165], v[186:189], v[50:53]
	v_mfma_f32_16x16x32_bf16 v[42:45], v[178:181], v[186:189], v[42:45]
	v_mfma_f32_16x16x32_bf16 v[34:37], v[162:165], v[194:197], v[34:37]
	v_mfma_f32_16x16x32_bf16 v[26:29], v[178:181], v[194:197], v[26:29]
	v_mfma_f32_16x16x32_bf16 v[18:21], v[162:165], v[212:215], v[18:21]
	v_mfma_f32_16x16x32_bf16 v[10:13], v[178:181], v[212:215], v[10:13]
	v_mfma_f32_16x16x32_bf16 v[6:9], v[162:165], v[220:223], v[6:9]
	v_mfma_f32_16x16x32_bf16 v[2:5], v[178:181], v[220:223], v[2:5]
	v_mfma_f32_16x16x32_bf16 v[50:53], v[166:169], v[190:193], v[50:53]
	v_mfma_f32_16x16x32_bf16 v[42:45], v[182:185], v[190:193], v[42:45]
	v_mfma_f32_16x16x32_bf16 v[34:37], v[166:169], v[198:201], v[34:37]
	v_mfma_f32_16x16x32_bf16 v[26:29], v[182:185], v[198:201], v[26:29]
	v_mfma_f32_16x16x32_bf16 v[18:21], v[166:169], v[216:219], v[18:21]
	v_mfma_f32_16x16x32_bf16 v[10:13], v[182:185], v[216:219], v[10:13]
	v_mfma_f32_16x16x32_bf16 v[6:9], v[166:169], v[224:227], v[6:9]
	v_mfma_f32_16x16x32_bf16 v[2:5], v[182:185], v[224:227], v[2:5]
	s_setprio 0
	s_barrier
; #define PG8_STAGE(bufoff, gbase, voff) do { _Pragma("unroll") for (int _i = 0; _i < 2; ++_i) \
;         __builtin_amdgcn_global_load_lds((const unsigned*)((const char*)(gbase) + (voff)[_i]), (LAS unsigned*)(lds + (bufoff) + ldsw + _i * 8192), 16, 0, 0); } while (0)
; #define PG8_LDA(dst, b, h) do { _Pragma("unroll") for (int m = 0; m < 4; ++m) _Pragma("unroll") for (int k = 0; k < 2; ++k) dst[m][k] = *(const LAS bf16x8*)(lds + PG8_SA(b, h) + aoff + m * 2048 + k * 1024); } while (0)
; #define PG8_LDB(dst, b, h) do { _Pragma("unroll") for (int n = 0; n < 2; ++n) _Pragma("unroll") for (int k = 0; k < 2; ++k) dst[n][k] = *(const LAS bf16x8*)(lds + PG8_SB(b, h) + boff + n * 2048 + k * 1024); } while (0)
; #define PG8_MMA(ai, bj, At, Bt) do { __builtin_amdgcn_s_setprio(1); _Pragma("unroll") for (int m = 0; m < 4; ++m) _Pragma("unroll") for (int n = 0; n < 2; ++n) _Pragma("unroll") for (int k = 0; k < 2; ++k) \
;         acc[ai][bj][m][n] = __builtin_amdgcn_mfma_f32_16x16x32_bf16(Bt[n][k], At[m][k], acc[ai][bj][m][n], 0, 0, 0); __builtin_amdgcn_s_setprio(0); } while (0)
; #define PG8_WAIT_V(n) asm volatile("s_waitcnt vmcnt(" #n ")" ::: "memory")
; #define PG8_WAIT_L(n) asm volatile("s_waitcnt lgkmcnt(" #n ")" ::: "memory")
; #define PG8_BAR __builtin_amdgcn_s_barrier()
; #define PG8_SCHED __builtin_amdgcn_sched_barrier(0)
; template <class Epi>
; __device__ __forceinline__ void gemm_phase(LAS unsigned char* lds, const Gemm g, const StaticOrder& S, const Epi& E, const int tid) {
;     ...
;             PG8_LDB(B0, 1, 0); PG8_LDB(B1, 1, 1); PG8_SCHED; PG8_LDA(At, 1, 0); PG8_STAGE(PG8_SA(0, 1), a2 + hstep, voffA);
;             PG8_WAIT_V(8); PG8_WAIT_L(0); PG8_BAR; PG8_MMA(0, 0, At, B0); PG8_MMA(0, 1, At, B1); PG8_BAR; PG8_SCHED;
	s_add_i32 s48, 0, 0x18000
	v_add_u32_e32 v145, s48, v142
	s_add_i32 s49, 0, 0x1c000
	ds_read_b128 v[146:149], v145
	ds_read_b128 v[150:153], v145 offset:1024
	ds_read_b128 v[154:157], v145 offset:2048
	ds_read_b128 v[158:161], v145 offset:3072
	v_add_u32_e32 v145, s49, v142
	ds_read_b128 v[162:165], v145
	ds_read_b128 v[166:169], v145 offset:1024
	ds_read_b128 v[178:181], v145 offset:2048
	ds_read_b128 v[182:185], v145 offset:3072
	s_add_u32 s30, s30, 0x80000
	s_addc_u32 s31, s31, 0
	s_mov_b32 m0, s38
	v_lshl_add_u64 v[230:231], s[30:31], 0, v[130:131]
	ds_read_b128 v[186:189], v144 offset:32768
	global_load_lds_dwordx4 v[230:231], off
	ds_read_b128 v[190:193], v144 offset:33792
	ds_read_b128 v[194:197], v144 offset:34816
	v_lshl_add_u64 v[230:231], s[30:31], 0, v[132:133]
	s_mov_b32 m0, s39
	s_nop 0
	global_load_lds_dwordx4 v[230:231], off
	ds_read_b128 v[198:201], v144 offset:35840
	ds_read_b128 v[212:215], v144 offset:36864
	ds_read_b128 v[216:219], v144 offset:37888
	ds_read_b128 v[220:223], v144 offset:38912
	ds_read_b128 v[224:227], v144 offset:39936
	s_waitcnt vmcnt(8)
	s_waitcnt lgkmcnt(0)
	s_barrier
	s_setprio 1
	s_waitcnt lgkmcnt(0)
	v_mfma_f32_16x16x32_bf16 v[126:129], v[146:149], v[186:189], v[126:129]
	v_mfma_f32_16x16x32_bf16 v[122:125], v[154:157], v[186:189], v[122:125]
	v_mfma_f32_16x16x32_bf16 v[118:121], v[146:149], v[194:197], v[118:121]
	v_mfma_f32_16x16x32_bf16 v[110:113], v[154:157], v[194:197], v[110:113]
	v_mfma_f32_16x16x32_bf16 v[102:105], v[146:149], v[212:215], v[102:105]
	v_mfma_f32_16x16x32_bf16 v[94:97], v[154:157], v[212:215], v[94:97]
	v_mfma_f32_16x16x32_bf16 v[86:89], v[146:149], v[220:223], v[86:89]
	v_mfma_f32_16x16x32_bf16 v[78:81], v[154:157], v[220:223], v[78:81]
	v_mfma_f32_16x16x32_bf16 v[126:129], v[150:153], v[190:193], v[126:129]
	v_mfma_f32_16x16x32_bf16 v[122:125], v[158:161], v[190:193], v[122:125]
	v_mfma_f32_16x16x32_bf16 v[118:121], v[150:153], v[198:201], v[118:121]
	v_mfma_f32_16x16x32_bf16 v[110:113], v[158:161], v[198:201], v[110:113]
	v_mfma_f32_16x16x32_bf16 v[102:105], v[150:153], v[216:219], v[102:105]
	v_mfma_f32_16x16x32_bf16 v[94:97], v[158:161], v[216:219], v[94:97]
	v_mfma_f32_16x16x32_bf16 v[86:89], v[150:153], v[224:227], v[86:89]
	v_mfma_f32_16x16x32_bf16 v[78:81], v[158:161], v[224:227], v[78:81]
	s_setprio 0
	s_setprio 1
	v_mfma_f32_16x16x32_bf16 v[114:117], v[162:165], v[186:189], v[114:117]
	v_mfma_f32_16x16x32_bf16 v[106:109], v[178:181], v[186:189], v[106:109]
	v_mfma_f32_16x16x32_bf16 v[98:101], v[162:165], v[194:197], v[98:101]
	v_mfma_f32_16x16x32_bf16 v[90:93], v[178:181], v[194:197], v[90:93]
	v_mfma_f32_16x16x32_bf16 v[82:85], v[162:165], v[212:215], v[82:85]
	v_mfma_f32_16x16x32_bf16 v[74:77], v[178:181], v[212:215], v[74:77]
	v_mfma_f32_16x16x32_bf16 v[70:73], v[162:165], v[220:223], v[70:73]
	v_mfma_f32_16x16x32_bf16 v[66:69], v[178:181], v[220:223], v[66:69]
	v_mfma_f32_16x16x32_bf16 v[114:117], v[166:169], v[190:193], v[114:117]
	v_mfma_f32_16x16x32_bf16 v[106:109], v[182:185], v[190:193], v[106:109]
	v_mfma_f32_16x16x32_bf16 v[98:101], v[166:169], v[198:201], v[98:101]
	v_mfma_f32_16x16x32_bf16 v[90:93], v[182:185], v[198:201], v[90:93]
	v_mfma_f32_16x16x32_bf16 v[82:85], v[166:169], v[216:219], v[82:85]
	v_mfma_f32_16x16x32_bf16 v[74:77], v[182:185], v[216:219], v[74:77]
	v_mfma_f32_16x16x32_bf16 v[70:73], v[166:169], v[224:227], v[70:73]
	v_mfma_f32_16x16x32_bf16 v[66:69], v[182:185], v[224:227], v[66:69]
	s_setprio 0
	s_barrier
; #define PG8_STAGE(bufoff, gbase, voff) do { _Pragma("unroll") for (int _i = 0; _i < 2; ++_i) \
;         __builtin_amdgcn_global_load_lds((const unsigned*)((const char*)(gbase) + (voff)[_i]), (LAS unsigned*)(lds + (bufoff) + ldsw + _i * 8192), 16, 0, 0); } while (0)
; #define PG8_LDA(dst, b, h) do { _Pragma("unroll") for (int m = 0; m < 4; ++m) _Pragma("unroll") for (int k = 0; k < 2; ++k) dst[m][k] = *(const LAS bf16x8*)(lds + PG8_SA(b, h) + aoff + m * 2048 + k * 1024); } while (0)
; #define PG8_MMA(ai, bj, At, Bt) do { __builtin_amdgcn_s_setprio(1); _Pragma("unroll") for (int m = 0; m < 4; ++m) _Pragma("unroll") for (int n = 0; n < 2; ++n) _Pragma("unroll") for (int k = 0; k < 2; ++k) \
;         acc[ai][bj][m][n] = __builtin_amdgcn_mfma_f32_16x16x32_bf16(Bt[n][k], At[m][k], acc[ai][bj][m][n], 0, 0, 0); __builtin_amdgcn_s_setprio(0); } while (0)
; #define PG8_WAIT_V(n) asm volatile("s_waitcnt vmcnt(" #n ")" ::: "memory")
; #define PG8_WAIT_L(n) asm volatile("s_waitcnt lgkmcnt(" #n ")" ::: "memory")
; #define PG8_BAR __builtin_amdgcn_s_barrier()
; #define PG8_SCHED __builtin_amdgcn_sched_barrier(0)
; template <class Epi>
; __device__ __forceinline__ void gemm_phase(LAS unsigned char* lds, const Gemm g, const StaticOrder& S, const Epi& E, const int tid) {
;     ...
;             const bool last = (t == ntt - 2);
;             const bool s1 = Epi::TWO && (t >= nt), s2 = Epi::TWO && (t + 2 >= nt);
;             const char* a1 = (s1 ? cA2 + (size_t)(t - nt + 1) * kstep : cA + (size_t)(t + 1) * kstep);
;             const char* a2 = last ? nA : (s2 ? cA2 + (size_t)(t + 2 - nt) * kstep : cA + (size_t)(t + 2) * kstep);
;             const char* b2 = last ? nB : (s2 ? cB2 + (size_t)(t + 2 - nt) * kstep : cB + (size_t)(t + 2) * kstep);
;             const char* a3 = a2 + kstep; const char* b3 = b2 + kstep;
;     ...
;             PG8_LDA(At, 1, 1); PG8_STAGE(PG8_SB(1, 0), b3, voffB); PG8_STAGE(PG8_SB(1, 1), b3 + bhs, voffB); PG8_STAGE(PG8_SA(1, 0), a3, voffA);
;             PG8_WAIT_V(8); PG8_WAIT_L(0); PG8_BAR; PG8_MMA(1, 0, At, B0); PG8_MMA(1, 1, At, B1); PG8_BAR; PG8_SCHED;
	s_add_i32 s30, s48, s37
	v_lshl_add_u64 v[172:173], v[172:173], 0, s[70:71]
	s_mov_b32 m0, s30
	ds_read_b128 v[186:189], v144 offset:49152
	global_load_lds_dwordx4 v[172:173], off
	ds_read_b128 v[190:193], v144 offset:50176
	ds_read_b128 v[194:197], v144 offset:51200
	s_add_i32 m0, s30, 0x2000
	s_add_u32 s28, s28, 0x8080
	v_lshl_add_u64 v[172:173], v[174:175], 0, s[70:71]
	s_addc_u32 s29, s29, 0
	s_add_i32 s30, s49, s37
	global_load_lds_dwordx4 v[172:173], off
	ds_read_b128 v[198:201], v144 offset:52224
	ds_read_b128 v[212:215], v144 offset:53248
	v_lshl_add_u64 v[172:173], s[28:29], 0, v[0:1]
	s_mov_b32 m0, s30
	s_nop 0
	global_load_lds_dwordx4 v[172:173], off
	ds_read_b128 v[216:219], v144 offset:54272
	ds_read_b128 v[220:223], v144 offset:55296
	v_lshl_add_u64 v[172:173], s[28:29], 0, v[134:135]
	s_add_i32 m0, s30, 0x2000
	s_nop 0
	global_load_lds_dwordx4 v[172:173], off
	ds_read_b128 v[224:227], v144 offset:56320
	v_lshl_add_u64 v[172:173], v[176:177], 0, s[70:71]
	s_mov_b32 m0, s40
	s_nop 0
	global_load_lds_dwordx4 v[172:173], off
	v_lshl_add_u64 v[172:173], v[228:229], 0, s[70:71]
	s_mov_b32 m0, s41
	s_nop 0
	global_load_lds_dwordx4 v[172:173], off
	s_waitcnt vmcnt(8)
	s_waitcnt lgkmcnt(0)
	s_barrier
	s_setprio 1
	s_waitcnt lgkmcnt(0)
	v_mfma_f32_16x16x32_bf16 v[62:65], v[146:149], v[186:189], v[62:65]
	v_mfma_f32_16x16x32_bf16 v[58:61], v[154:157], v[186:189], v[58:61]
	v_mfma_f32_16x16x32_bf16 v[54:57], v[146:149], v[194:197], v[54:57]
	v_mfma_f32_16x16x32_bf16 v[46:49], v[154:157], v[194:197], v[46:49]
	v_mfma_f32_16x16x32_bf16 v[38:41], v[146:149], v[212:215], v[38:41]
	v_mfma_f32_16x16x32_bf16 v[30:33], v[154:157], v[212:215], v[30:33]
	v_mfma_f32_16x16x32_bf16 v[22:25], v[146:149], v[220:223], v[22:25]
	v_mfma_f32_16x16x32_bf16 v[14:17], v[154:157], v[220:223], v[14:17]
	v_mfma_f32_16x16x32_bf16 v[62:65], v[150:153], v[190:193], v[62:65]
	v_mfma_f32_16x16x32_bf16 v[58:61], v[158:161], v[190:193], v[58:61]
	v_mfma_f32_16x16x32_bf16 v[54:57], v[150:153], v[198:201], v[54:57]
	v_mfma_f32_16x16x32_bf16 v[46:49], v[158:161], v[198:201], v[46:49]
	v_mfma_f32_16x16x32_bf16 v[38:41], v[150:153], v[216:219], v[38:41]
	v_mfma_f32_16x16x32_bf16 v[30:33], v[158:161], v[216:219], v[30:33]
	v_mfma_f32_16x16x32_bf16 v[22:25], v[150:153], v[224:227], v[22:25]
	v_mfma_f32_16x16x32_bf16 v[14:17], v[158:161], v[224:227], v[14:17]
	s_setprio 0
	s_setprio 1
	v_mfma_f32_16x16x32_bf16 v[50:53], v[162:165], v[186:189], v[50:53]
	s_add_i32 s47, s47, 2
	v_mfma_f32_16x16x32_bf16 v[42:45], v[178:181], v[186:189], v[42:45]
	s_add_u32 s45, s45, 0x100
	v_mfma_f32_16x16x32_bf16 v[34:37], v[162:165], v[194:197], v[34:37]
	s_addc_u32 s46, s46, 0
	v_mfma_f32_16x16x32_bf16 v[26:29], v[178:181], v[194:197], v[26:29]
	s_add_u32 s26, s26, 0x100
	v_mfma_f32_16x16x32_bf16 v[18:21], v[162:165], v[212:215], v[18:21]
	s_addc_u32 s27, s27, 0
	v_mfma_f32_16x16x32_bf16 v[10:13], v[178:181], v[212:215], v[10:13]
	s_add_u32 s28, s26, 0xfff80080
	v_mfma_f32_16x16x32_bf16 v[6:9], v[162:165], v[220:223], v[6:9]
	s_addc_u32 s29, s27, -1
	v_mfma_f32_16x16x32_bf16 v[2:5], v[178:181], v[220:223], v[2:5]
	s_add_i32 s48, 0, 0x10000
	v_mfma_f32_16x16x32_bf16 v[50:53], v[166:169], v[190:193], v[50:53]
	s_cmp_eq_u32 s47, 28
	v_mfma_f32_16x16x32_bf16 v[42:45], v[182:185], v[190:193], v[42:45]
	s_cselect_b32 s31, s15, s29
	v_mfma_f32_16x16x32_bf16 v[34:37], v[166:169], v[198:201], v[34:37]
	s_cselect_b32 s30, s43, s28
	v_mfma_f32_16x16x32_bf16 v[26:29], v[182:185], v[198:201], v[26:29]
	s_cselect_b32 s29, s13, s46
	v_mfma_f32_16x16x32_bf16 v[18:21], v[166:169], v[216:219], v[18:21]
	s_cselect_b32 s28, s44, s45
	v_mfma_f32_16x16x32_bf16 v[10:13], v[182:185], v[216:219], v[10:13]
	s_add_i32 s50, 0, 0x14000
	v_mfma_f32_16x16x32_bf16 v[6:9], v[166:169], v[224:227], v[6:9]
	s_cmp_gt_u32 s47, 29
	v_mfma_f32_16x16x32_bf16 v[2:5], v[182:185], v[224:227], v[2:5]
	s_setprio 0
	s_barrier
	s_cbranch_scc0 .LBB0_844
	s_and_b64 vcc, exec, s[10:11]
	s_cbranch_vccz .LBB0_847
	s_barrier

; #define PG8_STAGE(bufoff, gbase, voff) do { _Pragma("unroll") for (int _i = 0; _i < 2; ++_i) \
;         __builtin_amdgcn_global_load_lds((const unsigned*)((const char*)(gbase) + (voff)[_i]), (LAS unsigned*)(lds + (bufoff) + ldsw + _i * 8192), 16, 0, 0); } while (0)
; #define PG8_LDA(dst, b, h) do { _Pragma("unroll") for (int m = 0; m < 4; ++m) _Pragma("unroll") for (int k = 0; k < 2; ++k) dst[m][k] = *(const LAS bf16x8*)(lds + PG8_SA(b, h) + aoff + m * 2048 + k * 1024); } while (0)
; #define PG8_LDB(dst, b, h) do { _Pragma("unroll") for (int n = 0; n < 2; ++n) _Pragma("unroll") for (int k = 0; k < 2; ++k) dst[n][k] = *(const LAS bf16x8*)(lds + PG8_SB(b, h) + boff + n * 2048 + k * 1024); } while (0)
; template <class Epi>
; __device__ __forceinline__ void gemm_phase(LAS unsigned char* lds, const Gemm g, const StaticOrder& S, const Epi& E, const int tid) {
;     ...
;         const bool has_next = S.next(ui + 1, nxt);
;         const char* nA = has_next ? (const char*)g.A + (size_t)nxt.pm * tstep : cA; const char* nB = has_next ? (const char*)g.Bt + (size_t)nxt.pn * tstep : cB;
;         for (int t = 0; t < ntt; t += 2) {
;             const bool last = (t == ntt - 2);
;             const bool s1 = Epi::TWO && (t >= nt), s2 = Epi::TWO && (t + 2 >= nt);
;             const char* a1 = (s1 ? cA2 + (size_t)(t - nt + 1) * kstep : cA + (size_t)(t + 1) * kstep);
;             const char* a2 = last ? nA : (s2 ? cA2 + (size_t)(t + 2 - nt) * kstep : cA + (size_t)(t + 2) * kstep);
;             const char* b2 = last ? nB : (s2 ? cB2 + (size_t)(t + 2 - nt) * kstep : cB + (size_t)(t + 2) * kstep);
;             const char* a3 = a2 + kstep; const char* b3 = b2 + kstep;
;             if constexpr (Epi::TWO) { if (t == nt) E.mid(acc, cur, wr, wc, fr, fq); }
;             if constexpr (SP2) {
;             PG8_LDB(B0, 0, 0); PG8_LDB(B1, 0, 1); PG8_SCHED; PG8_LDA(At, 0, 0); PG8_STAGE(PG8_SA(1, 1), a1 + hstep, voffA);
;             PG8_WAIT_V(8); PG8_WAIT_L(0); PG8_BAR; PG8_MMA(0, 0, At, B0); PG8_MMA(0, 1, At, B1); PG8_BAR; PG8_SCHED;
;     ...
; #pragma unroll
;         for (int a = 0; a < 2; ++a)
; #pragma unroll
;             for (int b = 0; b < 2; ++b)
; #pragma unroll
;                 for (int m = 0; m < 4; ++m)
; #pragma unroll
;                     for (int n = 0; n < 2; ++n) acc[a][b][m][n] = (f32x4){0.f, 0.f, 0.f, 0.f};
;         cur = nxt; cA = nA; cB = nB; ++ui;
.LBB0_860:
	s_ashr_i32 s17, s16, 31
	s_lshl_b64 s[20:21], s[16:17], 20
	s_add_u32 s20, s37, s20
	s_addc_u32 s21, s38, s21
	s_and_b64 s[22:23], s[18:19], exec
	s_cselect_b32 s17, s21, s31
	s_cselect_b32 s46, s20, s30
	s_ashr_i32 s15, s14, 31
	s_lshl_b64 s[22:23], s[14:15], 20
	s_add_u32 s22, s2, s22
	s_addc_u32 s23, s33, s23
	s_and_b64 s[34:35], s[18:19], exec
	s_cselect_b32 s15, s23, s29
	s_cselect_b32 s47, s22, s28
	s_add_u32 s48, s28, 0x100
	s_addc_u32 s49, s29, 0
	s_add_u32 s28, s30, 0x80080
	v_mov_b32_e32 v2, 0
	s_addc_u32 s29, s31, 0
	s_mov_b32 s50, -2
	v_mov_b32_e32 v3, v2
	v_mov_b32_e32 v4, v2
	v_mov_b32_e32 v5, v2
	v_mov_b32_e32 v6, v2
	v_mov_b32_e32 v7, v2
	v_mov_b32_e32 v8, v2
	v_mov_b32_e32 v9, v2
	v_mov_b32_e32 v10, v2
	v_mov_b32_e32 v11, v2
	v_mov_b32_e32 v12, v2
	v_mov_b32_e32 v13, v2
	v_mov_b32_e32 v18, v2
	v_mov_b32_e32 v19, v2
	v_mov_b32_e32 v20, v2
	v_mov_b32_e32 v21, v2
	v_mov_b32_e32 v26, v2
	v_mov_b32_e32 v27, v2
	v_mov_b32_e32 v28, v2
	v_mov_b32_e32 v29, v2
	v_mov_b32_e32 v34, v2
	v_mov_b32_e32 v35, v2
	v_mov_b32_e32 v36, v2
	v_mov_b32_e32 v37, v2
	v_mov_b32_e32 v42, v2
	v_mov_b32_e32 v43, v2
	v_mov_b32_e32 v44, v2
	v_mov_b32_e32 v45, v2
	v_mov_b32_e32 v50, v2
	v_mov_b32_e32 v51, v2
	v_mov_b32_e32 v52, v2
	v_mov_b32_e32 v53, v2
	v_mov_b32_e32 v14, v2
	v_mov_b32_e32 v15, v2
	v_mov_b32_e32 v16, v2
	v_mov_b32_e32 v17, v2
	v_mov_b32_e32 v22, v2
	v_mov_b32_e32 v23, v2
	v_mov_b32_e32 v24, v2
	v_mov_b32_e32 v25, v2
	v_mov_b32_e32 v30, v2
	v_mov_b32_e32 v31, v2
	v_mov_b32_e32 v32, v2
	v_mov_b32_e32 v33, v2
	v_mov_b32_e32 v38, v2
	v_mov_b32_e32 v39, v2
	v_mov_b32_e32 v40, v2
	v_mov_b32_e32 v41, v2
	v_mov_b32_e32 v46, v2
	v_mov_b32_e32 v47, v2
	v_mov_b32_e32 v48, v2
	v_mov_b32_e32 v49, v2
	v_mov_b32_e32 v54, v2
	v_mov_b32_e32 v55, v2
	v_mov_b32_e32 v56, v2
	v_mov_b32_e32 v57, v2
	v_mov_b32_e32 v58, v2
	v_mov_b32_e32 v59, v2
	v_mov_b32_e32 v60, v2
	v_mov_b32_e32 v61, v2
	v_mov_b32_e32 v62, v2
	v_mov_b32_e32 v63, v2
	v_mov_b32_e32 v64, v2
	v_mov_b32_e32 v65, v2
	v_mov_b32_e32 v66, v2
	v_mov_b32_e32 v67, v2
	v_mov_b32_e32 v68, v2
	v_mov_b32_e32 v69, v2
	v_mov_b32_e32 v70, v2
	v_mov_b32_e32 v71, v2
	v_mov_b32_e32 v72, v2
	v_mov_b32_e32 v73, v2
	v_mov_b32_e32 v74, v2
	v_mov_b32_e32 v75, v2
	v_mov_b32_e32 v76, v2
	v_mov_b32_e32 v77, v2
	v_mov_b32_e32 v82, v2
	v_mov_b32_e32 v83, v2
	v_mov_b32_e32 v84, v2
	v_mov_b32_e32 v85, v2
	v_mov_b32_e32 v90, v2
	v_mov_b32_e32 v91, v2
	v_mov_b32_e32 v92, v2
	v_mov_b32_e32 v93, v2
	v_mov_b32_e32 v98, v2
	v_mov_b32_e32 v99, v2
	v_mov_b32_e32 v100, v2
	v_mov_b32_e32 v101, v2
	v_mov_b32_e32 v106, v2
	v_mov_b32_e32 v107, v2
	v_mov_b32_e32 v108, v2
	v_mov_b32_e32 v109, v2
	v_mov_b32_e32 v114, v2
	v_mov_b32_e32 v115, v2
	v_mov_b32_e32 v116, v2
	v_mov_b32_e32 v117, v2
	v_mov_b32_e32 v78, v2
	v_mov_b32_e32 v79, v2
	v_mov_b32_e32 v80, v2
	v_mov_b32_e32 v81, v2
	v_mov_b32_e32 v86, v2
	v_mov_b32_e32 v87, v2
	v_mov_b32_e32 v88, v2
	v_mov_b32_e32 v89, v2
	v_mov_b32_e32 v94, v2
	v_mov_b32_e32 v95, v2
	v_mov_b32_e32 v96, v2
	v_mov_b32_e32 v97, v2
	v_mov_b32_e32 v102, v2
	v_mov_b32_e32 v103, v2
	v_mov_b32_e32 v104, v2
	v_mov_b32_e32 v105, v2
	v_mov_b32_e32 v110, v2
	v_mov_b32_e32 v111, v2
	v_mov_b32_e32 v112, v2
	v_mov_b32_e32 v113, v2
	v_mov_b32_e32 v118, v2
	v_mov_b32_e32 v119, v2
	v_mov_b32_e32 v120, v2
	v_mov_b32_e32 v121, v2
	v_mov_b32_e32 v122, v2
	v_mov_b32_e32 v123, v2
	v_mov_b32_e32 v124, v2
	v_mov_b32_e32 v125, v2
	v_mov_b32_e32 v126, v2
	v_mov_b32_e32 v127, v2
	v_mov_b32_e32 v128, v2
	v_mov_b32_e32 v129, v2
	s_add_u32 s30, s28, 0xfff80080
	s_addc_u32 s31, s29, -1
	s_add_i32 s51, 0, 0x10000
	s_cmp_eq_u32 s50, 28
	s_cselect_b32 s35, s17, s31
	s_cselect_b32 s34, s46, s30
	s_cselect_b32 s31, s15, s49
	s_cselect_b32 s30, s47, s48
	s_add_i32 s54, 0, 0x14000
.LBB0_861:
	v_add_u32_e32 v145, s51, v142
	ds_read_b128 v[146:149], v145
	ds_read_b128 v[150:153], v145 offset:1024
	ds_read_b128 v[154:157], v145 offset:2048
	ds_read_b128 v[158:161], v145 offset:3072
	v_add_u32_e32 v145, s54, v142
	ds_read_b128 v[162:165], v145
	ds_read_b128 v[166:169], v145 offset:1024
	ds_read_b128 v[178:181], v145 offset:2048
	ds_read_b128 v[182:185], v145 offset:3072
	v_lshl_add_u64 v[172:173], s[28:29], 0, v[138:139]
	s_add_i32 m0, s25, 0xc000
	ds_read_b128 v[186:189], v144
	global_load_lds_dwordx4 v[172:173], off
	ds_read_b128 v[190:193], v144 offset:1024
	ds_read_b128 v[194:197], v144 offset:2048
	v_lshl_add_u64 v[172:173], s[28:29], 0, v[136:137]
	s_add_i32 m0, s25, 0xe000
	s_nop 0
	global_load_lds_dwordx4 v[172:173], off
	ds_read_b128 v[198:201], v144 offset:3072
	ds_read_b128 v[212:215], v144 offset:4096
	ds_read_b128 v[216:219], v144 offset:5120
	ds_read_b128 v[220:223], v144 offset:6144
	ds_read_b128 v[224:227], v144 offset:7168
	s_waitcnt vmcnt(8)
	s_waitcnt lgkmcnt(0)
	s_barrier
; #define PG8_STAGE(bufoff, gbase, voff) do { _Pragma("unroll") for (int _i = 0; _i < 2; ++_i) \
;         __builtin_amdgcn_global_load_lds((const unsigned*)((const char*)(gbase) + (voff)[_i]), (LAS unsigned*)(lds + (bufoff) + ldsw + _i * 8192), 16, 0, 0); } while (0)
; #define PG8_LDA(dst, b, h) do { _Pragma("unroll") for (int m = 0; m < 4; ++m) _Pragma("unroll") for (int k = 0; k < 2; ++k) dst[m][k] = *(const LAS bf16x8*)(lds + PG8_SA(b, h) + aoff + m * 2048 + k * 1024); } while (0)
; #define PG8_MMA(ai, bj, At, Bt) do { __builtin_amdgcn_s_setprio(1); _Pragma("unroll") for (int m = 0; m < 4; ++m) _Pragma("unroll") for (int n = 0; n < 2; ++n) _Pragma("unroll") for (int k = 0; k < 2; ++k) \
;         acc[ai][bj][m][n] = __builtin_amdgcn_mfma_f32_16x16x32_bf16(Bt[n][k], At[m][k], acc[ai][bj][m][n], 0, 0, 0); __builtin_amdgcn_s_setprio(0); } while (0)
; #define PG8_WAIT_V(n) asm volatile("s_waitcnt vmcnt(" #n ")" ::: "memory")
; #define PG8_WAIT_L(n) asm volatile("s_waitcnt lgkmcnt(" #n ")" ::: "memory")
; #define PG8_BAR __builtin_amdgcn_s_barrier()
; #define PG8_SCHED __builtin_amdgcn_sched_barrier(0)
; template <class Epi>
; __device__ __forceinline__ void gemm_phase(LAS unsigned char* lds, const Gemm g, const StaticOrder& S, const Epi& E, const int tid) {
;     ...
;             PG8_WAIT_V(8); PG8_WAIT_L(0); PG8_BAR; PG8_MMA(0, 0, At, B0); PG8_MMA(0, 1, At, B1); PG8_BAR; PG8_SCHED;
;             PG8_LDA(At, 0, 1); PG8_STAGE(PG8_SB(0, 0), b2, voffB); PG8_STAGE(PG8_SB(0, 1), b2 + bhs, voffB); PG8_STAGE(PG8_SA(0, 0), a2, voffA);
;             PG8_WAIT_V(8); PG8_WAIT_L(0); PG8_BAR; PG8_MMA(1, 0, At, B0); PG8_MMA(1, 1, At, B1); PG8_BAR; PG8_SCHED;
	s_setprio 1
	s_waitcnt lgkmcnt(0)
	v_mfma_f32_16x16x32_bf16 v[126:129], v[146:149], v[186:189], v[126:129]
	v_mfma_f32_16x16x32_bf16 v[122:125], v[154:157], v[186:189], v[122:125]
	v_mfma_f32_16x16x32_bf16 v[118:121], v[146:149], v[194:197], v[118:121]
	v_mfma_f32_16x16x32_bf16 v[110:113], v[154:157], v[194:197], v[110:113]
	v_mfma_f32_16x16x32_bf16 v[102:105], v[146:149], v[212:215], v[102:105]
	v_mfma_f32_16x16x32_bf16 v[94:97], v[154:157], v[212:215], v[94:97]
	v_mfma_f32_16x16x32_bf16 v[86:89], v[146:149], v[220:223], v[86:89]
	v_mfma_f32_16x16x32_bf16 v[78:81], v[154:157], v[220:223], v[78:81]
	v_mfma_f32_16x16x32_bf16 v[126:129], v[150:153], v[190:193], v[126:129]
	v_mfma_f32_16x16x32_bf16 v[122:125], v[158:161], v[190:193], v[122:125]
	v_mfma_f32_16x16x32_bf16 v[118:121], v[150:153], v[198:201], v[118:121]
	v_mfma_f32_16x16x32_bf16 v[110:113], v[158:161], v[198:201], v[110:113]
	v_mfma_f32_16x16x32_bf16 v[102:105], v[150:153], v[216:219], v[102:105]
	v_mfma_f32_16x16x32_bf16 v[94:97], v[158:161], v[216:219], v[94:97]
	v_mfma_f32_16x16x32_bf16 v[86:89], v[150:153], v[224:227], v[86:89]
	v_mfma_f32_16x16x32_bf16 v[78:81], v[158:161], v[224:227], v[78:81]
	s_setprio 0
	s_setprio 1
	v_mfma_f32_16x16x32_bf16 v[114:117], v[162:165], v[186:189], v[114:117]
	v_mfma_f32_16x16x32_bf16 v[106:109], v[178:181], v[186:189], v[106:109]
	v_mfma_f32_16x16x32_bf16 v[98:101], v[162:165], v[194:197], v[98:101]
	v_mfma_f32_16x16x32_bf16 v[90:93], v[178:181], v[194:197], v[90:93]
	v_mfma_f32_16x16x32_bf16 v[82:85], v[162:165], v[212:215], v[82:85]
	v_mfma_f32_16x16x32_bf16 v[74:77], v[178:181], v[212:215], v[74:77]
	v_mfma_f32_16x16x32_bf16 v[70:73], v[162:165], v[220:223], v[70:73]
	v_mfma_f32_16x16x32_bf16 v[66:69], v[178:181], v[220:223], v[66:69]
	v_mfma_f32_16x16x32_bf16 v[114:117], v[166:169], v[190:193], v[114:117]
	v_mfma_f32_16x16x32_bf16 v[106:109], v[182:185], v[190:193], v[106:109]
	v_mfma_f32_16x16x32_bf16 v[98:101], v[166:169], v[198:201], v[98:101]
	v_mfma_f32_16x16x32_bf16 v[90:93], v[182:185], v[198:201], v[90:93]
	v_mfma_f32_16x16x32_bf16 v[82:85], v[166:169], v[216:219], v[82:85]
	v_mfma_f32_16x16x32_bf16 v[74:77], v[182:185], v[216:219], v[74:77]
	v_mfma_f32_16x16x32_bf16 v[70:73], v[166:169], v[224:227], v[70:73]
	v_mfma_f32_16x16x32_bf16 v[66:69], v[182:185], v[224:227], v[66:69]
	s_setprio 0
	s_barrier
	s_add_i32 s51, s51, s40
	v_lshl_add_u64 v[172:173], s[30:31], 0, v[0:1]
	s_mov_b32 m0, s51
	ds_read_b128 v[186:189], v144 offset:16384
	global_load_lds_dwordx4 v[172:173], off
	ds_read_b128 v[190:193], v144 offset:17408
	ds_read_b128 v[194:197], v144 offset:18432
	s_add_i32 m0, s51, 0x2000
	s_add_u32 s52, s30, 0x8000
	v_lshl_add_u64 v[174:175], s[30:31], 0, v[134:135]
	s_addc_u32 s53, s31, 0
	s_add_i32 s51, s54, s40
	global_load_lds_dwordx4 v[174:175], off
	ds_read_b128 v[198:201], v144 offset:19456
	ds_read_b128 v[212:215], v144 offset:20480
	v_lshl_add_u64 v[176:177], s[52:53], 0, v[0:1]
	s_mov_b32 m0, s51
	v_lshl_add_u64 v[228:229], s[34:35], 0, v[132:133]
	global_load_lds_dwordx4 v[176:177], off
	ds_read_b128 v[216:219], v144 offset:21504
	ds_read_b128 v[220:223], v144 offset:22528
	v_lshl_add_u64 v[176:177], s[52:53], 0, v[134:135]
	s_add_i32 m0, s51, 0x2000
	s_nop 0
	global_load_lds_dwordx4 v[176:177], off
	ds_read_b128 v[224:227], v144 offset:23552
	v_lshl_add_u64 v[176:177], s[34:35], 0, v[130:131]
	s_mov_b32 m0, s25
	s_nop 0
	global_load_lds_dwordx4 v[176:177], off
	s_mov_b32 m0, s27
	s_nop 0
	global_load_lds_dwordx4 v[228:229], off
	s_waitcnt vmcnt(8)
	s_waitcnt lgkmcnt(0)
	s_barrier
	s_setprio 1
	s_waitcnt lgkmcnt(0)
	v_mfma_f32_16x16x32_bf16 v[62:65], v[146:149], v[186:189], v[62:65]
	v_mfma_f32_16x16x32_bf16 v[58:61], v[154:157], v[186:189], v[58:61]
	v_mfma_f32_16x16x32_bf16 v[54:57], v[146:149], v[194:197], v[54:57]
	v_mfma_f32_16x16x32_bf16 v[46:49], v[154:157], v[194:197], v[46:49]
	v_mfma_f32_16x16x32_bf16 v[38:41], v[146:149], v[212:215], v[38:41]
	v_mfma_f32_16x16x32_bf16 v[30:33], v[154:157], v[212:215], v[30:33]
	v_mfma_f32_16x16x32_bf16 v[22:25], v[146:149], v[220:223], v[22:25]
	v_mfma_f32_16x16x32_bf16 v[14:17], v[154:157], v[220:223], v[14:17]
	v_mfma_f32_16x16x32_bf16 v[62:65], v[150:153], v[190:193], v[62:65]
	v_mfma_f32_16x16x32_bf16 v[58:61], v[158:161], v[190:193], v[58:61]
	v_mfma_f32_16x16x32_bf16 v[54:57], v[150:153], v[198:201], v[54:57]
	v_mfma_f32_16x16x32_bf16 v[46:49], v[158:161], v[198:201], v[46:49]
	v_mfma_f32_16x16x32_bf16 v[38:41], v[150:153], v[216:219], v[38:41]
	v_mfma_f32_16x16x32_bf16 v[30:33], v[158:161], v[216:219], v[30:33]
	v_mfma_f32_16x16x32_bf16 v[22:25], v[150:153], v[224:227], v[22:25]
	v_mfma_f32_16x16x32_bf16 v[14:17], v[158:161], v[224:227], v[14:17]
	s_setprio 0
	s_setprio 1
	v_mfma_f32_16x16x32_bf16 v[50:53], v[162:165], v[186:189], v[50:53]
	v_mfma_f32_16x16x32_bf16 v[42:45], v[178:181], v[186:189], v[42:45]
	v_mfma_f32_16x16x32_bf16 v[34:37], v[162:165], v[194:197], v[34:37]
	v_mfma_f32_16x16x32_bf16 v[26:29], v[178:181], v[194:197], v[26:29]
	v_mfma_f32_16x16x32_bf16 v[18:21], v[162:165], v[212:215], v[18:21]
	v_mfma_f32_16x16x32_bf16 v[10:13], v[178:181], v[212:215], v[10:13]
	v_mfma_f32_16x16x32_bf16 v[6:9], v[162:165], v[220:223], v[6:9]
	v_mfma_f32_16x16x32_bf16 v[2:5], v[178:181], v[220:223], v[2:5]
	v_mfma_f32_16x16x32_bf16 v[50:53], v[166:169], v[190:193], v[50:53]
	v_mfma_f32_16x16x32_bf16 v[42:45], v[182:185], v[190:193], v[42:45]
	v_mfma_f32_16x16x32_bf16 v[34:37], v[166:169], v[198:201], v[34:37]
	v_mfma_f32_16x16x32_bf16 v[26:29], v[182:185], v[198:201], v[26:29]
	v_mfma_f32_16x16x32_bf16 v[18:21], v[166:169], v[216:219], v[18:21]
	v_mfma_f32_16x16x32_bf16 v[10:13], v[182:185], v[216:219], v[10:13]
	v_mfma_f32_16x16x32_bf16 v[6:9], v[166:169], v[224:227], v[6:9]
	v_mfma_f32_16x16x32_bf16 v[2:5], v[182:185], v[224:227], v[2:5]
	s_setprio 0
	s_barrier
; #define PG8_STAGE(bufoff, gbase, voff) do { _Pragma("unroll") for (int _i = 0; _i < 2; ++_i) \
;         __builtin_amdgcn_global_load_lds((const unsigned*)((const char*)(gbase) + (voff)[_i]), (LAS unsigned*)(lds + (bufoff) + ldsw + _i * 8192), 16, 0, 0); } while (0)
; #define PG8_LDA(dst, b, h) do { _Pragma("unroll") for (int m = 0; m < 4; ++m) _Pragma("unroll") for (int k = 0; k < 2; ++k) dst[m][k] = *(const LAS bf16x8*)(lds + PG8_SA(b, h) + aoff + m * 2048 + k * 1024); } while (0)
; #define PG8_LDB(dst, b, h) do { _Pragma("unroll") for (int n = 0; n < 2; ++n) _Pragma("unroll") for (int k = 0; k < 2; ++k) dst[n][k] = *(const LAS bf16x8*)(lds + PG8_SB(b, h) + boff + n * 2048 + k * 1024); } while (0)
; #define PG8_MMA(ai, bj, At, Bt) do { __builtin_amdgcn_s_setprio(1); _Pragma("unroll") for (int m = 0; m < 4; ++m) _Pragma("unroll") for (int n = 0; n < 2; ++n) _Pragma("unroll") for (int k = 0; k < 2; ++k) \
;         acc[ai][bj][m][n] = __builtin_amdgcn_mfma_f32_16x16x32_bf16(Bt[n][k], At[m][k], acc[ai][bj][m][n], 0, 0, 0); __builtin_amdgcn_s_setprio(0); } while (0)
; #define PG8_WAIT_V(n) asm volatile("s_waitcnt vmcnt(" #n ")" ::: "memory")
; #define PG8_WAIT_L(n) asm volatile("s_waitcnt lgkmcnt(" #n ")" ::: "memory")
; #define PG8_BAR __builtin_amdgcn_s_barrier()
; #define PG8_SCHED __builtin_amdgcn_sched_barrier(0)
; template <class Epi>
; __device__ __forceinline__ void gemm_phase(LAS unsigned char* lds, const Gemm g, const StaticOrder& S, const Epi& E, const int tid) {
;     ...
;             PG8_LDB(B0, 1, 0); PG8_LDB(B1, 1, 1); PG8_SCHED; PG8_LDA(At, 1, 0); PG8_STAGE(PG8_SA(0, 1), a2 + hstep, voffA);
;             PG8_WAIT_V(8); PG8_WAIT_L(0); PG8_BAR; PG8_MMA(0, 0, At, B0); PG8_MMA(0, 1, At, B1); PG8_BAR; PG8_SCHED;
	s_add_i32 s51, 0, 0x18000
	v_add_u32_e32 v145, s51, v142
	s_add_i32 s52, 0, 0x1c000
	ds_read_b128 v[146:149], v145
	ds_read_b128 v[150:153], v145 offset:1024
	ds_read_b128 v[154:157], v145 offset:2048
	ds_read_b128 v[158:161], v145 offset:3072
	v_add_u32_e32 v145, s52, v142
	ds_read_b128 v[162:165], v145
	ds_read_b128 v[166:169], v145 offset:1024
	ds_read_b128 v[178:181], v145 offset:2048
	ds_read_b128 v[182:185], v145 offset:3072
	s_add_u32 s34, s34, 0x80000
	s_addc_u32 s35, s35, 0
	s_mov_b32 m0, s41
	v_lshl_add_u64 v[230:231], s[34:35], 0, v[130:131]
	ds_read_b128 v[186:189], v144 offset:32768
	global_load_lds_dwordx4 v[230:231], off
	ds_read_b128 v[190:193], v144 offset:33792
	ds_read_b128 v[194:197], v144 offset:34816
	v_lshl_add_u64 v[230:231], s[34:35], 0, v[132:133]
	s_mov_b32 m0, s42
	s_nop 0
	global_load_lds_dwordx4 v[230:231], off
	ds_read_b128 v[198:201], v144 offset:35840
	ds_read_b128 v[212:215], v144 offset:36864
	ds_read_b128 v[216:219], v144 offset:37888
	ds_read_b128 v[220:223], v144 offset:38912
	ds_read_b128 v[224:227], v144 offset:39936
	s_waitcnt vmcnt(8)
	s_waitcnt lgkmcnt(0)
	s_barrier
	s_setprio 1
	s_waitcnt lgkmcnt(0)
	v_mfma_f32_16x16x32_bf16 v[126:129], v[146:149], v[186:189], v[126:129]
	v_mfma_f32_16x16x32_bf16 v[122:125], v[154:157], v[186:189], v[122:125]
	v_mfma_f32_16x16x32_bf16 v[118:121], v[146:149], v[194:197], v[118:121]
	v_mfma_f32_16x16x32_bf16 v[110:113], v[154:157], v[194:197], v[110:113]
	v_mfma_f32_16x16x32_bf16 v[102:105], v[146:149], v[212:215], v[102:105]
	v_mfma_f32_16x16x32_bf16 v[94:97], v[154:157], v[212:215], v[94:97]
	v_mfma_f32_16x16x32_bf16 v[86:89], v[146:149], v[220:223], v[86:89]
	v_mfma_f32_16x16x32_bf16 v[78:81], v[154:157], v[220:223], v[78:81]
	v_mfma_f32_16x16x32_bf16 v[126:129], v[150:153], v[190:193], v[126:129]
	v_mfma_f32_16x16x32_bf16 v[122:125], v[158:161], v[190:193], v[122:125]
	v_mfma_f32_16x16x32_bf16 v[118:121], v[150:153], v[198:201], v[118:121]
	v_mfma_f32_16x16x32_bf16 v[110:113], v[158:161], v[198:201], v[110:113]
	v_mfma_f32_16x16x32_bf16 v[102:105], v[150:153], v[216:219], v[102:105]
	v_mfma_f32_16x16x32_bf16 v[94:97], v[158:161], v[216:219], v[94:97]
	v_mfma_f32_16x16x32_bf16 v[86:89], v[150:153], v[224:227], v[86:89]
	v_mfma_f32_16x16x32_bf16 v[78:81], v[158:161], v[224:227], v[78:81]
	s_setprio 0
	s_setprio 1
	v_mfma_f32_16x16x32_bf16 v[114:117], v[162:165], v[186:189], v[114:117]
	v_mfma_f32_16x16x32_bf16 v[106:109], v[178:181], v[186:189], v[106:109]
	v_mfma_f32_16x16x32_bf16 v[98:101], v[162:165], v[194:197], v[98:101]
	v_mfma_f32_16x16x32_bf16 v[90:93], v[178:181], v[194:197], v[90:93]
	v_mfma_f32_16x16x32_bf16 v[82:85], v[162:165], v[212:215], v[82:85]
	v_mfma_f32_16x16x32_bf16 v[74:77], v[178:181], v[212:215], v[74:77]
	v_mfma_f32_16x16x32_bf16 v[70:73], v[162:165], v[220:223], v[70:73]
	v_mfma_f32_16x16x32_bf16 v[66:69], v[178:181], v[220:223], v[66:69]
	v_mfma_f32_16x16x32_bf16 v[114:117], v[166:169], v[190:193], v[114:117]
	v_mfma_f32_16x16x32_bf16 v[106:109], v[182:185], v[190:193], v[106:109]
	v_mfma_f32_16x16x32_bf16 v[98:101], v[166:169], v[198:201], v[98:101]
	v_mfma_f32_16x16x32_bf16 v[90:93], v[182:185], v[198:201], v[90:93]
	v_mfma_f32_16x16x32_bf16 v[82:85], v[166:169], v[216:219], v[82:85]
	v_mfma_f32_16x16x32_bf16 v[74:77], v[182:185], v[216:219], v[74:77]
	v_mfma_f32_16x16x32_bf16 v[70:73], v[166:169], v[224:227], v[70:73]
	v_mfma_f32_16x16x32_bf16 v[66:69], v[182:185], v[224:227], v[66:69]
	s_setprio 0
	s_barrier
; #define PG8_STAGE(bufoff, gbase, voff) do { _Pragma("unroll") for (int _i = 0; _i < 2; ++_i) \
;         __builtin_amdgcn_global_load_lds((const unsigned*)((const char*)(gbase) + (voff)[_i]), (LAS unsigned*)(lds + (bufoff) + ldsw + _i * 8192), 16, 0, 0); } while (0)
; #define PG8_LDA(dst, b, h) do { _Pragma("unroll") for (int m = 0; m < 4; ++m) _Pragma("unroll") for (int k = 0; k < 2; ++k) dst[m][k] = *(const LAS bf16x8*)(lds + PG8_SA(b, h) + aoff + m * 2048 + k * 1024); } while (0)
; #define PG8_MMA(ai, bj, At, Bt) do { __builtin_amdgcn_s_setprio(1); _Pragma("unroll") for (int m = 0; m < 4; ++m) _Pragma("unroll") for (int n = 0; n < 2; ++n) _Pragma("unroll") for (int k = 0; k < 2; ++k) \
;         acc[ai][bj][m][n] = __builtin_amdgcn_mfma_f32_16x16x32_bf16(Bt[n][k], At[m][k], acc[ai][bj][m][n], 0, 0, 0); __builtin_amdgcn_s_setprio(0); } while (0)
; #define PG8_WAIT_V(n) asm volatile("s_waitcnt vmcnt(" #n ")" ::: "memory")
; #define PG8_WAIT_L(n) asm volatile("s_waitcnt lgkmcnt(" #n ")" ::: "memory")
; #define PG8_BAR __builtin_amdgcn_s_barrier()
; #define PG8_SCHED __builtin_amdgcn_sched_barrier(0)
; template <class Epi>
; __device__ __forceinline__ void gemm_phase(LAS unsigned char* lds, const Gemm g, const StaticOrder& S, const Epi& E, const int tid) {
;     ...
;             const bool last = (t == ntt - 2);
;             const bool s1 = Epi::TWO && (t >= nt), s2 = Epi::TWO && (t + 2 >= nt);
;             const char* a1 = (s1 ? cA2 + (size_t)(t - nt + 1) * kstep : cA + (size_t)(t + 1) * kstep);
;             const char* a2 = last ? nA : (s2 ? cA2 + (size_t)(t + 2 - nt) * kstep : cA + (size_t)(t + 2) * kstep);
;             const char* b2 = last ? nB : (s2 ? cB2 + (size_t)(t + 2 - nt) * kstep : cB + (size_t)(t + 2) * kstep);
;             const char* a3 = a2 + kstep; const char* b3 = b2 + kstep;
;     ...
;             PG8_LDA(At, 1, 1); PG8_STAGE(PG8_SB(1, 0), b3, voffB); PG8_STAGE(PG8_SB(1, 1), b3 + bhs, voffB); PG8_STAGE(PG8_SA(1, 0), a3, voffA);
;             PG8_WAIT_V(8); PG8_WAIT_L(0); PG8_BAR; PG8_MMA(1, 0, At, B0); PG8_MMA(1, 1, At, B1); PG8_BAR; PG8_SCHED;
	s_add_i32 s34, s51, s40
	v_lshl_add_u64 v[172:173], v[172:173], 0, s[70:71]
	s_mov_b32 m0, s34
	ds_read_b128 v[186:189], v144 offset:49152
	global_load_lds_dwordx4 v[172:173], off
	ds_read_b128 v[190:193], v144 offset:50176
	ds_read_b128 v[194:197], v144 offset:51200
	s_add_i32 m0, s34, 0x2000
	s_add_u32 s30, s30, 0x8080
	v_lshl_add_u64 v[172:173], v[174:175], 0, s[70:71]
	s_addc_u32 s31, s31, 0
	s_add_i32 s34, s52, s40
	global_load_lds_dwordx4 v[172:173], off
	ds_read_b128 v[198:201], v144 offset:52224
	ds_read_b128 v[212:215], v144 offset:53248
	v_lshl_add_u64 v[172:173], s[30:31], 0, v[0:1]
	s_mov_b32 m0, s34
	s_nop 0
	global_load_lds_dwordx4 v[172:173], off
	ds_read_b128 v[216:219], v144 offset:54272
	ds_read_b128 v[220:223], v144 offset:55296
	v_lshl_add_u64 v[172:173], s[30:31], 0, v[134:135]
	s_add_i32 m0, s34, 0x2000
	s_nop 0
	global_load_lds_dwordx4 v[172:173], off
	ds_read_b128 v[224:227], v144 offset:56320
	v_lshl_add_u64 v[172:173], v[176:177], 0, s[70:71]
	s_mov_b32 m0, s43
	s_nop 0
	global_load_lds_dwordx4 v[172:173], off
	v_lshl_add_u64 v[172:173], v[228:229], 0, s[70:71]
	s_mov_b32 m0, s44
	s_nop 0
	global_load_lds_dwordx4 v[172:173], off
	s_waitcnt vmcnt(8)
	s_waitcnt lgkmcnt(0)
	s_barrier
	s_setprio 1
	s_waitcnt lgkmcnt(0)
	v_mfma_f32_16x16x32_bf16 v[62:65], v[146:149], v[186:189], v[62:65]
	v_mfma_f32_16x16x32_bf16 v[58:61], v[154:157], v[186:189], v[58:61]
	v_mfma_f32_16x16x32_bf16 v[54:57], v[146:149], v[194:197], v[54:57]
	v_mfma_f32_16x16x32_bf16 v[46:49], v[154:157], v[194:197], v[46:49]
	v_mfma_f32_16x16x32_bf16 v[38:41], v[146:149], v[212:215], v[38:41]
	v_mfma_f32_16x16x32_bf16 v[30:33], v[154:157], v[212:215], v[30:33]
	v_mfma_f32_16x16x32_bf16 v[22:25], v[146:149], v[220:223], v[22:25]
	v_mfma_f32_16x16x32_bf16 v[14:17], v[154:157], v[220:223], v[14:17]
	v_mfma_f32_16x16x32_bf16 v[62:65], v[150:153], v[190:193], v[62:65]
	v_mfma_f32_16x16x32_bf16 v[58:61], v[158:161], v[190:193], v[58:61]
	v_mfma_f32_16x16x32_bf16 v[54:57], v[150:153], v[198:201], v[54:57]
	v_mfma_f32_16x16x32_bf16 v[46:49], v[158:161], v[198:201], v[46:49]
	v_mfma_f32_16x16x32_bf16 v[38:41], v[150:153], v[216:219], v[38:41]
	v_mfma_f32_16x16x32_bf16 v[30:33], v[158:161], v[216:219], v[30:33]
	v_mfma_f32_16x16x32_bf16 v[22:25], v[150:153], v[224:227], v[22:25]
	v_mfma_f32_16x16x32_bf16 v[14:17], v[158:161], v[224:227], v[14:17]
	s_setprio 0
	s_setprio 1
	v_mfma_f32_16x16x32_bf16 v[50:53], v[162:165], v[186:189], v[50:53]
	s_add_i32 s50, s50, 2
	v_mfma_f32_16x16x32_bf16 v[42:45], v[178:181], v[186:189], v[42:45]
	s_add_u32 s48, s48, 0x100
	v_mfma_f32_16x16x32_bf16 v[34:37], v[162:165], v[194:197], v[34:37]
	s_addc_u32 s49, s49, 0
	v_mfma_f32_16x16x32_bf16 v[26:29], v[178:181], v[194:197], v[26:29]
	s_add_u32 s28, s28, 0x100
	v_mfma_f32_16x16x32_bf16 v[18:21], v[162:165], v[212:215], v[18:21]
	s_addc_u32 s29, s29, 0
	v_mfma_f32_16x16x32_bf16 v[10:13], v[178:181], v[212:215], v[10:13]
	s_add_u32 s30, s28, 0xfff80080
	v_mfma_f32_16x16x32_bf16 v[6:9], v[162:165], v[220:223], v[6:9]
	s_addc_u32 s31, s29, -1
	v_mfma_f32_16x16x32_bf16 v[2:5], v[178:181], v[220:223], v[2:5]
	s_add_i32 s51, 0, 0x10000
	v_mfma_f32_16x16x32_bf16 v[50:53], v[166:169], v[190:193], v[50:53]
	s_cmp_eq_u32 s50, 28
	v_mfma_f32_16x16x32_bf16 v[42:45], v[182:185], v[190:193], v[42:45]
	s_cselect_b32 s35, s17, s31
	v_mfma_f32_16x16x32_bf16 v[34:37], v[166:169], v[198:201], v[34:37]
	s_cselect_b32 s34, s46, s30
	v_mfma_f32_16x16x32_bf16 v[26:29], v[182:185], v[198:201], v[26:29]
	s_cselect_b32 s31, s15, s49
	v_mfma_f32_16x16x32_bf16 v[18:21], v[166:169], v[216:219], v[18:21]
	s_cselect_b32 s30, s47, s48
	v_mfma_f32_16x16x32_bf16 v[10:13], v[182:185], v[216:219], v[10:13]
	s_add_i32 s54, 0, 0x14000
	v_mfma_f32_16x16x32_bf16 v[6:9], v[166:169], v[224:227], v[6:9]
	s_cmp_gt_u32 s50, 29
	v_mfma_f32_16x16x32_bf16 v[2:5], v[182:185], v[224:227], v[2:5]
	s_setprio 0
	s_barrier
	s_cbranch_scc0 .LBB0_861
	s_and_b64 vcc, exec, s[12:13]
	s_cbranch_vccz .LBB0_864
	s_barrier
